# dn_chunk_prep triangular solve: batch v_readlane over 4 SGPRs (s2,s3,s98,s99) removing per-element hazard s_nops
# speedup vs baseline: 1.0247x; 1.0106x over previous
.LBB0_654:
	s_andn2_saveexec_b64 s[0:1], s[2:3]
	s_cbranch_execz .LBB0_660
	v_cmp_lt_i32_e64 s[40:41], 63, v74
	ds_read2st64_b32 v[72:73], v77 offset0:109 offset1:110
	ds_read2st64_b32 v[70:71], v77 offset0:111 offset1:112
	ds_read2st64_b32 v[68:69], v77 offset0:113 offset1:114
	ds_read2st64_b32 v[66:67], v77 offset0:115 offset1:116
	ds_read2st64_b32 v[64:65], v77 offset0:117 offset1:118
	ds_read2st64_b32 v[62:63], v77 offset0:119 offset1:120
	ds_read2st64_b32 v[60:61], v77 offset0:121 offset1:122
	ds_read2st64_b32 v[58:59], v77 offset0:123 offset1:124
	ds_read2st64_b32 v[56:57], v77 offset0:125 offset1:126
	ds_read2st64_b32 v[54:55], v77 offset0:127 offset1:128
	ds_read2st64_b32 v[52:53], v77 offset0:129 offset1:130
	ds_read2st64_b32 v[50:51], v77 offset0:131 offset1:132
	ds_read2st64_b32 v[48:49], v77 offset0:133 offset1:134
	ds_read2st64_b32 v[46:47], v77 offset0:135 offset1:136
	ds_read2st64_b32 v[44:45], v77 offset0:137 offset1:138
	ds_read2st64_b32 v[42:43], v77 offset0:139 offset1:140
	ds_read2st64_b32 v[40:41], v77 offset0:141 offset1:142
	ds_read2st64_b32 v[38:39], v77 offset0:143 offset1:144
	ds_read2st64_b32 v[36:37], v77 offset0:145 offset1:146
	ds_read2st64_b32 v[34:35], v77 offset0:147 offset1:148
	ds_read2st64_b32 v[32:33], v77 offset0:149 offset1:150
	ds_read2st64_b32 v[30:31], v77 offset0:151 offset1:152
	ds_read2st64_b32 v[28:29], v77 offset0:153 offset1:154
	ds_read2st64_b32 v[26:27], v77 offset0:155 offset1:156
	ds_read2st64_b32 v[24:25], v77 offset0:157 offset1:158
	ds_read2st64_b32 v[22:23], v77 offset0:159 offset1:160
	ds_read2st64_b32 v[20:21], v77 offset0:161 offset1:162
	ds_read2st64_b32 v[18:19], v77 offset0:163 offset1:164
	ds_read2st64_b32 v[16:17], v77 offset0:165 offset1:166
	ds_read2st64_b32 v[14:15], v77 offset0:167 offset1:168
	ds_read2st64_b32 v[12:13], v77 offset0:169 offset1:170
	ds_read_b32 v80, v77 offset:43776
	v_cndmask_b32_e64 v0, v194, v192, s[40:41]
	v_lshlrev_b32_e32 v77, 1, v75
	v_or_b32_e32 v82, v0, v77
	ds_read_u16 v0, v82
	ds_read_b128 v[84:87], v137 offset:60672
	s_waitcnt lgkmcnt(14)
	v_readlane_b32 s2, v72, 0
	v_cmp_gt_i32_e64 s[38:39], 64, v74
	s_waitcnt lgkmcnt(1)
	v_lshlrev_b32_e32 v0, 16, v0
	s_waitcnt lgkmcnt(0)
	v_mul_f32_e32 v79, v84, v0
	ds_read_b128 v[88:91], v137 offset:60416
	ds_read_b128 v[8:11], v137 offset:60432
	ds_read_b128 v[4:7], v137 offset:60448
	ds_read_b128 v[0:3], v137 offset:60464
	ds_read_u16 v83, v82 offset:144
	s_waitcnt lgkmcnt(4)
	v_mul_f32_e32 v84, 0x3fb8aa3b, v89
	v_exp_f32_e32 v84, v84
	s_waitcnt lgkmcnt(3)
	v_mul_f32_e32 v8, 0x3fb8aa3b, v8
	v_exp_f32_e32 v8, v8
	s_waitcnt lgkmcnt(0)
	v_lshlrev_b32_e32 v83, 16, v83
	v_mul_f32_e32 v83, v85, v83
	v_mul_f32_e32 v84, v83, v84
	v_cndmask_b32_e64 v105, v83, v84, s[40:41]
	ds_read_u16 v83, v82 offset:288
	v_mul_f32_e32 v84, 0x3fb8aa3b, v90
	v_exp_f32_e32 v84, v84
	v_mul_f32_e32 v9, 0x3fb8aa3b, v9
	v_exp_f32_e32 v9, v9
	s_waitcnt lgkmcnt(0)
	v_lshlrev_b32_e32 v83, 16, v83
	v_mul_f32_e32 v83, v86, v83
	v_mul_f32_e32 v84, v83, v84
	v_cndmask_b32_e64 v106, v83, v84, s[40:41]
	ds_read_u16 v83, v82 offset:432
	v_mul_f32_e32 v84, 0x3fb8aa3b, v91
	v_exp_f32_e32 v84, v84
	v_mul_f32_e32 v10, 0x3fb8aa3b, v10
	v_exp_f32_e32 v10, v10
	s_waitcnt lgkmcnt(0)
	v_lshlrev_b32_e32 v83, 16, v83
	v_mul_f32_e32 v83, v87, v83
	v_mul_f32_e32 v84, v83, v84
	v_cndmask_b32_e64 v109, v83, v84, s[40:41]
	ds_read_u16 v83, v82 offset:576
	ds_read_b128 v[84:87], v137 offset:60688
	v_mul_f32_e32 v11, 0x3fb8aa3b, v11
	v_exp_f32_e32 v11, v11
	v_mul_f32_e32 v4, 0x3fb8aa3b, v4
	s_waitcnt lgkmcnt(1)
	v_lshlrev_b32_e32 v83, 16, v83
	s_waitcnt lgkmcnt(0)
	v_mul_f32_e32 v83, v84, v83
	v_mul_f32_e32 v8, v83, v8
	v_cndmask_b32_e64 v8, v83, v8, s[40:41]
	ds_read_u16 v83, v82 offset:720
	v_exp_f32_e32 v4, v4
	v_mul_f32_e32 v5, 0x3fb8aa3b, v5
	v_exp_f32_e32 v5, v5
	v_mul_f32_e32 v0, 0x3fb8aa3b, v0
	s_waitcnt lgkmcnt(0)
	v_lshlrev_b32_e32 v83, 16, v83
	v_mul_f32_e32 v83, v85, v83
	v_mul_f32_e32 v9, v83, v9
	v_cndmask_b32_e64 v9, v83, v9, s[40:41]
	ds_read_u16 v83, v82 offset:864
	v_exp_f32_e32 v0, v0
	v_mul_f32_e32 v1, 0x3fb8aa3b, v1
	v_exp_f32_e32 v1, v1
	v_mul_f32_e32 v78, 0x3fb8aa3b, v88
	s_waitcnt lgkmcnt(0)
	v_lshlrev_b32_e32 v83, 16, v83
	v_mul_f32_e32 v83, v86, v83
	v_mul_f32_e32 v10, v83, v10
	v_cndmask_b32_e64 v10, v83, v10, s[40:41]
	ds_read_u16 v83, v82 offset:1008
	v_exp_f32_e32 v78, v78
	s_waitcnt lgkmcnt(0)
	v_lshlrev_b32_e32 v83, 16, v83
	v_mul_f32_e32 v83, v87, v83
	v_mul_f32_e32 v11, v83, v11
	v_cndmask_b32_e64 v11, v83, v11, s[40:41]
	ds_read_u16 v83, v82 offset:1152
	ds_read_b128 v[84:87], v137 offset:60704
	v_mul_f32_e32 v78, v79, v78
	v_cndmask_b32_e64 v81, v79, v78, s[40:41]
	s_waitcnt lgkmcnt(1)
	v_lshlrev_b32_e32 v83, 16, v83
	s_waitcnt lgkmcnt(0)
	v_mul_f32_e32 v83, v84, v83
	v_mul_f32_e32 v4, v83, v4
	v_cndmask_b32_e64 v116, v83, v4, s[40:41]
	ds_read_u16 v4, v82 offset:1296
	s_waitcnt lgkmcnt(0)
	v_lshlrev_b32_e32 v4, 16, v4
	v_mul_f32_e32 v4, v85, v4
	v_mul_f32_e32 v5, v4, v5
	v_cndmask_b32_e64 v117, v4, v5, s[40:41]
	ds_read_u16 v4, v82 offset:1440
	v_mul_f32_e32 v5, 0x3fb8aa3b, v6
	v_exp_f32_e32 v5, v5
	s_waitcnt lgkmcnt(0)
	v_lshlrev_b32_e32 v4, 16, v4
	v_mul_f32_e32 v4, v86, v4
	v_mul_f32_e32 v5, v4, v5
	v_cndmask_b32_e64 v120, v4, v5, s[40:41]
	ds_read_u16 v4, v82 offset:1584
	v_mul_f32_e32 v5, 0x3fb8aa3b, v7
	v_exp_f32_e32 v5, v5
	s_waitcnt lgkmcnt(0)
	v_lshlrev_b32_e32 v4, 16, v4
	v_mul_f32_e32 v4, v87, v4
	v_mul_f32_e32 v5, v4, v5
	v_cndmask_b32_e64 v121, v4, v5, s[40:41]
	ds_read_u16 v4, v82 offset:1728
	s_waitcnt lgkmcnt(0)
	v_lshlrev_b32_e32 v83, 16, v4
	ds_read_b128 v[4:7], v137 offset:60720
	s_waitcnt lgkmcnt(0)
	v_mul_f32_e32 v4, v4, v83
	v_mul_f32_e32 v0, v4, v0
	v_cndmask_b32_e64 v122, v4, v0, s[40:41]
	ds_read_u16 v0, v82 offset:1872
	s_waitcnt lgkmcnt(0)
	v_lshlrev_b32_e32 v0, 16, v0
	v_mul_f32_e32 v0, v5, v0
	v_mul_f32_e32 v1, v0, v1
	v_cndmask_b32_e64 v123, v0, v1, s[40:41]
	ds_read_u16 v0, v82 offset:2016
	v_mul_f32_e32 v1, 0x3fb8aa3b, v2
	v_exp_f32_e32 v1, v1
	s_waitcnt lgkmcnt(0)
	v_lshlrev_b32_e32 v0, 16, v0
	v_mul_f32_e32 v0, v6, v0
	v_mul_f32_e32 v1, v0, v1
	v_cndmask_b32_e64 v124, v0, v1, s[40:41]
	ds_read_u16 v0, v82 offset:2160
	v_mul_f32_e32 v1, 0x3fb8aa3b, v3
	v_exp_f32_e32 v1, v1
	s_waitcnt lgkmcnt(0)
	v_lshlrev_b32_e32 v0, 16, v0
	v_mul_f32_e32 v0, v7, v0
	v_mul_f32_e32 v1, v0, v1
	v_cndmask_b32_e64 v143, v0, v1, s[40:41]
	ds_read_u16 v0, v82 offset:2304
	s_waitcnt lgkmcnt(0)
	v_lshlrev_b32_e32 v4, 16, v0
	ds_read_b128 v[0:3], v137 offset:60736
	s_waitcnt lgkmcnt(0)
	v_mul_f32_e32 v0, v0, v4
	ds_read_b128 v[4:7], v137 offset:60480
	s_waitcnt lgkmcnt(0)
	v_mul_f32_e32 v4, 0x3fb8aa3b, v4
	v_exp_f32_e32 v4, v4
	s_nop 0
	v_mul_f32_e32 v4, v0, v4
	v_cndmask_b32_e64 v145, v0, v4, s[40:41]
	ds_read_u16 v0, v82 offset:2448
	s_waitcnt lgkmcnt(0)
	v_lshlrev_b32_e32 v0, 16, v0
	v_mul_f32_e32 v0, v1, v0
	v_mul_f32_e32 v1, 0x3fb8aa3b, v5
	v_exp_f32_e32 v1, v1
	s_nop 0
	v_mul_f32_e32 v1, v0, v1
	v_cndmask_b32_e64 v133, v0, v1, s[40:41]
	ds_read_u16 v0, v82 offset:2592
	v_mul_f32_e32 v1, 0x3fb8aa3b, v6
	v_exp_f32_e32 v1, v1
	s_waitcnt lgkmcnt(0)
	v_lshlrev_b32_e32 v0, 16, v0
	v_mul_f32_e32 v0, v2, v0
	v_mul_f32_e32 v1, v0, v1
	v_cndmask_b32_e64 v129, v0, v1, s[40:41]
	ds_read_u16 v0, v82 offset:2736
	v_mul_f32_e32 v1, 0x3fb8aa3b, v7
	v_exp_f32_e32 v1, v1
	s_waitcnt lgkmcnt(0)
	v_lshlrev_b32_e32 v0, 16, v0
	v_mul_f32_e32 v0, v3, v0
	v_mul_f32_e32 v1, v0, v1
	v_cndmask_b32_e64 v125, v0, v1, s[40:41]
	ds_read_u16 v0, v82 offset:2880
	s_waitcnt lgkmcnt(0)
	v_lshlrev_b32_e32 v4, 16, v0
	ds_read_b128 v[0:3], v137 offset:60752
	s_waitcnt lgkmcnt(0)
	v_mul_f32_e32 v0, v0, v4
	ds_read_b128 v[4:7], v137 offset:60496
	s_waitcnt lgkmcnt(0)
	v_mul_f32_e32 v4, 0x3fb8aa3b, v4
	v_exp_f32_e32 v4, v4
	s_nop 0
	v_mul_f32_e32 v4, v0, v4
	v_cndmask_b32_e64 v136, v0, v4, s[40:41]
	ds_read_u16 v0, v82 offset:3024
	s_waitcnt lgkmcnt(0)
	v_lshlrev_b32_e32 v0, 16, v0
	v_mul_f32_e32 v0, v1, v0
	v_mul_f32_e32 v1, 0x3fb8aa3b, v5
	v_exp_f32_e32 v1, v1
	s_nop 0
	v_mul_f32_e32 v1, v0, v1
	v_cndmask_b32_e64 v134, v0, v1, s[40:41]
	ds_read_u16 v0, v82 offset:3168
	v_mul_f32_e32 v1, 0x3fb8aa3b, v6
	v_exp_f32_e32 v1, v1
	s_waitcnt lgkmcnt(0)
	v_lshlrev_b32_e32 v0, 16, v0
	v_mul_f32_e32 v0, v2, v0
	v_mul_f32_e32 v1, v0, v1
	v_cndmask_b32_e64 v132, v0, v1, s[40:41]
	ds_read_u16 v0, v82 offset:3312
	v_mul_f32_e32 v1, 0x3fb8aa3b, v7
	v_exp_f32_e32 v1, v1
	s_waitcnt lgkmcnt(0)
	v_lshlrev_b32_e32 v0, 16, v0
	v_mul_f32_e32 v0, v3, v0
	v_mul_f32_e32 v1, v0, v1
	v_cndmask_b32_e64 v147, v0, v1, s[40:41]
	ds_read_u16 v0, v82 offset:3456
	s_waitcnt lgkmcnt(0)
	v_lshlrev_b32_e32 v4, 16, v0
	ds_read_b128 v[0:3], v137 offset:60768
	s_waitcnt lgkmcnt(0)
	v_mul_f32_e32 v0, v0, v4
	ds_read_b128 v[4:7], v137 offset:60512
	s_waitcnt lgkmcnt(0)
	v_mul_f32_e32 v4, 0x3fb8aa3b, v4
	v_exp_f32_e32 v4, v4
	s_nop 0
	v_mul_f32_e32 v4, v0, v4
	v_cndmask_b32_e64 v146, v0, v4, s[40:41]
	ds_read_u16 v0, v82 offset:3600
	s_waitcnt lgkmcnt(0)
	v_lshlrev_b32_e32 v0, 16, v0
	v_mul_f32_e32 v0, v1, v0
	v_mul_f32_e32 v1, 0x3fb8aa3b, v5
	v_exp_f32_e32 v1, v1
	s_nop 0
	v_mul_f32_e32 v1, v0, v1
	v_cndmask_b32_e64 v135, v0, v1, s[40:41]
	ds_read_u16 v0, v82 offset:3744
	v_mul_f32_e32 v1, 0x3fb8aa3b, v6
	v_exp_f32_e32 v1, v1
	s_waitcnt lgkmcnt(0)
	v_lshlrev_b32_e32 v0, 16, v0
	v_mul_f32_e32 v0, v2, v0
	v_mul_f32_e32 v1, v0, v1
	v_cndmask_b32_e64 v128, v0, v1, s[40:41]
	ds_read_u16 v0, v82 offset:3888
	v_mul_f32_e32 v1, 0x3fb8aa3b, v7
	v_exp_f32_e32 v1, v1
	s_waitcnt lgkmcnt(0)
	v_lshlrev_b32_e32 v0, 16, v0
	v_mul_f32_e32 v0, v3, v0
	v_mul_f32_e32 v1, v0, v1
	v_cndmask_b32_e64 v118, v0, v1, s[40:41]
	ds_read_u16 v0, v82 offset:4032
	s_waitcnt lgkmcnt(0)
	v_lshlrev_b32_e32 v4, 16, v0
	ds_read_b128 v[0:3], v137 offset:60784
	s_waitcnt lgkmcnt(0)
	v_mul_f32_e32 v0, v0, v4
	ds_read_b128 v[4:7], v137 offset:60528
	s_waitcnt lgkmcnt(0)
	v_mul_f32_e32 v4, 0x3fb8aa3b, v4
	v_exp_f32_e32 v4, v4
	s_nop 0
	v_mul_f32_e32 v4, v0, v4
	v_cndmask_b32_e64 v130, v0, v4, s[40:41]
	ds_read_u16 v0, v82 offset:4176
	s_waitcnt lgkmcnt(0)
	v_lshlrev_b32_e32 v0, 16, v0
	v_mul_f32_e32 v0, v1, v0
	v_mul_f32_e32 v1, 0x3fb8aa3b, v5
	v_exp_f32_e32 v1, v1
	s_nop 0
	v_mul_f32_e32 v1, v0, v1
	v_cndmask_b32_e64 v127, v0, v1, s[40:41]
	ds_read_u16 v0, v82 offset:4320
	v_mul_f32_e32 v1, 0x3fb8aa3b, v6
	v_exp_f32_e32 v1, v1
	s_waitcnt lgkmcnt(0)
	v_lshlrev_b32_e32 v0, 16, v0
	v_mul_f32_e32 v0, v2, v0
	v_mul_f32_e32 v1, v0, v1
	v_cndmask_b32_e64 v119, v0, v1, s[40:41]
	ds_read_u16 v0, v82 offset:4464
	v_mul_f32_e32 v1, 0x3fb8aa3b, v7
	v_exp_f32_e32 v1, v1
	s_waitcnt lgkmcnt(0)
	v_lshlrev_b32_e32 v0, 16, v0
	v_mul_f32_e32 v0, v3, v0
	v_mul_f32_e32 v1, v0, v1
	v_cndmask_b32_e64 v131, v0, v1, s[40:41]
	ds_read_u16 v0, v82 offset:4608
	s_waitcnt lgkmcnt(0)
	v_lshlrev_b32_e32 v4, 16, v0
	ds_read_b128 v[0:3], v137 offset:60800
	s_waitcnt lgkmcnt(0)
	v_mul_f32_e32 v0, v0, v4
	ds_read_b128 v[4:7], v137 offset:60544
	s_waitcnt lgkmcnt(0)
	v_mul_f32_e32 v4, 0x3fb8aa3b, v4
	v_exp_f32_e32 v4, v4
	s_nop 0
	v_mul_f32_e32 v4, v0, v4
	v_cndmask_b32_e64 v126, v0, v4, s[40:41]
	ds_read_u16 v0, v82 offset:4752
	s_waitcnt lgkmcnt(0)
	v_lshlrev_b32_e32 v0, 16, v0
	v_mul_f32_e32 v0, v1, v0
	v_mul_f32_e32 v1, 0x3fb8aa3b, v5
	v_exp_f32_e32 v1, v1
	s_nop 0
	v_mul_f32_e32 v1, v0, v1
	v_cndmask_b32_e64 v115, v0, v1, s[40:41]
	ds_read_u16 v0, v82 offset:4896
	v_mul_f32_e32 v1, 0x3fb8aa3b, v6
	v_exp_f32_e32 v1, v1
	s_waitcnt lgkmcnt(0)
	v_lshlrev_b32_e32 v0, 16, v0
	v_mul_f32_e32 v0, v2, v0
	v_mul_f32_e32 v1, v0, v1
	v_cndmask_b32_e64 v114, v0, v1, s[40:41]
	ds_read_u16 v0, v82 offset:5040
	v_mul_f32_e32 v1, 0x3fb8aa3b, v7
	v_exp_f32_e32 v1, v1
	s_waitcnt lgkmcnt(0)
	v_lshlrev_b32_e32 v0, 16, v0
	v_mul_f32_e32 v0, v3, v0
	v_mul_f32_e32 v1, v0, v1
	v_cndmask_b32_e64 v111, v0, v1, s[40:41]
	ds_read_u16 v0, v82 offset:5184
	s_waitcnt lgkmcnt(0)
	v_lshlrev_b32_e32 v4, 16, v0
	ds_read_b128 v[0:3], v137 offset:60816
	s_waitcnt lgkmcnt(0)
	v_mul_f32_e32 v0, v0, v4
	ds_read_b128 v[4:7], v137 offset:60560
	s_waitcnt lgkmcnt(0)
	v_mul_f32_e32 v4, 0x3fb8aa3b, v4
	v_exp_f32_e32 v4, v4
	s_nop 0
	v_mul_f32_e32 v4, v0, v4
	v_cndmask_b32_e64 v113, v0, v4, s[40:41]
	ds_read_u16 v0, v82 offset:5328
	s_waitcnt lgkmcnt(0)
	v_lshlrev_b32_e32 v0, 16, v0
	v_mul_f32_e32 v0, v1, v0
	v_mul_f32_e32 v1, 0x3fb8aa3b, v5
	v_exp_f32_e32 v1, v1
	s_nop 0
	v_mul_f32_e32 v1, v0, v1
	v_cndmask_b32_e64 v112, v0, v1, s[40:41]
	ds_read_u16 v0, v82 offset:5472
	v_mul_f32_e32 v1, 0x3fb8aa3b, v6
	v_exp_f32_e32 v1, v1
	s_waitcnt lgkmcnt(0)
	v_lshlrev_b32_e32 v0, 16, v0
	v_mul_f32_e32 v0, v2, v0
	v_mul_f32_e32 v1, v0, v1
	v_cndmask_b32_e64 v108, v0, v1, s[40:41]
	ds_read_u16 v0, v82 offset:5616
	v_mul_f32_e32 v1, 0x3fb8aa3b, v7
	v_exp_f32_e32 v1, v1
	s_waitcnt lgkmcnt(0)
	v_lshlrev_b32_e32 v0, 16, v0
	v_mul_f32_e32 v0, v3, v0
	v_mul_f32_e32 v1, v0, v1
	v_cndmask_b32_e64 v110, v0, v1, s[40:41]
	ds_read_u16 v0, v82 offset:5760
	s_waitcnt lgkmcnt(0)
	v_lshlrev_b32_e32 v4, 16, v0
	ds_read_b128 v[0:3], v137 offset:60832
	s_waitcnt lgkmcnt(0)
	v_mul_f32_e32 v0, v0, v4
	ds_read_b128 v[4:7], v137 offset:60576
	s_waitcnt lgkmcnt(0)
	v_mul_f32_e32 v4, 0x3fb8aa3b, v4
	v_exp_f32_e32 v4, v4
	s_nop 0
	v_mul_f32_e32 v4, v0, v4
	v_cndmask_b32_e64 v107, v0, v4, s[40:41]
	ds_read_u16 v0, v82 offset:5904
	s_waitcnt lgkmcnt(0)
	v_lshlrev_b32_e32 v0, 16, v0
	v_mul_f32_e32 v0, v1, v0
	v_mul_f32_e32 v1, 0x3fb8aa3b, v5
	v_exp_f32_e32 v1, v1
	s_nop 0
	v_mul_f32_e32 v1, v0, v1
	v_cndmask_b32_e64 v104, v0, v1, s[40:41]
	ds_read_u16 v0, v82 offset:6048
	v_mul_f32_e32 v1, 0x3fb8aa3b, v6
	v_exp_f32_e32 v1, v1
	s_waitcnt lgkmcnt(0)
	v_lshlrev_b32_e32 v0, 16, v0
	v_mul_f32_e32 v0, v2, v0
	v_mul_f32_e32 v1, v0, v1
	v_cndmask_b32_e64 v103, v0, v1, s[40:41]
	ds_read_u16 v0, v82 offset:6192
	v_mul_f32_e32 v1, 0x3fb8aa3b, v7
	v_exp_f32_e32 v1, v1
	s_waitcnt lgkmcnt(0)
	v_lshlrev_b32_e32 v0, 16, v0
	v_mul_f32_e32 v0, v3, v0
	v_mul_f32_e32 v1, v0, v1
	v_cndmask_b32_e64 v101, v0, v1, s[40:41]
	ds_read_u16 v0, v82 offset:6336
	s_waitcnt lgkmcnt(0)
	v_lshlrev_b32_e32 v4, 16, v0
	ds_read_b128 v[0:3], v137 offset:60848
	s_waitcnt lgkmcnt(0)
	v_mul_f32_e32 v0, v0, v4
	ds_read_b128 v[4:7], v137 offset:60592
	s_waitcnt lgkmcnt(0)
	v_mul_f32_e32 v4, 0x3fb8aa3b, v4
	v_exp_f32_e32 v4, v4
	s_nop 0
	v_mul_f32_e32 v4, v0, v4
	v_cndmask_b32_e64 v102, v0, v4, s[40:41]
	ds_read_u16 v0, v82 offset:6480
	s_waitcnt lgkmcnt(0)
	v_lshlrev_b32_e32 v0, 16, v0
	v_mul_f32_e32 v0, v1, v0
	v_mul_f32_e32 v1, 0x3fb8aa3b, v5
	v_exp_f32_e32 v1, v1
	s_nop 0
	v_mul_f32_e32 v1, v0, v1
	v_cndmask_b32_e64 v100, v0, v1, s[40:41]
	ds_read_u16 v0, v82 offset:6624
	v_mul_f32_e32 v1, 0x3fb8aa3b, v6
	v_exp_f32_e32 v1, v1
	s_waitcnt lgkmcnt(0)
	v_lshlrev_b32_e32 v0, 16, v0
	v_mul_f32_e32 v0, v2, v0
	v_mul_f32_e32 v1, v0, v1
	v_cndmask_b32_e64 v98, v0, v1, s[40:41]
	ds_read_u16 v0, v82 offset:6768
	v_mul_f32_e32 v1, 0x3fb8aa3b, v7
	v_exp_f32_e32 v1, v1
	s_waitcnt lgkmcnt(0)
	v_lshlrev_b32_e32 v0, 16, v0
	v_mul_f32_e32 v0, v3, v0
	v_mul_f32_e32 v1, v0, v1
	v_cndmask_b32_e64 v99, v0, v1, s[40:41]
	ds_read_u16 v0, v82 offset:6912
	s_waitcnt lgkmcnt(0)
	v_lshlrev_b32_e32 v4, 16, v0
	ds_read_b128 v[0:3], v137 offset:60864
	s_waitcnt lgkmcnt(0)
	v_mul_f32_e32 v0, v0, v4
	ds_read_b128 v[4:7], v137 offset:60608
	s_waitcnt lgkmcnt(0)
	v_mul_f32_e32 v4, 0x3fb8aa3b, v4
	v_exp_f32_e32 v4, v4
	s_nop 0
	v_mul_f32_e32 v4, v0, v4
	v_cndmask_b32_e64 v97, v0, v4, s[40:41]
	ds_read_u16 v0, v82 offset:7056
	s_waitcnt lgkmcnt(0)
	v_lshlrev_b32_e32 v0, 16, v0
	v_mul_f32_e32 v0, v1, v0
	v_mul_f32_e32 v1, 0x3fb8aa3b, v5
	v_exp_f32_e32 v1, v1
	s_nop 0
	v_mul_f32_e32 v1, v0, v1
	v_cndmask_b32_e64 v96, v0, v1, s[40:41]
	ds_read_u16 v0, v82 offset:7200
	v_mul_f32_e32 v1, 0x3fb8aa3b, v6
	v_exp_f32_e32 v1, v1
	s_waitcnt lgkmcnt(0)
	v_lshlrev_b32_e32 v0, 16, v0
	v_mul_f32_e32 v0, v2, v0
	v_mul_f32_e32 v1, v0, v1
	v_cndmask_b32_e64 v95, v0, v1, s[40:41]
	ds_read_u16 v0, v82 offset:7344
	v_mul_f32_e32 v1, 0x3fb8aa3b, v7
	v_exp_f32_e32 v1, v1
	s_waitcnt lgkmcnt(0)
	v_lshlrev_b32_e32 v0, 16, v0
	v_mul_f32_e32 v0, v3, v0
	v_mul_f32_e32 v1, v0, v1
	v_cndmask_b32_e64 v93, v0, v1, s[40:41]
	ds_read_u16 v0, v82 offset:7488
	s_waitcnt lgkmcnt(0)
	v_lshlrev_b32_e32 v4, 16, v0
	ds_read_b128 v[0:3], v137 offset:60880
	s_waitcnt lgkmcnt(0)
	v_mul_f32_e32 v0, v0, v4
	ds_read_b128 v[4:7], v137 offset:60624
	s_waitcnt lgkmcnt(0)
	v_mul_f32_e32 v4, 0x3fb8aa3b, v4
	v_exp_f32_e32 v4, v4
	s_nop 0
	v_mul_f32_e32 v4, v0, v4
	v_cndmask_b32_e64 v94, v0, v4, s[40:41]
	ds_read_u16 v0, v82 offset:7632
	s_waitcnt lgkmcnt(0)
	v_lshlrev_b32_e32 v0, 16, v0
	v_mul_f32_e32 v0, v1, v0
	v_mul_f32_e32 v1, 0x3fb8aa3b, v5
	v_exp_f32_e32 v1, v1
	s_nop 0
	v_mul_f32_e32 v1, v0, v1
	v_cndmask_b32_e64 v92, v0, v1, s[40:41]
	ds_read_u16 v0, v82 offset:7776
	v_mul_f32_e32 v1, 0x3fb8aa3b, v6
	v_exp_f32_e32 v1, v1
	s_waitcnt lgkmcnt(0)
	v_lshlrev_b32_e32 v0, 16, v0
	v_mul_f32_e32 v0, v2, v0
	v_mul_f32_e32 v1, v0, v1
	v_cndmask_b32_e64 v90, v0, v1, s[40:41]
	ds_read_u16 v0, v82 offset:7920
	v_mul_f32_e32 v1, 0x3fb8aa3b, v7
	v_exp_f32_e32 v1, v1
	s_waitcnt lgkmcnt(0)
	v_lshlrev_b32_e32 v0, 16, v0
	v_mul_f32_e32 v0, v3, v0
	v_mul_f32_e32 v1, v0, v1
	v_cndmask_b32_e64 v91, v0, v1, s[40:41]
	ds_read_u16 v0, v82 offset:8064
	s_waitcnt lgkmcnt(0)
	v_lshlrev_b32_e32 v4, 16, v0
	ds_read_b128 v[0:3], v137 offset:60896
	s_waitcnt lgkmcnt(0)
	v_mul_f32_e32 v0, v0, v4
	ds_read_b128 v[4:7], v137 offset:60640
	s_waitcnt lgkmcnt(0)
	v_mul_f32_e32 v4, 0x3fb8aa3b, v4
	v_exp_f32_e32 v4, v4
	s_nop 0
	v_mul_f32_e32 v4, v0, v4
	v_cndmask_b32_e64 v89, v0, v4, s[40:41]
	ds_read_u16 v0, v82 offset:8208
	s_waitcnt lgkmcnt(0)
	v_lshlrev_b32_e32 v0, 16, v0
	v_mul_f32_e32 v0, v1, v0
	v_mul_f32_e32 v1, 0x3fb8aa3b, v5
	v_exp_f32_e32 v1, v1
	s_nop 0
	v_mul_f32_e32 v1, v0, v1
	v_cndmask_b32_e64 v88, v0, v1, s[40:41]
	ds_read_u16 v0, v82 offset:8352
	v_mul_f32_e32 v1, 0x3fb8aa3b, v6
	v_exp_f32_e32 v1, v1
	s_waitcnt lgkmcnt(0)
	v_lshlrev_b32_e32 v0, 16, v0
	v_mul_f32_e32 v0, v2, v0
	v_mul_f32_e32 v1, v0, v1
	v_cndmask_b32_e64 v87, v0, v1, s[40:41]
	ds_read_u16 v0, v82 offset:8496
	v_mul_f32_e32 v1, 0x3fb8aa3b, v7
	v_exp_f32_e32 v1, v1
	s_waitcnt lgkmcnt(0)
	v_lshlrev_b32_e32 v0, 16, v0
	v_mul_f32_e32 v0, v3, v0
	v_mul_f32_e32 v1, v0, v1
	v_cndmask_b32_e64 v86, v0, v1, s[40:41]
	ds_read_u16 v0, v82 offset:8640
	s_waitcnt lgkmcnt(0)
	v_lshlrev_b32_e32 v4, 16, v0
	ds_read_b128 v[0:3], v137 offset:60912
	s_waitcnt lgkmcnt(0)
	v_mul_f32_e32 v0, v0, v4
	ds_read_b128 v[4:7], v137 offset:60656
	s_waitcnt lgkmcnt(0)
	v_mul_f32_e32 v4, 0x3fb8aa3b, v4
	v_exp_f32_e32 v4, v4
	s_nop 0
	v_mul_f32_e32 v4, v0, v4
	v_cndmask_b32_e64 v85, v0, v4, s[40:41]
	ds_read_u16 v0, v82 offset:8784
	s_waitcnt lgkmcnt(0)
	v_lshlrev_b32_e32 v0, 16, v0
	v_mul_f32_e32 v0, v1, v0
	v_mul_f32_e32 v1, 0x3fb8aa3b, v5
	v_exp_f32_e32 v1, v1
	s_nop 0
	v_mul_f32_e32 v1, v0, v1
	v_cndmask_b32_e64 v84, v0, v1, s[40:41]
	ds_read_u16 v0, v82 offset:8928
	v_mul_f32_e32 v1, 0x3fb8aa3b, v6
	v_exp_f32_e32 v1, v1
	s_waitcnt lgkmcnt(0)
	v_lshlrev_b32_e32 v0, 16, v0
	v_mul_f32_e32 v0, v2, v0
	v_mul_f32_e32 v1, v0, v1
	v_cndmask_b32_e64 v83, v0, v1, s[40:41]
	ds_read_u16 v0, v82 offset:9072
	v_mul_f32_e32 v1, 0x3fb8aa3b, v7
	v_exp_f32_e32 v1, v1
	s_waitcnt lgkmcnt(0)
	v_lshlrev_b32_e32 v0, 16, v0
	v_mul_f32_e32 v0, v3, v0
	v_mul_f32_e32 v1, v0, v1
	v_cndmask_b32_e64 v82, v0, v1, s[40:41]
	v_fma_f32 v0, -v81, s2, v105
	v_readlane_b32 s2, v73, 0
	v_add_f32_e32 v0, 0, v0
	s_nop 0
	v_fma_f32 v1, -v81, s2, v106
	v_readlane_b32 s2, v73, 1
	s_nop 1
	v_fma_f32 v2, -v0, s2, 0
	v_readlane_b32 s2, v70, 0
	v_add_f32_e32 v1, v1, v2
	s_nop 0
	v_fma_f32 v2, -v81, s2, v109
	v_readlane_b32 s2, v70, 1
	v_readlane_b32 s3, v70, 2
	s_nop 0
	v_fma_f32 v3, -v0, s2, 0
	v_fma_f32 v2, -v1, s3, v2
	v_readlane_b32 s2, v71, 0
	v_add_f32_e32 v2, v3, v2
	s_nop 0
	v_fma_f32 v3, -v81, s2, v8
	v_readlane_b32 s2, v71, 1
	v_readlane_b32 s3, v71, 2
	v_readlane_b32 s98, v71, 3
	v_fma_f32 v4, -v0, s2, 0
	v_fma_f32 v3, -v1, s3, v3
	v_fma_f32 v4, -v2, s98, v4
	v_readlane_b32 s2, v68, 0
	v_add_f32_e32 v3, v3, v4
	s_nop 0
	v_fma_f32 v4, -v81, s2, v9
	v_readlane_b32 s2, v68, 1
	v_readlane_b32 s3, v68, 2
	v_readlane_b32 s98, v68, 3
	v_readlane_b32 s99, v68, 4
	v_fma_f32 v5, -v0, s2, 0
	v_fma_f32 v4, -v1, s3, v4
	v_fma_f32 v5, -v2, s98, v5
	v_fma_f32 v4, -v3, s99, v4
	v_readlane_b32 s2, v69, 0
	v_add_f32_e32 v4, v5, v4
	s_nop 0
	v_fma_f32 v5, -v81, s2, v10
	v_readlane_b32 s2, v69, 1
	v_readlane_b32 s3, v69, 2
	v_readlane_b32 s98, v69, 3
	v_readlane_b32 s99, v69, 4
	v_fma_f32 v6, -v0, s2, 0
	v_fma_f32 v5, -v1, s3, v5
	v_fma_f32 v6, -v2, s98, v6
	v_fma_f32 v5, -v3, s99, v5
	v_readlane_b32 s2, v69, 5
	s_nop 1
	v_fma_f32 v6, -v4, s2, v6
	v_readlane_b32 s2, v66, 0
	v_add_f32_e32 v5, v5, v6
	s_nop 0
	v_fma_f32 v6, -v81, s2, v11
	v_readlane_b32 s2, v66, 1
	v_readlane_b32 s3, v66, 2
	v_readlane_b32 s98, v66, 3
	v_readlane_b32 s99, v66, 4
	v_fma_f32 v7, -v0, s2, 0
	v_fma_f32 v6, -v1, s3, v6
	v_fma_f32 v7, -v2, s98, v7
	v_fma_f32 v6, -v3, s99, v6
	v_readlane_b32 s2, v66, 5
	v_readlane_b32 s3, v66, 6
	s_nop 0
	v_fma_f32 v7, -v4, s2, v7
	v_fma_f32 v6, -v5, s3, v6
	v_readlane_b32 s2, v67, 0
	v_add_f32_e32 v7, v7, v6
	s_nop 0
	v_fma_f32 v6, -v81, s2, v116
	v_readlane_b32 s2, v67, 1
	v_readlane_b32 s3, v67, 2
	v_readlane_b32 s98, v67, 3
	v_readlane_b32 s99, v67, 4
	v_fma_f32 v8, -v0, s2, 0
	v_fma_f32 v6, -v1, s3, v6
	v_fma_f32 v8, -v2, s98, v8
	v_fma_f32 v6, -v3, s99, v6
	v_readlane_b32 s2, v67, 5
	v_readlane_b32 s3, v67, 6
	v_readlane_b32 s98, v67, 7
	v_fma_f32 v8, -v4, s2, v8
	v_fma_f32 v6, -v5, s3, v6
	v_fma_f32 v8, -v7, s98, v8
	v_readlane_b32 s2, v64, 0
	v_add_f32_e32 v6, v6, v8
	s_nop 0
	v_fma_f32 v8, -v81, s2, v117
	v_readlane_b32 s2, v64, 1
	v_readlane_b32 s3, v64, 2
	v_readlane_b32 s98, v64, 3
	v_readlane_b32 s99, v64, 4
	v_fma_f32 v9, -v0, s2, 0
	v_fma_f32 v8, -v1, s3, v8
	v_fma_f32 v9, -v2, s98, v9
	v_fma_f32 v8, -v3, s99, v8
	v_readlane_b32 s2, v64, 5
	v_readlane_b32 s3, v64, 6
	v_readlane_b32 s98, v64, 7
	v_readlane_b32 s99, v64, 8
	v_fma_f32 v9, -v4, s2, v9
	v_fma_f32 v8, -v5, s3, v8
	v_fma_f32 v9, -v7, s98, v9
	v_fma_f32 v8, -v6, s99, v8
	v_readlane_b32 s2, v65, 0
	v_add_f32_e32 v8, v9, v8
	s_nop 0
	v_fma_f32 v9, -v81, s2, v120
	v_readlane_b32 s2, v65, 1
	v_readlane_b32 s3, v65, 2
	v_readlane_b32 s98, v65, 3
	v_readlane_b32 s99, v65, 4
	v_fma_f32 v10, -v0, s2, 0
	v_fma_f32 v9, -v1, s3, v9
	v_fma_f32 v10, -v2, s98, v10
	v_fma_f32 v9, -v3, s99, v9
	v_readlane_b32 s2, v65, 5
	v_readlane_b32 s3, v65, 6
	v_readlane_b32 s98, v65, 7
	v_readlane_b32 s99, v65, 8
	v_fma_f32 v10, -v4, s2, v10
	v_fma_f32 v9, -v5, s3, v9
	v_fma_f32 v10, -v7, s98, v10
	v_fma_f32 v9, -v6, s99, v9
	v_readlane_b32 s2, v65, 9
	s_nop 1
	v_fma_f32 v10, -v8, s2, v10
	v_readlane_b32 s2, v62, 0
	v_add_f32_e32 v9, v9, v10
	s_nop 0
	v_fma_f32 v10, -v81, s2, v121
	v_readlane_b32 s2, v62, 1
	v_readlane_b32 s3, v62, 2
	v_readlane_b32 s98, v62, 3
	v_readlane_b32 s99, v62, 4
	v_fma_f32 v11, -v0, s2, 0
	v_fma_f32 v10, -v1, s3, v10
	v_fma_f32 v11, -v2, s98, v11
	v_fma_f32 v10, -v3, s99, v10
	v_readlane_b32 s2, v62, 5
	v_readlane_b32 s3, v62, 6
	v_readlane_b32 s98, v62, 7
	v_readlane_b32 s99, v62, 8
	v_fma_f32 v11, -v4, s2, v11
	v_fma_f32 v10, -v5, s3, v10
	v_fma_f32 v11, -v7, s98, v11
	v_fma_f32 v10, -v6, s99, v10
	v_readlane_b32 s2, v62, 9
	v_readlane_b32 s3, v62, 10
	s_nop 0
	v_fma_f32 v11, -v8, s2, v11
	v_fma_f32 v10, -v9, s3, v10
	v_readlane_b32 s2, v63, 0
	v_add_f32_e32 v10, v11, v10
	s_nop 0
	v_fma_f32 v11, -v81, s2, v122
	v_readlane_b32 s2, v63, 1
	v_readlane_b32 s3, v63, 2
	v_readlane_b32 s98, v63, 3
	v_readlane_b32 s99, v63, 4
	v_fma_f32 v62, -v0, s2, 0
	v_fma_f32 v11, -v1, s3, v11
	v_fma_f32 v62, -v2, s98, v62
	v_fma_f32 v11, -v3, s99, v11
	v_readlane_b32 s2, v63, 5
	v_readlane_b32 s3, v63, 6
	v_readlane_b32 s98, v63, 7
	v_readlane_b32 s99, v63, 8
	v_fma_f32 v62, -v4, s2, v62
	v_fma_f32 v11, -v5, s3, v11
	v_fma_f32 v62, -v7, s98, v62
	v_fma_f32 v11, -v6, s99, v11
	v_readlane_b32 s2, v63, 9
	v_readlane_b32 s3, v63, 10
	v_readlane_b32 s98, v63, 11
	v_fma_f32 v62, -v8, s2, v62
	v_fma_f32 v11, -v9, s3, v11
	v_fma_f32 v62, -v10, s98, v62
	v_readlane_b32 s2, v60, 0
	v_add_f32_e32 v11, v11, v62
	s_nop 0
	v_fma_f32 v62, -v81, s2, v123
	v_readlane_b32 s2, v60, 1
	v_readlane_b32 s3, v60, 2
	v_readlane_b32 s98, v60, 3
	v_readlane_b32 s99, v60, 4
	v_fma_f32 v63, -v0, s2, 0
	v_fma_f32 v62, -v1, s3, v62
	v_fma_f32 v63, -v2, s98, v63
	v_fma_f32 v62, -v3, s99, v62
	v_readlane_b32 s2, v60, 5
	v_readlane_b32 s3, v60, 6
	v_readlane_b32 s98, v60, 7
	v_readlane_b32 s99, v60, 8
	v_fma_f32 v63, -v4, s2, v63
	v_fma_f32 v62, -v5, s3, v62
	v_fma_f32 v63, -v7, s98, v63
	v_fma_f32 v62, -v6, s99, v62
	v_readlane_b32 s2, v60, 9
	v_readlane_b32 s3, v60, 10
	v_readlane_b32 s98, v60, 11
	v_readlane_b32 s99, v60, 12
	v_fma_f32 v63, -v8, s2, v63
	v_fma_f32 v62, -v9, s3, v62
	v_fma_f32 v63, -v10, s98, v63
	v_fma_f32 v60, -v11, s99, v62
	v_readlane_b32 s2, v61, 0
	v_add_f32_e32 v60, v63, v60
	s_nop 0
	v_fma_f32 v62, -v81, s2, v124
	v_readlane_b32 s2, v61, 1
	v_readlane_b32 s3, v61, 2
	v_readlane_b32 s98, v61, 3
	v_readlane_b32 s99, v61, 4
	v_fma_f32 v63, -v0, s2, 0
	v_fma_f32 v62, -v1, s3, v62
	v_fma_f32 v63, -v2, s98, v63
	v_fma_f32 v62, -v3, s99, v62
	v_readlane_b32 s2, v61, 5
	v_readlane_b32 s3, v61, 6
	v_readlane_b32 s98, v61, 7
	v_readlane_b32 s99, v61, 8
	v_fma_f32 v63, -v4, s2, v63
	v_fma_f32 v62, -v5, s3, v62
	v_fma_f32 v63, -v7, s98, v63
	v_fma_f32 v62, -v6, s99, v62
	v_readlane_b32 s2, v61, 9
	v_readlane_b32 s3, v61, 10
	v_readlane_b32 s98, v61, 11
	v_readlane_b32 s99, v61, 12
	v_fma_f32 v63, -v8, s2, v63
	v_fma_f32 v62, -v9, s3, v62
	v_fma_f32 v63, -v10, s98, v63
	v_fma_f32 v62, -v11, s99, v62
	v_readlane_b32 s2, v61, 13
	s_nop 1
	v_fma_f32 v61, -v60, s2, v63
	v_readlane_b32 s2, v58, 0
	v_add_f32_e32 v61, v62, v61
	s_nop 0
	v_fma_f32 v62, -v81, s2, v143
	v_readlane_b32 s2, v58, 1
	v_readlane_b32 s3, v58, 2
	v_readlane_b32 s98, v58, 3
	v_readlane_b32 s99, v58, 4
	v_fma_f32 v63, -v0, s2, 0
	v_fma_f32 v62, -v1, s3, v62
	v_fma_f32 v63, -v2, s98, v63
	v_fma_f32 v62, -v3, s99, v62
	v_readlane_b32 s2, v58, 5
	v_readlane_b32 s3, v58, 6
	v_readlane_b32 s98, v58, 7
	v_readlane_b32 s99, v58, 8
	v_fma_f32 v63, -v4, s2, v63
	v_fma_f32 v62, -v5, s3, v62
	v_fma_f32 v63, -v7, s98, v63
	v_fma_f32 v62, -v6, s99, v62
	v_readlane_b32 s2, v58, 9
	v_readlane_b32 s3, v58, 10
	v_readlane_b32 s98, v58, 11
	v_readlane_b32 s99, v58, 12
	v_fma_f32 v63, -v8, s2, v63
	v_fma_f32 v62, -v9, s3, v62
	v_fma_f32 v63, -v10, s98, v63
	v_fma_f32 v62, -v11, s99, v62
	v_readlane_b32 s2, v58, 13
	v_readlane_b32 s3, v58, 14
	s_nop 0
	v_fma_f32 v63, -v60, s2, v63
	v_fma_f32 v58, -v61, s3, v62
	v_readlane_b32 s2, v59, 0
	v_add_f32_e32 v58, v63, v58
	s_nop 0
	v_fma_f32 v62, -v81, s2, v145
	v_readlane_b32 s2, v59, 1
	v_readlane_b32 s3, v59, 2
	v_readlane_b32 s98, v59, 3
	v_readlane_b32 s99, v59, 4
	v_fma_f32 v63, -v0, s2, 0
	v_fma_f32 v62, -v1, s3, v62
	v_fma_f32 v63, -v2, s98, v63
	v_fma_f32 v62, -v3, s99, v62
	v_readlane_b32 s2, v59, 5
	v_readlane_b32 s3, v59, 6
	v_readlane_b32 s98, v59, 7
	v_readlane_b32 s99, v59, 8
	v_fma_f32 v63, -v4, s2, v63
	v_fma_f32 v62, -v5, s3, v62
	v_fma_f32 v63, -v7, s98, v63
	v_fma_f32 v62, -v6, s99, v62
	v_readlane_b32 s2, v59, 9
	v_readlane_b32 s3, v59, 10
	v_readlane_b32 s98, v59, 11
	v_readlane_b32 s99, v59, 12
	v_fma_f32 v63, -v8, s2, v63
	v_fma_f32 v62, -v9, s3, v62
	v_fma_f32 v63, -v10, s98, v63
	v_fma_f32 v62, -v11, s99, v62
	v_readlane_b32 s2, v59, 13
	v_readlane_b32 s3, v59, 14
	v_readlane_b32 s98, v59, 15
	v_fma_f32 v63, -v60, s2, v63
	v_fma_f32 v62, -v61, s3, v62
	v_fma_f32 v59, -v58, s98, v63
	v_readlane_b32 s2, v56, 0
	v_add_f32_e32 v59, v62, v59
	s_nop 0
	v_fma_f32 v62, -v81, s2, v133
	v_readlane_b32 s2, v56, 1
	v_readlane_b32 s3, v56, 2
	v_readlane_b32 s98, v56, 3
	v_readlane_b32 s99, v56, 4
	v_fma_f32 v63, -v0, s2, 0
	v_fma_f32 v62, -v1, s3, v62
	v_fma_f32 v63, -v2, s98, v63
	v_fma_f32 v62, -v3, s99, v62
	v_readlane_b32 s2, v56, 5
	v_readlane_b32 s3, v56, 6
	v_readlane_b32 s98, v56, 7
	v_readlane_b32 s99, v56, 8
	v_fma_f32 v63, -v4, s2, v63
	v_fma_f32 v62, -v5, s3, v62
	v_fma_f32 v63, -v7, s98, v63
	v_fma_f32 v62, -v6, s99, v62
	v_readlane_b32 s2, v56, 9
	v_readlane_b32 s3, v56, 10
	v_readlane_b32 s98, v56, 11
	v_readlane_b32 s99, v56, 12
	v_fma_f32 v63, -v8, s2, v63
	v_fma_f32 v62, -v9, s3, v62
	v_fma_f32 v63, -v10, s98, v63
	v_fma_f32 v62, -v11, s99, v62
	v_readlane_b32 s2, v56, 13
	v_readlane_b32 s3, v56, 14
	v_readlane_b32 s98, v56, 15
	v_readlane_b32 s99, v56, 16
	v_fma_f32 v63, -v60, s2, v63
	v_fma_f32 v62, -v61, s3, v62
	v_fma_f32 v63, -v58, s98, v63
	v_fma_f32 v56, -v59, s99, v62
	v_readlane_b32 s2, v57, 0
	v_add_f32_e32 v56, v63, v56
	s_nop 0
	v_fma_f32 v62, -v81, s2, v129
	v_readlane_b32 s2, v57, 1
	v_readlane_b32 s3, v57, 2
	v_readlane_b32 s98, v57, 3
	v_readlane_b32 s99, v57, 4
	v_fma_f32 v63, -v0, s2, 0
	v_fma_f32 v62, -v1, s3, v62
	v_fma_f32 v63, -v2, s98, v63
	v_fma_f32 v62, -v3, s99, v62
	v_readlane_b32 s2, v57, 5
	v_readlane_b32 s3, v57, 6
	v_readlane_b32 s98, v57, 7
	v_readlane_b32 s99, v57, 8
	v_fma_f32 v63, -v4, s2, v63
	v_fma_f32 v62, -v5, s3, v62
	v_fma_f32 v63, -v7, s98, v63
	v_fma_f32 v62, -v6, s99, v62
	v_readlane_b32 s2, v57, 9
	v_readlane_b32 s3, v57, 10
	v_readlane_b32 s98, v57, 11
	v_readlane_b32 s99, v57, 12
	v_fma_f32 v63, -v8, s2, v63
	v_fma_f32 v62, -v9, s3, v62
	v_fma_f32 v63, -v10, s98, v63
	v_fma_f32 v62, -v11, s99, v62
	v_readlane_b32 s2, v57, 13
	v_readlane_b32 s3, v57, 14
	v_readlane_b32 s98, v57, 15
	v_readlane_b32 s99, v57, 16
	v_fma_f32 v63, -v60, s2, v63
	v_fma_f32 v62, -v61, s3, v62
	v_fma_f32 v63, -v58, s98, v63
	v_fma_f32 v62, -v59, s99, v62
	v_readlane_b32 s2, v57, 17
	s_nop 1
	v_fma_f32 v57, -v56, s2, v63
	v_readlane_b32 s2, v54, 0
	v_add_f32_e32 v57, v62, v57
	s_nop 0
	v_fma_f32 v62, -v81, s2, v125
	v_readlane_b32 s2, v54, 1
	v_readlane_b32 s3, v54, 2
	v_readlane_b32 s98, v54, 3
	v_readlane_b32 s99, v54, 4
	v_fma_f32 v63, -v0, s2, 0
	v_fma_f32 v62, -v1, s3, v62
	v_fma_f32 v63, -v2, s98, v63
	v_fma_f32 v62, -v3, s99, v62
	v_readlane_b32 s2, v54, 5
	v_readlane_b32 s3, v54, 6
	v_readlane_b32 s98, v54, 7
	v_readlane_b32 s99, v54, 8
	v_fma_f32 v63, -v4, s2, v63
	v_fma_f32 v62, -v5, s3, v62
	v_fma_f32 v63, -v7, s98, v63
	v_fma_f32 v62, -v6, s99, v62
	v_readlane_b32 s2, v54, 9
	v_readlane_b32 s3, v54, 10
	v_readlane_b32 s98, v54, 11
	v_readlane_b32 s99, v54, 12
	v_fma_f32 v63, -v8, s2, v63
	v_fma_f32 v62, -v9, s3, v62
	v_fma_f32 v63, -v10, s98, v63
	v_fma_f32 v62, -v11, s99, v62
	v_readlane_b32 s2, v54, 13
	v_readlane_b32 s3, v54, 14
	v_readlane_b32 s98, v54, 15
	v_readlane_b32 s99, v54, 16
	v_fma_f32 v63, -v60, s2, v63
	v_fma_f32 v62, -v61, s3, v62
	v_fma_f32 v63, -v58, s98, v63
	v_fma_f32 v62, -v59, s99, v62
	v_readlane_b32 s2, v54, 17
	v_readlane_b32 s3, v54, 18
	s_nop 0
	v_fma_f32 v63, -v56, s2, v63
	v_fma_f32 v54, -v57, s3, v62
	v_readlane_b32 s2, v55, 0
	v_add_f32_e32 v54, v63, v54
	s_nop 0
	v_fma_f32 v62, -v81, s2, v136
	v_readlane_b32 s2, v55, 1
	v_readlane_b32 s3, v55, 2
	v_readlane_b32 s98, v55, 3
	v_readlane_b32 s99, v55, 4
	v_fma_f32 v63, -v0, s2, 0
	v_fma_f32 v62, -v1, s3, v62
	v_fma_f32 v63, -v2, s98, v63
	v_fma_f32 v62, -v3, s99, v62
	v_readlane_b32 s2, v55, 5
	v_readlane_b32 s3, v55, 6
	v_readlane_b32 s98, v55, 7
	v_readlane_b32 s99, v55, 8
	v_fma_f32 v63, -v4, s2, v63
	v_fma_f32 v62, -v5, s3, v62
	v_fma_f32 v63, -v7, s98, v63
	v_fma_f32 v62, -v6, s99, v62
	v_readlane_b32 s2, v55, 9
	v_readlane_b32 s3, v55, 10
	v_readlane_b32 s98, v55, 11
	v_readlane_b32 s99, v55, 12
	v_fma_f32 v63, -v8, s2, v63
	v_fma_f32 v62, -v9, s3, v62
	v_fma_f32 v63, -v10, s98, v63
	v_fma_f32 v62, -v11, s99, v62
	v_readlane_b32 s2, v55, 13
	v_readlane_b32 s3, v55, 14
	v_readlane_b32 s98, v55, 15
	v_readlane_b32 s99, v55, 16
	v_fma_f32 v63, -v60, s2, v63
	v_fma_f32 v62, -v61, s3, v62
	v_fma_f32 v63, -v58, s98, v63
	v_fma_f32 v62, -v59, s99, v62
	v_readlane_b32 s2, v55, 17
	v_readlane_b32 s3, v55, 18
	v_readlane_b32 s98, v55, 19
	v_fma_f32 v63, -v56, s2, v63
	v_fma_f32 v62, -v57, s3, v62
	v_fma_f32 v55, -v54, s98, v63
	v_readlane_b32 s2, v52, 0
	v_add_f32_e32 v55, v62, v55
	s_nop 0
	v_fma_f32 v62, -v81, s2, v134
	v_readlane_b32 s2, v52, 1
	v_readlane_b32 s3, v52, 2
	v_readlane_b32 s98, v52, 3
	v_readlane_b32 s99, v52, 4
	v_fma_f32 v63, -v0, s2, 0
	v_fma_f32 v62, -v1, s3, v62
	v_fma_f32 v63, -v2, s98, v63
	v_fma_f32 v62, -v3, s99, v62
	v_readlane_b32 s2, v52, 5
	v_readlane_b32 s3, v52, 6
	v_readlane_b32 s98, v52, 7
	v_readlane_b32 s99, v52, 8
	v_fma_f32 v63, -v4, s2, v63
	v_fma_f32 v62, -v5, s3, v62
	v_fma_f32 v63, -v7, s98, v63
	v_fma_f32 v62, -v6, s99, v62
	v_readlane_b32 s2, v52, 9
	v_readlane_b32 s3, v52, 10
	v_readlane_b32 s98, v52, 11
	v_readlane_b32 s99, v52, 12
	v_fma_f32 v63, -v8, s2, v63
	v_fma_f32 v62, -v9, s3, v62
	v_fma_f32 v63, -v10, s98, v63
	v_fma_f32 v62, -v11, s99, v62
	v_readlane_b32 s2, v52, 13
	v_readlane_b32 s3, v52, 14
	v_readlane_b32 s98, v52, 15
	v_readlane_b32 s99, v52, 16
	v_fma_f32 v63, -v60, s2, v63
	v_fma_f32 v62, -v61, s3, v62
	v_fma_f32 v63, -v58, s98, v63
	v_fma_f32 v62, -v59, s99, v62
	v_readlane_b32 s2, v52, 17
	v_readlane_b32 s3, v52, 18
	v_readlane_b32 s98, v52, 19
	v_readlane_b32 s99, v52, 20
	v_fma_f32 v63, -v56, s2, v63
	v_fma_f32 v62, -v57, s3, v62
	v_fma_f32 v63, -v54, s98, v63
	v_fma_f32 v52, -v55, s99, v62
	v_readlane_b32 s2, v53, 0
	v_add_f32_e32 v52, v63, v52
	s_nop 0
	v_fma_f32 v62, -v81, s2, v132
	v_readlane_b32 s2, v53, 1
	v_readlane_b32 s3, v53, 2
	v_readlane_b32 s98, v53, 3
	v_readlane_b32 s99, v53, 4
	v_fma_f32 v63, -v0, s2, 0
	v_fma_f32 v62, -v1, s3, v62
	v_fma_f32 v63, -v2, s98, v63
	v_fma_f32 v62, -v3, s99, v62
	v_readlane_b32 s2, v53, 5
	v_readlane_b32 s3, v53, 6
	v_readlane_b32 s98, v53, 7
	v_readlane_b32 s99, v53, 8
	v_fma_f32 v63, -v4, s2, v63
	v_fma_f32 v62, -v5, s3, v62
	v_fma_f32 v63, -v7, s98, v63
	v_fma_f32 v62, -v6, s99, v62
	v_readlane_b32 s2, v53, 9
	v_readlane_b32 s3, v53, 10
	v_readlane_b32 s98, v53, 11
	v_readlane_b32 s99, v53, 12
	v_fma_f32 v63, -v8, s2, v63
	v_fma_f32 v62, -v9, s3, v62
	v_fma_f32 v63, -v10, s98, v63
	v_fma_f32 v62, -v11, s99, v62
	v_readlane_b32 s2, v53, 13
	v_readlane_b32 s3, v53, 14
	v_readlane_b32 s98, v53, 15
	v_readlane_b32 s99, v53, 16
	v_fma_f32 v63, -v60, s2, v63
	v_fma_f32 v62, -v61, s3, v62
	v_fma_f32 v63, -v58, s98, v63
	v_fma_f32 v62, -v59, s99, v62
	v_readlane_b32 s2, v53, 17
	v_readlane_b32 s3, v53, 18
	v_readlane_b32 s98, v53, 19
	v_readlane_b32 s99, v53, 20
	v_fma_f32 v63, -v56, s2, v63
	v_fma_f32 v62, -v57, s3, v62
	v_fma_f32 v63, -v54, s98, v63
	v_fma_f32 v62, -v55, s99, v62
	v_readlane_b32 s2, v53, 21
	s_nop 1
	v_fma_f32 v53, -v52, s2, v63
	v_readlane_b32 s2, v50, 0
	v_add_f32_e32 v53, v62, v53
	s_nop 0
	v_fma_f32 v62, -v81, s2, v147
	v_readlane_b32 s2, v50, 1
	v_readlane_b32 s3, v50, 2
	v_readlane_b32 s98, v50, 3
	v_readlane_b32 s99, v50, 4
	v_fma_f32 v63, -v0, s2, 0
	v_fma_f32 v62, -v1, s3, v62
	v_fma_f32 v63, -v2, s98, v63
	v_fma_f32 v62, -v3, s99, v62
	v_readlane_b32 s2, v50, 5
	v_readlane_b32 s3, v50, 6
	v_readlane_b32 s98, v50, 7
	v_readlane_b32 s99, v50, 8
	v_fma_f32 v63, -v4, s2, v63
	v_fma_f32 v62, -v5, s3, v62
	v_fma_f32 v63, -v7, s98, v63
	v_fma_f32 v62, -v6, s99, v62
	v_readlane_b32 s2, v50, 9
	v_readlane_b32 s3, v50, 10
	v_readlane_b32 s98, v50, 11
	v_readlane_b32 s99, v50, 12
	v_fma_f32 v63, -v8, s2, v63
	v_fma_f32 v62, -v9, s3, v62
	v_fma_f32 v63, -v10, s98, v63
	v_fma_f32 v62, -v11, s99, v62
	v_readlane_b32 s2, v50, 13
	v_readlane_b32 s3, v50, 14
	v_readlane_b32 s98, v50, 15
	v_readlane_b32 s99, v50, 16
	v_fma_f32 v63, -v60, s2, v63
	v_fma_f32 v62, -v61, s3, v62
	v_fma_f32 v63, -v58, s98, v63
	v_fma_f32 v62, -v59, s99, v62
	v_readlane_b32 s2, v50, 17
	v_readlane_b32 s3, v50, 18
	v_readlane_b32 s98, v50, 19
	v_readlane_b32 s99, v50, 20
	v_fma_f32 v63, -v56, s2, v63
	v_fma_f32 v62, -v57, s3, v62
	v_fma_f32 v63, -v54, s98, v63
	v_fma_f32 v62, -v55, s99, v62
	v_readlane_b32 s2, v50, 21
	v_readlane_b32 s3, v50, 22
	s_nop 0
	v_fma_f32 v63, -v52, s2, v63
	v_fma_f32 v50, -v53, s3, v62
	v_readlane_b32 s2, v51, 0
	v_add_f32_e32 v50, v63, v50
	s_nop 0
	v_fma_f32 v62, -v81, s2, v146
	v_readlane_b32 s2, v51, 1
	v_readlane_b32 s3, v51, 2
	v_readlane_b32 s98, v51, 3
	v_readlane_b32 s99, v51, 4
	v_fma_f32 v63, -v0, s2, 0
	v_fma_f32 v62, -v1, s3, v62
	v_fma_f32 v63, -v2, s98, v63
	v_fma_f32 v62, -v3, s99, v62
	v_readlane_b32 s2, v51, 5
	v_readlane_b32 s3, v51, 6
	v_readlane_b32 s98, v51, 7
	v_readlane_b32 s99, v51, 8
	v_fma_f32 v63, -v4, s2, v63
	v_fma_f32 v62, -v5, s3, v62
	v_fma_f32 v63, -v7, s98, v63
	v_fma_f32 v62, -v6, s99, v62
	v_readlane_b32 s2, v51, 9
	v_readlane_b32 s3, v51, 10
	v_readlane_b32 s98, v51, 11
	v_readlane_b32 s99, v51, 12
	v_fma_f32 v63, -v8, s2, v63
	v_fma_f32 v62, -v9, s3, v62
	v_fma_f32 v63, -v10, s98, v63
	v_fma_f32 v62, -v11, s99, v62
	v_readlane_b32 s2, v51, 13
	v_readlane_b32 s3, v51, 14
	v_readlane_b32 s98, v51, 15
	v_readlane_b32 s99, v51, 16
	v_fma_f32 v63, -v60, s2, v63
	v_fma_f32 v62, -v61, s3, v62
	v_fma_f32 v63, -v58, s98, v63
	v_fma_f32 v62, -v59, s99, v62
	v_readlane_b32 s2, v51, 17
	v_readlane_b32 s3, v51, 18
	v_readlane_b32 s98, v51, 19
	v_readlane_b32 s99, v51, 20
	v_fma_f32 v63, -v56, s2, v63
	v_fma_f32 v62, -v57, s3, v62
	v_fma_f32 v63, -v54, s98, v63
	v_fma_f32 v62, -v55, s99, v62
	v_readlane_b32 s2, v51, 21
	v_readlane_b32 s3, v51, 22
	v_readlane_b32 s98, v51, 23
	v_fma_f32 v63, -v52, s2, v63
	v_fma_f32 v62, -v53, s3, v62
	v_fma_f32 v51, -v50, s98, v63
	v_readlane_b32 s2, v48, 0
	v_add_f32_e32 v51, v62, v51
	s_nop 0
	v_fma_f32 v62, -v81, s2, v135
	v_readlane_b32 s2, v48, 1
	v_readlane_b32 s3, v48, 2
	v_readlane_b32 s98, v48, 3
	v_readlane_b32 s99, v48, 4
	v_fma_f32 v63, -v0, s2, 0
	v_fma_f32 v62, -v1, s3, v62
	v_fma_f32 v63, -v2, s98, v63
	v_fma_f32 v62, -v3, s99, v62
	v_readlane_b32 s2, v48, 5
	v_readlane_b32 s3, v48, 6
	v_readlane_b32 s98, v48, 7
	v_readlane_b32 s99, v48, 8
	v_fma_f32 v63, -v4, s2, v63
	v_fma_f32 v62, -v5, s3, v62
	v_fma_f32 v63, -v7, s98, v63
	v_fma_f32 v62, -v6, s99, v62
	v_readlane_b32 s2, v48, 9
	v_readlane_b32 s3, v48, 10
	v_readlane_b32 s98, v48, 11
	v_readlane_b32 s99, v48, 12
	v_fma_f32 v63, -v8, s2, v63
	v_fma_f32 v62, -v9, s3, v62
	v_fma_f32 v63, -v10, s98, v63
	v_fma_f32 v62, -v11, s99, v62
	v_readlane_b32 s2, v48, 13
	v_readlane_b32 s3, v48, 14
	v_readlane_b32 s98, v48, 15
	v_readlane_b32 s99, v48, 16
	v_fma_f32 v63, -v60, s2, v63
	v_fma_f32 v62, -v61, s3, v62
	v_fma_f32 v63, -v58, s98, v63
	v_fma_f32 v62, -v59, s99, v62
	v_readlane_b32 s2, v48, 17
	v_readlane_b32 s3, v48, 18
	v_readlane_b32 s98, v48, 19
	v_readlane_b32 s99, v48, 20
	v_fma_f32 v63, -v56, s2, v63
	v_fma_f32 v62, -v57, s3, v62
	v_fma_f32 v63, -v54, s98, v63
	v_fma_f32 v62, -v55, s99, v62
	v_readlane_b32 s2, v48, 21
	v_readlane_b32 s3, v48, 22
	v_readlane_b32 s98, v48, 23
	v_readlane_b32 s99, v48, 24
	v_fma_f32 v63, -v52, s2, v63
	v_fma_f32 v62, -v53, s3, v62
	v_fma_f32 v63, -v50, s98, v63
	v_fma_f32 v48, -v51, s99, v62
	v_readlane_b32 s2, v49, 0
	v_add_f32_e32 v48, v63, v48
	s_nop 0
	v_fma_f32 v62, -v81, s2, v128
	v_readlane_b32 s2, v49, 1
	v_readlane_b32 s3, v49, 2
	v_readlane_b32 s98, v49, 3
	v_readlane_b32 s99, v49, 4
	v_fma_f32 v63, -v0, s2, 0
	v_fma_f32 v62, -v1, s3, v62
	v_fma_f32 v63, -v2, s98, v63
	v_fma_f32 v62, -v3, s99, v62
	v_readlane_b32 s2, v49, 5
	v_readlane_b32 s3, v49, 6
	v_readlane_b32 s98, v49, 7
	v_readlane_b32 s99, v49, 8
	v_fma_f32 v63, -v4, s2, v63
	v_fma_f32 v62, -v5, s3, v62
	v_fma_f32 v63, -v7, s98, v63
	v_fma_f32 v62, -v6, s99, v62
	v_readlane_b32 s2, v49, 9
	v_readlane_b32 s3, v49, 10
	v_readlane_b32 s98, v49, 11
	v_readlane_b32 s99, v49, 12
	v_fma_f32 v63, -v8, s2, v63
	v_fma_f32 v62, -v9, s3, v62
	v_fma_f32 v63, -v10, s98, v63
	v_fma_f32 v62, -v11, s99, v62
	v_readlane_b32 s2, v49, 13
	v_readlane_b32 s3, v49, 14
	v_readlane_b32 s98, v49, 15
	v_readlane_b32 s99, v49, 16
	v_fma_f32 v63, -v60, s2, v63
	v_fma_f32 v62, -v61, s3, v62
	v_fma_f32 v63, -v58, s98, v63
	v_fma_f32 v62, -v59, s99, v62
	v_readlane_b32 s2, v49, 17
	v_readlane_b32 s3, v49, 18
	v_readlane_b32 s98, v49, 19
	v_readlane_b32 s99, v49, 20
	v_fma_f32 v63, -v56, s2, v63
	v_fma_f32 v62, -v57, s3, v62
	v_fma_f32 v63, -v54, s98, v63
	v_fma_f32 v62, -v55, s99, v62
	v_readlane_b32 s2, v49, 21
	v_readlane_b32 s3, v49, 22
	v_readlane_b32 s98, v49, 23
	v_readlane_b32 s99, v49, 24
	v_fma_f32 v63, -v52, s2, v63
	v_fma_f32 v62, -v53, s3, v62
	v_fma_f32 v63, -v50, s98, v63
	v_fma_f32 v62, -v51, s99, v62
	v_readlane_b32 s2, v49, 25
	s_nop 1
	v_fma_f32 v49, -v48, s2, v63
	v_readlane_b32 s2, v46, 0
	v_add_f32_e32 v49, v62, v49
	s_nop 0
	v_fma_f32 v62, -v81, s2, v118
	v_readlane_b32 s2, v46, 1
	v_readlane_b32 s3, v46, 2
	v_readlane_b32 s98, v46, 3
	v_readlane_b32 s99, v46, 4
	v_fma_f32 v63, -v0, s2, 0
	v_fma_f32 v62, -v1, s3, v62
	v_fma_f32 v63, -v2, s98, v63
	v_fma_f32 v62, -v3, s99, v62
	v_readlane_b32 s2, v46, 5
	v_readlane_b32 s3, v46, 6
	v_readlane_b32 s98, v46, 7
	v_readlane_b32 s99, v46, 8
	v_fma_f32 v63, -v4, s2, v63
	v_fma_f32 v62, -v5, s3, v62
	v_fma_f32 v63, -v7, s98, v63
	v_fma_f32 v62, -v6, s99, v62
	v_readlane_b32 s2, v46, 9
	v_readlane_b32 s3, v46, 10
	v_readlane_b32 s98, v46, 11
	v_readlane_b32 s99, v46, 12
	v_fma_f32 v63, -v8, s2, v63
	v_fma_f32 v62, -v9, s3, v62
	v_fma_f32 v63, -v10, s98, v63
	v_fma_f32 v62, -v11, s99, v62
	v_readlane_b32 s2, v46, 13
	v_readlane_b32 s3, v46, 14
	v_readlane_b32 s98, v46, 15
	v_readlane_b32 s99, v46, 16
	v_fma_f32 v63, -v60, s2, v63
	v_fma_f32 v62, -v61, s3, v62
	v_fma_f32 v63, -v58, s98, v63
	v_fma_f32 v62, -v59, s99, v62
	v_readlane_b32 s2, v46, 17
	v_readlane_b32 s3, v46, 18
	v_readlane_b32 s98, v46, 19
	v_readlane_b32 s99, v46, 20
	v_fma_f32 v63, -v56, s2, v63
	v_fma_f32 v62, -v57, s3, v62
	v_fma_f32 v63, -v54, s98, v63
	v_fma_f32 v62, -v55, s99, v62
	v_readlane_b32 s2, v46, 21
	v_readlane_b32 s3, v46, 22
	v_readlane_b32 s98, v46, 23
	v_readlane_b32 s99, v46, 24
	v_fma_f32 v63, -v52, s2, v63
	v_fma_f32 v62, -v53, s3, v62
	v_fma_f32 v63, -v50, s98, v63
	v_fma_f32 v62, -v51, s99, v62
	v_readlane_b32 s2, v46, 25
	v_readlane_b32 s3, v46, 26
	s_nop 0
	v_fma_f32 v63, -v48, s2, v63
	v_fma_f32 v46, -v49, s3, v62
	v_readlane_b32 s2, v47, 0
	v_add_f32_e32 v46, v63, v46
	s_nop 0
	v_fma_f32 v62, -v81, s2, v130
	v_readlane_b32 s2, v47, 1
	v_readlane_b32 s3, v47, 2
	v_readlane_b32 s98, v47, 3
	v_readlane_b32 s99, v47, 4
	v_fma_f32 v63, -v0, s2, 0
	v_fma_f32 v62, -v1, s3, v62
	v_fma_f32 v63, -v2, s98, v63
	v_fma_f32 v62, -v3, s99, v62
	v_readlane_b32 s2, v47, 5
	v_readlane_b32 s3, v47, 6
	v_readlane_b32 s98, v47, 7
	v_readlane_b32 s99, v47, 8
	v_fma_f32 v63, -v4, s2, v63
	v_fma_f32 v62, -v5, s3, v62
	v_fma_f32 v63, -v7, s98, v63
	v_fma_f32 v62, -v6, s99, v62
	v_readlane_b32 s2, v47, 9
	v_readlane_b32 s3, v47, 10
	v_readlane_b32 s98, v47, 11
	v_readlane_b32 s99, v47, 12
	v_fma_f32 v63, -v8, s2, v63
	v_fma_f32 v62, -v9, s3, v62
	v_fma_f32 v63, -v10, s98, v63
	v_fma_f32 v62, -v11, s99, v62
	v_readlane_b32 s2, v47, 13
	v_readlane_b32 s3, v47, 14
	v_readlane_b32 s98, v47, 15
	v_readlane_b32 s99, v47, 16
	v_fma_f32 v63, -v60, s2, v63
	v_fma_f32 v62, -v61, s3, v62
	v_fma_f32 v63, -v58, s98, v63
	v_fma_f32 v62, -v59, s99, v62
	v_readlane_b32 s2, v47, 17
	v_readlane_b32 s3, v47, 18
	v_readlane_b32 s98, v47, 19
	v_readlane_b32 s99, v47, 20
	v_fma_f32 v63, -v56, s2, v63
	v_fma_f32 v62, -v57, s3, v62
	v_fma_f32 v63, -v54, s98, v63
	v_fma_f32 v62, -v55, s99, v62
	v_readlane_b32 s2, v47, 21
	v_readlane_b32 s3, v47, 22
	v_readlane_b32 s98, v47, 23
	v_readlane_b32 s99, v47, 24
	v_fma_f32 v63, -v52, s2, v63
	v_fma_f32 v62, -v53, s3, v62
	v_fma_f32 v63, -v50, s98, v63
	v_fma_f32 v62, -v51, s99, v62
	v_readlane_b32 s2, v47, 25
	v_readlane_b32 s3, v47, 26
	v_readlane_b32 s98, v47, 27
	v_fma_f32 v63, -v48, s2, v63
	v_fma_f32 v62, -v49, s3, v62
	v_fma_f32 v47, -v46, s98, v63
	v_readlane_b32 s2, v44, 0
	v_add_f32_e32 v47, v62, v47
	s_nop 0
	v_fma_f32 v62, -v81, s2, v127
	v_readlane_b32 s2, v44, 1
	v_readlane_b32 s3, v44, 2
	v_readlane_b32 s98, v44, 3
	v_readlane_b32 s99, v44, 4
	v_fma_f32 v63, -v0, s2, 0
	v_fma_f32 v62, -v1, s3, v62
	v_fma_f32 v63, -v2, s98, v63
	v_fma_f32 v62, -v3, s99, v62
	v_readlane_b32 s2, v44, 5
	v_readlane_b32 s3, v44, 6
	v_readlane_b32 s98, v44, 7
	v_readlane_b32 s99, v44, 8
	v_fma_f32 v63, -v4, s2, v63
	v_fma_f32 v62, -v5, s3, v62
	v_fma_f32 v63, -v7, s98, v63
	v_fma_f32 v62, -v6, s99, v62
	v_readlane_b32 s2, v44, 9
	v_readlane_b32 s3, v44, 10
	v_readlane_b32 s98, v44, 11
	v_readlane_b32 s99, v44, 12
	v_fma_f32 v63, -v8, s2, v63
	v_fma_f32 v62, -v9, s3, v62
	v_fma_f32 v63, -v10, s98, v63
	v_fma_f32 v62, -v11, s99, v62
	v_readlane_b32 s2, v44, 13
	v_readlane_b32 s3, v44, 14
	v_readlane_b32 s98, v44, 15
	v_readlane_b32 s99, v44, 16
	v_fma_f32 v63, -v60, s2, v63
	v_fma_f32 v62, -v61, s3, v62
	v_fma_f32 v63, -v58, s98, v63
	v_fma_f32 v62, -v59, s99, v62
	v_readlane_b32 s2, v44, 17
	v_readlane_b32 s3, v44, 18
	v_readlane_b32 s98, v44, 19
	v_readlane_b32 s99, v44, 20
	v_fma_f32 v63, -v56, s2, v63
	v_fma_f32 v62, -v57, s3, v62
	v_fma_f32 v63, -v54, s98, v63
	v_fma_f32 v62, -v55, s99, v62
	v_readlane_b32 s2, v44, 21
	v_readlane_b32 s3, v44, 22
	v_readlane_b32 s98, v44, 23
	v_readlane_b32 s99, v44, 24
	v_fma_f32 v63, -v52, s2, v63
	v_fma_f32 v62, -v53, s3, v62
	v_fma_f32 v63, -v50, s98, v63
	v_fma_f32 v62, -v51, s99, v62
	v_readlane_b32 s2, v44, 25
	v_readlane_b32 s3, v44, 26
	v_readlane_b32 s98, v44, 27
	v_readlane_b32 s99, v44, 28
	v_fma_f32 v63, -v48, s2, v63
	v_fma_f32 v62, -v49, s3, v62
	v_fma_f32 v63, -v46, s98, v63
	v_fma_f32 v44, -v47, s99, v62
	v_readlane_b32 s2, v45, 0
	v_add_f32_e32 v44, v63, v44
	s_nop 0
	v_fma_f32 v62, -v81, s2, v119
	v_readlane_b32 s2, v45, 1
	v_readlane_b32 s3, v45, 2
	v_readlane_b32 s98, v45, 3
	v_readlane_b32 s99, v45, 4
	v_fma_f32 v63, -v0, s2, 0
	v_fma_f32 v62, -v1, s3, v62
	v_fma_f32 v63, -v2, s98, v63
	v_fma_f32 v62, -v3, s99, v62
	v_readlane_b32 s2, v45, 5
	v_readlane_b32 s3, v45, 6
	v_readlane_b32 s98, v45, 7
	v_readlane_b32 s99, v45, 8
	v_fma_f32 v63, -v4, s2, v63
	v_fma_f32 v62, -v5, s3, v62
	v_fma_f32 v63, -v7, s98, v63
	v_fma_f32 v62, -v6, s99, v62
	v_readlane_b32 s2, v45, 9
	v_readlane_b32 s3, v45, 10
	v_readlane_b32 s98, v45, 11
	v_readlane_b32 s99, v45, 12
	v_fma_f32 v63, -v8, s2, v63
	v_fma_f32 v62, -v9, s3, v62
	v_fma_f32 v63, -v10, s98, v63
	v_fma_f32 v62, -v11, s99, v62
	v_readlane_b32 s2, v45, 13
	v_readlane_b32 s3, v45, 14
	v_readlane_b32 s98, v45, 15
	v_readlane_b32 s99, v45, 16
	v_fma_f32 v63, -v60, s2, v63
	v_fma_f32 v62, -v61, s3, v62
	v_fma_f32 v63, -v58, s98, v63
	v_fma_f32 v62, -v59, s99, v62
	v_readlane_b32 s2, v45, 17
	v_readlane_b32 s3, v45, 18
	v_readlane_b32 s98, v45, 19
	v_readlane_b32 s99, v45, 20
	v_fma_f32 v63, -v56, s2, v63
	v_fma_f32 v62, -v57, s3, v62
	v_fma_f32 v63, -v54, s98, v63
	v_fma_f32 v62, -v55, s99, v62
	v_readlane_b32 s2, v45, 21
	v_readlane_b32 s3, v45, 22
	v_readlane_b32 s98, v45, 23
	v_readlane_b32 s99, v45, 24
	v_fma_f32 v63, -v52, s2, v63
	v_fma_f32 v62, -v53, s3, v62
	v_fma_f32 v63, -v50, s98, v63
	v_fma_f32 v62, -v51, s99, v62
	v_readlane_b32 s2, v45, 25
	v_readlane_b32 s3, v45, 26
	v_readlane_b32 s98, v45, 27
	v_readlane_b32 s99, v45, 28
	v_fma_f32 v63, -v48, s2, v63
	v_fma_f32 v62, -v49, s3, v62
	v_fma_f32 v63, -v46, s98, v63
	v_fma_f32 v62, -v47, s99, v62
	v_readlane_b32 s2, v45, 29
	s_nop 1
	v_fma_f32 v45, -v44, s2, v63
	v_readlane_b32 s2, v42, 0
	v_add_f32_e32 v45, v62, v45
	s_nop 0
	v_fma_f32 v62, -v81, s2, v131
	v_readlane_b32 s2, v42, 1
	v_readlane_b32 s3, v42, 2
	v_readlane_b32 s98, v42, 3
	v_readlane_b32 s99, v42, 4
	v_fma_f32 v63, -v0, s2, 0
	v_fma_f32 v62, -v1, s3, v62
	v_fma_f32 v63, -v2, s98, v63
	v_fma_f32 v62, -v3, s99, v62
	v_readlane_b32 s2, v42, 5
	v_readlane_b32 s3, v42, 6
	v_readlane_b32 s98, v42, 7
	v_readlane_b32 s99, v42, 8
	v_fma_f32 v63, -v4, s2, v63
	v_fma_f32 v62, -v5, s3, v62
	v_fma_f32 v63, -v7, s98, v63
	v_fma_f32 v62, -v6, s99, v62
	v_readlane_b32 s2, v42, 9
	v_readlane_b32 s3, v42, 10
	v_readlane_b32 s98, v42, 11
	v_readlane_b32 s99, v42, 12
	v_fma_f32 v63, -v8, s2, v63
	v_fma_f32 v62, -v9, s3, v62
	v_fma_f32 v63, -v10, s98, v63
	v_fma_f32 v62, -v11, s99, v62
	v_readlane_b32 s2, v42, 13
	v_readlane_b32 s3, v42, 14
	v_readlane_b32 s98, v42, 15
	v_readlane_b32 s99, v42, 16
	v_fma_f32 v63, -v60, s2, v63
	v_fma_f32 v62, -v61, s3, v62
	v_fma_f32 v63, -v58, s98, v63
	v_fma_f32 v62, -v59, s99, v62
	v_readlane_b32 s2, v42, 17
	v_readlane_b32 s3, v42, 18
	v_readlane_b32 s98, v42, 19
	v_readlane_b32 s99, v42, 20
	v_fma_f32 v63, -v56, s2, v63
	v_fma_f32 v62, -v57, s3, v62
	v_fma_f32 v63, -v54, s98, v63
	v_fma_f32 v62, -v55, s99, v62
	v_readlane_b32 s2, v42, 21
	v_readlane_b32 s3, v42, 22
	v_readlane_b32 s98, v42, 23
	v_readlane_b32 s99, v42, 24
	v_fma_f32 v63, -v52, s2, v63
	v_fma_f32 v62, -v53, s3, v62
	v_fma_f32 v63, -v50, s98, v63
	v_fma_f32 v62, -v51, s99, v62
	v_readlane_b32 s2, v42, 25
	v_readlane_b32 s3, v42, 26
	v_readlane_b32 s98, v42, 27
	v_readlane_b32 s99, v42, 28
	v_fma_f32 v63, -v48, s2, v63
	v_fma_f32 v62, -v49, s3, v62
	v_fma_f32 v63, -v46, s98, v63
	v_fma_f32 v62, -v47, s99, v62
	v_readlane_b32 s2, v42, 29
	v_readlane_b32 s3, v42, 30
	s_nop 0
	v_fma_f32 v63, -v44, s2, v63
	v_fma_f32 v42, -v45, s3, v62
	v_readlane_b32 s2, v43, 0
	v_add_f32_e32 v42, v63, v42
	s_nop 0
	v_fma_f32 v62, -v81, s2, v126
	v_readlane_b32 s2, v43, 1
	v_readlane_b32 s3, v43, 2
	v_readlane_b32 s98, v43, 3
	v_readlane_b32 s99, v43, 4
	v_fma_f32 v63, -v0, s2, 0
	v_fma_f32 v62, -v1, s3, v62
	v_fma_f32 v63, -v2, s98, v63
	v_fma_f32 v62, -v3, s99, v62
	v_readlane_b32 s2, v43, 5
	v_readlane_b32 s3, v43, 6
	v_readlane_b32 s98, v43, 7
	v_readlane_b32 s99, v43, 8
	v_fma_f32 v63, -v4, s2, v63
	v_fma_f32 v62, -v5, s3, v62
	v_fma_f32 v63, -v7, s98, v63
	v_fma_f32 v62, -v6, s99, v62
	v_readlane_b32 s2, v43, 9
	v_readlane_b32 s3, v43, 10
	v_readlane_b32 s98, v43, 11
	v_readlane_b32 s99, v43, 12
	v_fma_f32 v63, -v8, s2, v63
	v_fma_f32 v62, -v9, s3, v62
	v_fma_f32 v63, -v10, s98, v63
	v_fma_f32 v62, -v11, s99, v62
	v_readlane_b32 s2, v43, 13
	v_readlane_b32 s3, v43, 14
	v_readlane_b32 s98, v43, 15
	v_readlane_b32 s99, v43, 16
	v_fma_f32 v63, -v60, s2, v63
	v_fma_f32 v62, -v61, s3, v62
	v_fma_f32 v63, -v58, s98, v63
	v_fma_f32 v62, -v59, s99, v62
	v_readlane_b32 s2, v43, 17
	v_readlane_b32 s3, v43, 18
	v_readlane_b32 s98, v43, 19
	v_readlane_b32 s99, v43, 20
	v_fma_f32 v63, -v56, s2, v63
	v_fma_f32 v62, -v57, s3, v62
	v_fma_f32 v63, -v54, s98, v63
	v_fma_f32 v62, -v55, s99, v62
	v_readlane_b32 s2, v43, 21
	v_readlane_b32 s3, v43, 22
	v_readlane_b32 s98, v43, 23
	v_readlane_b32 s99, v43, 24
	v_fma_f32 v63, -v52, s2, v63
	v_fma_f32 v62, -v53, s3, v62
	v_fma_f32 v63, -v50, s98, v63
	v_fma_f32 v62, -v51, s99, v62
	v_readlane_b32 s2, v43, 25
	v_readlane_b32 s3, v43, 26
	v_readlane_b32 s98, v43, 27
	v_readlane_b32 s99, v43, 28
	v_fma_f32 v63, -v48, s2, v63
	v_fma_f32 v62, -v49, s3, v62
	v_fma_f32 v63, -v46, s98, v63
	v_fma_f32 v62, -v47, s99, v62
	v_readlane_b32 s2, v43, 29
	v_readlane_b32 s3, v43, 30
	v_readlane_b32 s98, v43, 31
	v_fma_f32 v63, -v44, s2, v63
	v_fma_f32 v62, -v45, s3, v62
	v_fma_f32 v43, -v42, s98, v63
	v_readlane_b32 s2, v40, 0
	v_add_f32_e32 v43, v62, v43
	s_nop 0
	v_fma_f32 v62, -v81, s2, v115
	v_readlane_b32 s2, v40, 1
	v_readlane_b32 s3, v40, 2
	v_readlane_b32 s98, v40, 3
	v_readlane_b32 s99, v40, 4
	v_fma_f32 v63, -v0, s2, 0
	v_fma_f32 v62, -v1, s3, v62
	v_fma_f32 v63, -v2, s98, v63
	v_fma_f32 v62, -v3, s99, v62
	v_readlane_b32 s2, v40, 5
	v_readlane_b32 s3, v40, 6
	v_readlane_b32 s98, v40, 7
	v_readlane_b32 s99, v40, 8
	v_fma_f32 v63, -v4, s2, v63
	v_fma_f32 v62, -v5, s3, v62
	v_fma_f32 v63, -v7, s98, v63
	v_fma_f32 v62, -v6, s99, v62
	v_readlane_b32 s2, v40, 9
	v_readlane_b32 s3, v40, 10
	v_readlane_b32 s98, v40, 11
	v_readlane_b32 s99, v40, 12
	v_fma_f32 v63, -v8, s2, v63
	v_fma_f32 v62, -v9, s3, v62
	v_fma_f32 v63, -v10, s98, v63
	v_fma_f32 v62, -v11, s99, v62
	v_readlane_b32 s2, v40, 13
	v_readlane_b32 s3, v40, 14
	v_readlane_b32 s98, v40, 15
	v_readlane_b32 s99, v40, 16
	v_fma_f32 v63, -v60, s2, v63
	v_fma_f32 v62, -v61, s3, v62
	v_fma_f32 v63, -v58, s98, v63
	v_fma_f32 v62, -v59, s99, v62
	v_readlane_b32 s2, v40, 17
	v_readlane_b32 s3, v40, 18
	v_readlane_b32 s98, v40, 19
	v_readlane_b32 s99, v40, 20
	v_fma_f32 v63, -v56, s2, v63
	v_fma_f32 v62, -v57, s3, v62
	v_fma_f32 v63, -v54, s98, v63
	v_fma_f32 v62, -v55, s99, v62
	v_readlane_b32 s2, v40, 21
	v_readlane_b32 s3, v40, 22
	v_readlane_b32 s98, v40, 23
	v_readlane_b32 s99, v40, 24
	v_fma_f32 v63, -v52, s2, v63
	v_fma_f32 v62, -v53, s3, v62
	v_fma_f32 v63, -v50, s98, v63
	v_fma_f32 v62, -v51, s99, v62
	v_readlane_b32 s2, v40, 25
	v_readlane_b32 s3, v40, 26
	v_readlane_b32 s98, v40, 27
	v_readlane_b32 s99, v40, 28
	v_fma_f32 v63, -v48, s2, v63
	v_fma_f32 v62, -v49, s3, v62
	v_fma_f32 v63, -v46, s98, v63
	v_fma_f32 v62, -v47, s99, v62
	v_readlane_b32 s2, v40, 29
	v_readlane_b32 s3, v40, 30
	v_readlane_b32 s98, v40, 31
	v_readlane_b32 s99, v40, 32
	v_fma_f32 v63, -v44, s2, v63
	v_fma_f32 v62, -v45, s3, v62
	v_fma_f32 v63, -v42, s98, v63
	v_fma_f32 v40, -v43, s99, v62
	v_readlane_b32 s2, v41, 0
	v_add_f32_e32 v40, v63, v40
	s_nop 0
	v_fma_f32 v62, -v81, s2, v114
	v_readlane_b32 s2, v41, 1
	v_readlane_b32 s3, v41, 2
	v_readlane_b32 s98, v41, 3
	v_readlane_b32 s99, v41, 4
	v_fma_f32 v63, -v0, s2, 0
	v_fma_f32 v62, -v1, s3, v62
	v_fma_f32 v63, -v2, s98, v63
	v_fma_f32 v62, -v3, s99, v62
	v_readlane_b32 s2, v41, 5
	v_readlane_b32 s3, v41, 6
	v_readlane_b32 s98, v41, 7
	v_readlane_b32 s99, v41, 8
	v_fma_f32 v63, -v4, s2, v63
	v_fma_f32 v62, -v5, s3, v62
	v_fma_f32 v63, -v7, s98, v63
	v_fma_f32 v62, -v6, s99, v62
	v_readlane_b32 s2, v41, 9
	v_readlane_b32 s3, v41, 10
	v_readlane_b32 s98, v41, 11
	v_readlane_b32 s99, v41, 12
	v_fma_f32 v63, -v8, s2, v63
	v_fma_f32 v62, -v9, s3, v62
	v_fma_f32 v63, -v10, s98, v63
	v_fma_f32 v62, -v11, s99, v62
	v_readlane_b32 s2, v41, 13
	v_readlane_b32 s3, v41, 14
	v_readlane_b32 s98, v41, 15
	v_readlane_b32 s99, v41, 16
	v_fma_f32 v63, -v60, s2, v63
	v_fma_f32 v62, -v61, s3, v62
	v_fma_f32 v63, -v58, s98, v63
	v_fma_f32 v62, -v59, s99, v62
	v_readlane_b32 s2, v41, 17
	v_readlane_b32 s3, v41, 18
	v_readlane_b32 s98, v41, 19
	v_readlane_b32 s99, v41, 20
	v_fma_f32 v63, -v56, s2, v63
	v_fma_f32 v62, -v57, s3, v62
	v_fma_f32 v63, -v54, s98, v63
	v_fma_f32 v62, -v55, s99, v62
	v_readlane_b32 s2, v41, 21
	v_readlane_b32 s3, v41, 22
	v_readlane_b32 s98, v41, 23
	v_readlane_b32 s99, v41, 24
	v_fma_f32 v63, -v52, s2, v63
	v_fma_f32 v62, -v53, s3, v62
	v_fma_f32 v63, -v50, s98, v63
	v_fma_f32 v62, -v51, s99, v62
	v_readlane_b32 s2, v41, 25
	v_readlane_b32 s3, v41, 26
	v_readlane_b32 s98, v41, 27
	v_readlane_b32 s99, v41, 28
	v_fma_f32 v63, -v48, s2, v63
	v_fma_f32 v62, -v49, s3, v62
	v_fma_f32 v63, -v46, s98, v63
	v_fma_f32 v62, -v47, s99, v62
	v_readlane_b32 s2, v41, 29
	v_readlane_b32 s3, v41, 30
	v_readlane_b32 s98, v41, 31
	v_readlane_b32 s99, v41, 32
	v_fma_f32 v63, -v44, s2, v63
	v_fma_f32 v62, -v45, s3, v62
	v_fma_f32 v63, -v42, s98, v63
	v_fma_f32 v62, -v43, s99, v62
	v_readlane_b32 s2, v41, 33
	s_nop 1
	v_fma_f32 v41, -v40, s2, v63
	v_readlane_b32 s2, v38, 0
	v_add_f32_e32 v41, v62, v41
	s_nop 0
	v_fma_f32 v62, -v81, s2, v111
	v_readlane_b32 s2, v38, 1
	v_readlane_b32 s3, v38, 2
	v_readlane_b32 s98, v38, 3
	v_readlane_b32 s99, v38, 4
	v_fma_f32 v63, -v0, s2, 0
	v_fma_f32 v62, -v1, s3, v62
	v_fma_f32 v63, -v2, s98, v63
	v_fma_f32 v62, -v3, s99, v62
	v_readlane_b32 s2, v38, 5
	v_readlane_b32 s3, v38, 6
	v_readlane_b32 s98, v38, 7
	v_readlane_b32 s99, v38, 8
	v_fma_f32 v63, -v4, s2, v63
	v_fma_f32 v62, -v5, s3, v62
	v_fma_f32 v63, -v7, s98, v63
	v_fma_f32 v62, -v6, s99, v62
	v_readlane_b32 s2, v38, 9
	v_readlane_b32 s3, v38, 10
	v_readlane_b32 s98, v38, 11
	v_readlane_b32 s99, v38, 12
	v_fma_f32 v63, -v8, s2, v63
	v_fma_f32 v62, -v9, s3, v62
	v_fma_f32 v63, -v10, s98, v63
	v_fma_f32 v62, -v11, s99, v62
	v_readlane_b32 s2, v38, 13
	v_readlane_b32 s3, v38, 14
	v_readlane_b32 s98, v38, 15
	v_readlane_b32 s99, v38, 16
	v_fma_f32 v63, -v60, s2, v63
	v_fma_f32 v62, -v61, s3, v62
	v_fma_f32 v63, -v58, s98, v63
	v_fma_f32 v62, -v59, s99, v62
	v_readlane_b32 s2, v38, 17
	v_readlane_b32 s3, v38, 18
	v_readlane_b32 s98, v38, 19
	v_readlane_b32 s99, v38, 20
	v_fma_f32 v63, -v56, s2, v63
	v_fma_f32 v62, -v57, s3, v62
	v_fma_f32 v63, -v54, s98, v63
	v_fma_f32 v62, -v55, s99, v62
	v_readlane_b32 s2, v38, 21
	v_readlane_b32 s3, v38, 22
	v_readlane_b32 s98, v38, 23
	v_readlane_b32 s99, v38, 24
	v_fma_f32 v63, -v52, s2, v63
	v_fma_f32 v62, -v53, s3, v62
	v_fma_f32 v63, -v50, s98, v63
	v_fma_f32 v62, -v51, s99, v62
	v_readlane_b32 s2, v38, 25
	v_readlane_b32 s3, v38, 26
	v_readlane_b32 s98, v38, 27
	v_readlane_b32 s99, v38, 28
	v_fma_f32 v63, -v48, s2, v63
	v_fma_f32 v62, -v49, s3, v62
	v_fma_f32 v63, -v46, s98, v63
	v_fma_f32 v62, -v47, s99, v62
	v_readlane_b32 s2, v38, 29
	v_readlane_b32 s3, v38, 30
	v_readlane_b32 s98, v38, 31
	v_readlane_b32 s99, v38, 32
	v_fma_f32 v63, -v44, s2, v63
	v_fma_f32 v62, -v45, s3, v62
	v_fma_f32 v63, -v42, s98, v63
	v_fma_f32 v62, -v43, s99, v62
	v_readlane_b32 s2, v38, 33
	v_readlane_b32 s3, v38, 34
	s_nop 0
	v_fma_f32 v63, -v40, s2, v63
	v_fma_f32 v38, -v41, s3, v62
	v_readlane_b32 s2, v39, 0
	v_add_f32_e32 v38, v63, v38
	s_nop 0
	v_fma_f32 v62, -v81, s2, v113
	v_readlane_b32 s2, v39, 1
	v_readlane_b32 s3, v39, 2
	v_readlane_b32 s98, v39, 3
	v_readlane_b32 s99, v39, 4
	v_fma_f32 v63, -v0, s2, 0
	v_fma_f32 v62, -v1, s3, v62
	v_fma_f32 v63, -v2, s98, v63
	v_fma_f32 v62, -v3, s99, v62
	v_readlane_b32 s2, v39, 5
	v_readlane_b32 s3, v39, 6
	v_readlane_b32 s98, v39, 7
	v_readlane_b32 s99, v39, 8
	v_fma_f32 v63, -v4, s2, v63
	v_fma_f32 v62, -v5, s3, v62
	v_fma_f32 v63, -v7, s98, v63
	v_fma_f32 v62, -v6, s99, v62
	v_readlane_b32 s2, v39, 9
	v_readlane_b32 s3, v39, 10
	v_readlane_b32 s98, v39, 11
	v_readlane_b32 s99, v39, 12
	v_fma_f32 v63, -v8, s2, v63
	v_fma_f32 v62, -v9, s3, v62
	v_fma_f32 v63, -v10, s98, v63
	v_fma_f32 v62, -v11, s99, v62
	v_readlane_b32 s2, v39, 13
	v_readlane_b32 s3, v39, 14
	v_readlane_b32 s98, v39, 15
	v_readlane_b32 s99, v39, 16
	v_fma_f32 v63, -v60, s2, v63
	v_fma_f32 v62, -v61, s3, v62
	v_fma_f32 v63, -v58, s98, v63
	v_fma_f32 v62, -v59, s99, v62
	v_readlane_b32 s2, v39, 17
	v_readlane_b32 s3, v39, 18
	v_readlane_b32 s98, v39, 19
	v_readlane_b32 s99, v39, 20
	v_fma_f32 v63, -v56, s2, v63
	v_fma_f32 v62, -v57, s3, v62
	v_fma_f32 v63, -v54, s98, v63
	v_fma_f32 v62, -v55, s99, v62
	v_readlane_b32 s2, v39, 21
	v_readlane_b32 s3, v39, 22
	v_readlane_b32 s98, v39, 23
	v_readlane_b32 s99, v39, 24
	v_fma_f32 v63, -v52, s2, v63
	v_fma_f32 v62, -v53, s3, v62
	v_fma_f32 v63, -v50, s98, v63
	v_fma_f32 v62, -v51, s99, v62
	v_readlane_b32 s2, v39, 25
	v_readlane_b32 s3, v39, 26
	v_readlane_b32 s98, v39, 27
	v_readlane_b32 s99, v39, 28
	v_fma_f32 v63, -v48, s2, v63
	v_fma_f32 v62, -v49, s3, v62
	v_fma_f32 v63, -v46, s98, v63
	v_fma_f32 v62, -v47, s99, v62
	v_readlane_b32 s2, v39, 29
	v_readlane_b32 s3, v39, 30
	v_readlane_b32 s98, v39, 31
	v_readlane_b32 s99, v39, 32
	v_fma_f32 v63, -v44, s2, v63
	v_fma_f32 v62, -v45, s3, v62
	v_fma_f32 v63, -v42, s98, v63
	v_fma_f32 v62, -v43, s99, v62
	v_readlane_b32 s2, v39, 33
	v_readlane_b32 s3, v39, 34
	v_readlane_b32 s98, v39, 35
	v_fma_f32 v63, -v40, s2, v63
	v_fma_f32 v62, -v41, s3, v62
	v_fma_f32 v39, -v38, s98, v63
	v_readlane_b32 s2, v36, 0
	v_add_f32_e32 v39, v62, v39
	s_nop 0
	v_fma_f32 v62, -v81, s2, v112
	v_readlane_b32 s2, v36, 1
	v_readlane_b32 s3, v36, 2
	v_readlane_b32 s98, v36, 3
	v_readlane_b32 s99, v36, 4
	v_fma_f32 v63, -v0, s2, 0
	v_fma_f32 v62, -v1, s3, v62
	v_fma_f32 v63, -v2, s98, v63
	v_fma_f32 v62, -v3, s99, v62
	v_readlane_b32 s2, v36, 5
	v_readlane_b32 s3, v36, 6
	v_readlane_b32 s98, v36, 7
	v_readlane_b32 s99, v36, 8
	v_fma_f32 v63, -v4, s2, v63
	v_fma_f32 v62, -v5, s3, v62
	v_fma_f32 v63, -v7, s98, v63
	v_fma_f32 v62, -v6, s99, v62
	v_readlane_b32 s2, v36, 9
	v_readlane_b32 s3, v36, 10
	v_readlane_b32 s98, v36, 11
	v_readlane_b32 s99, v36, 12
	v_fma_f32 v63, -v8, s2, v63
	v_fma_f32 v62, -v9, s3, v62
	v_fma_f32 v63, -v10, s98, v63
	v_fma_f32 v62, -v11, s99, v62
	v_readlane_b32 s2, v36, 13
	v_readlane_b32 s3, v36, 14
	v_readlane_b32 s98, v36, 15
	v_readlane_b32 s99, v36, 16
	v_fma_f32 v63, -v60, s2, v63
	v_fma_f32 v62, -v61, s3, v62
	v_fma_f32 v63, -v58, s98, v63
	v_fma_f32 v62, -v59, s99, v62
	v_readlane_b32 s2, v36, 17
	v_readlane_b32 s3, v36, 18
	v_readlane_b32 s98, v36, 19
	v_readlane_b32 s99, v36, 20
	v_fma_f32 v63, -v56, s2, v63
	v_fma_f32 v62, -v57, s3, v62
	v_fma_f32 v63, -v54, s98, v63
	v_fma_f32 v62, -v55, s99, v62
	v_readlane_b32 s2, v36, 21
	v_readlane_b32 s3, v36, 22
	v_readlane_b32 s98, v36, 23
	v_readlane_b32 s99, v36, 24
	v_fma_f32 v63, -v52, s2, v63
	v_fma_f32 v62, -v53, s3, v62
	v_fma_f32 v63, -v50, s98, v63
	v_fma_f32 v62, -v51, s99, v62
	v_readlane_b32 s2, v36, 25
	v_readlane_b32 s3, v36, 26
	v_readlane_b32 s98, v36, 27
	v_readlane_b32 s99, v36, 28
	v_fma_f32 v63, -v48, s2, v63
	v_fma_f32 v62, -v49, s3, v62
	v_fma_f32 v63, -v46, s98, v63
	v_fma_f32 v62, -v47, s99, v62
	v_readlane_b32 s2, v36, 29
	v_readlane_b32 s3, v36, 30
	v_readlane_b32 s98, v36, 31
	v_readlane_b32 s99, v36, 32
	v_fma_f32 v63, -v44, s2, v63
	v_fma_f32 v62, -v45, s3, v62
	v_fma_f32 v63, -v42, s98, v63
	v_fma_f32 v62, -v43, s99, v62
	v_readlane_b32 s2, v36, 33
	v_readlane_b32 s3, v36, 34
	v_readlane_b32 s98, v36, 35
	v_readlane_b32 s99, v36, 36
	v_fma_f32 v63, -v40, s2, v63
	v_fma_f32 v62, -v41, s3, v62
	v_fma_f32 v63, -v38, s98, v63
	v_fma_f32 v36, -v39, s99, v62
	v_readlane_b32 s2, v37, 0
	v_add_f32_e32 v36, v63, v36
	s_nop 0
	v_fma_f32 v62, -v81, s2, v108
	v_readlane_b32 s2, v37, 1
	v_readlane_b32 s3, v37, 2
	v_readlane_b32 s98, v37, 3
	v_readlane_b32 s99, v37, 4
	v_fma_f32 v63, -v0, s2, 0
	v_fma_f32 v62, -v1, s3, v62
	v_fma_f32 v63, -v2, s98, v63
	v_fma_f32 v62, -v3, s99, v62
	v_readlane_b32 s2, v37, 5
	v_readlane_b32 s3, v37, 6
	v_readlane_b32 s98, v37, 7
	v_readlane_b32 s99, v37, 8
	v_fma_f32 v63, -v4, s2, v63
	v_fma_f32 v62, -v5, s3, v62
	v_fma_f32 v63, -v7, s98, v63
	v_fma_f32 v62, -v6, s99, v62
	v_readlane_b32 s2, v37, 9
	v_readlane_b32 s3, v37, 10
	v_readlane_b32 s98, v37, 11
	v_readlane_b32 s99, v37, 12
	v_fma_f32 v63, -v8, s2, v63
	v_fma_f32 v62, -v9, s3, v62
	v_fma_f32 v63, -v10, s98, v63
	v_fma_f32 v62, -v11, s99, v62
	v_readlane_b32 s2, v37, 13
	v_readlane_b32 s3, v37, 14
	v_readlane_b32 s98, v37, 15
	v_readlane_b32 s99, v37, 16
	v_fma_f32 v63, -v60, s2, v63
	v_fma_f32 v62, -v61, s3, v62
	v_fma_f32 v63, -v58, s98, v63
	v_fma_f32 v62, -v59, s99, v62
	v_readlane_b32 s2, v37, 17
	v_readlane_b32 s3, v37, 18
	v_readlane_b32 s98, v37, 19
	v_readlane_b32 s99, v37, 20
	v_fma_f32 v63, -v56, s2, v63
	v_fma_f32 v62, -v57, s3, v62
	v_fma_f32 v63, -v54, s98, v63
	v_fma_f32 v62, -v55, s99, v62
	v_readlane_b32 s2, v37, 21
	v_readlane_b32 s3, v37, 22
	v_readlane_b32 s98, v37, 23
	v_readlane_b32 s99, v37, 24
	v_fma_f32 v63, -v52, s2, v63
	v_fma_f32 v62, -v53, s3, v62
	v_fma_f32 v63, -v50, s98, v63
	v_fma_f32 v62, -v51, s99, v62
	v_readlane_b32 s2, v37, 25
	v_readlane_b32 s3, v37, 26
	v_readlane_b32 s98, v37, 27
	v_readlane_b32 s99, v37, 28
	v_fma_f32 v63, -v48, s2, v63
	v_fma_f32 v62, -v49, s3, v62
	v_fma_f32 v63, -v46, s98, v63
	v_fma_f32 v62, -v47, s99, v62
	v_readlane_b32 s2, v37, 29
	v_readlane_b32 s3, v37, 30
	v_readlane_b32 s98, v37, 31
	v_readlane_b32 s99, v37, 32
	v_fma_f32 v63, -v44, s2, v63
	v_fma_f32 v62, -v45, s3, v62
	v_fma_f32 v63, -v42, s98, v63
	v_fma_f32 v62, -v43, s99, v62
	v_readlane_b32 s2, v37, 33
	v_readlane_b32 s3, v37, 34
	v_readlane_b32 s98, v37, 35
	v_readlane_b32 s99, v37, 36
	v_fma_f32 v63, -v40, s2, v63
	v_fma_f32 v62, -v41, s3, v62
	v_fma_f32 v63, -v38, s98, v63
	v_fma_f32 v62, -v39, s99, v62
	v_readlane_b32 s2, v37, 37
	s_nop 1
	v_fma_f32 v37, -v36, s2, v63
	v_readlane_b32 s2, v34, 0
	v_add_f32_e32 v37, v62, v37
	s_nop 0
	v_fma_f32 v62, -v81, s2, v110
	v_readlane_b32 s2, v34, 1
	v_readlane_b32 s3, v34, 2
	v_readlane_b32 s98, v34, 3
	v_readlane_b32 s99, v34, 4
	v_fma_f32 v63, -v0, s2, 0
	v_fma_f32 v62, -v1, s3, v62
	v_fma_f32 v63, -v2, s98, v63
	v_fma_f32 v62, -v3, s99, v62
	v_readlane_b32 s2, v34, 5
	v_readlane_b32 s3, v34, 6
	v_readlane_b32 s98, v34, 7
	v_readlane_b32 s99, v34, 8
	v_fma_f32 v63, -v4, s2, v63
	v_fma_f32 v62, -v5, s3, v62
	v_fma_f32 v63, -v7, s98, v63
	v_fma_f32 v62, -v6, s99, v62
	v_readlane_b32 s2, v34, 9
	v_readlane_b32 s3, v34, 10
	v_readlane_b32 s98, v34, 11
	v_readlane_b32 s99, v34, 12
	v_fma_f32 v63, -v8, s2, v63
	v_fma_f32 v62, -v9, s3, v62
	v_fma_f32 v63, -v10, s98, v63
	v_fma_f32 v62, -v11, s99, v62
	v_readlane_b32 s2, v34, 13
	v_readlane_b32 s3, v34, 14
	v_readlane_b32 s98, v34, 15
	v_readlane_b32 s99, v34, 16
	v_fma_f32 v63, -v60, s2, v63
	v_fma_f32 v62, -v61, s3, v62
	v_fma_f32 v63, -v58, s98, v63
	v_fma_f32 v62, -v59, s99, v62
	v_readlane_b32 s2, v34, 17
	v_readlane_b32 s3, v34, 18
	v_readlane_b32 s98, v34, 19
	v_readlane_b32 s99, v34, 20
	v_fma_f32 v63, -v56, s2, v63
	v_fma_f32 v62, -v57, s3, v62
	v_fma_f32 v63, -v54, s98, v63
	v_fma_f32 v62, -v55, s99, v62
	v_readlane_b32 s2, v34, 21
	v_readlane_b32 s3, v34, 22
	v_readlane_b32 s98, v34, 23
	v_readlane_b32 s99, v34, 24
	v_fma_f32 v63, -v52, s2, v63
	v_fma_f32 v62, -v53, s3, v62
	v_fma_f32 v63, -v50, s98, v63
	v_fma_f32 v62, -v51, s99, v62
	v_readlane_b32 s2, v34, 25
	v_readlane_b32 s3, v34, 26
	v_readlane_b32 s98, v34, 27
	v_readlane_b32 s99, v34, 28
	v_fma_f32 v63, -v48, s2, v63
	v_fma_f32 v62, -v49, s3, v62
	v_fma_f32 v63, -v46, s98, v63
	v_fma_f32 v62, -v47, s99, v62
	v_readlane_b32 s2, v34, 29
	v_readlane_b32 s3, v34, 30
	v_readlane_b32 s98, v34, 31
	v_readlane_b32 s99, v34, 32
	v_fma_f32 v63, -v44, s2, v63
	v_fma_f32 v62, -v45, s3, v62
	v_fma_f32 v63, -v42, s98, v63
	v_fma_f32 v62, -v43, s99, v62
	v_readlane_b32 s2, v34, 33
	v_readlane_b32 s3, v34, 34
	v_readlane_b32 s98, v34, 35
	v_readlane_b32 s99, v34, 36
	v_fma_f32 v63, -v40, s2, v63
	v_fma_f32 v62, -v41, s3, v62
	v_fma_f32 v63, -v38, s98, v63
	v_fma_f32 v62, -v39, s99, v62
	v_readlane_b32 s2, v34, 37
	v_readlane_b32 s3, v34, 38
	s_nop 0
	v_fma_f32 v63, -v36, s2, v63
	v_fma_f32 v34, -v37, s3, v62
	v_readlane_b32 s2, v35, 0
	v_add_f32_e32 v34, v63, v34
	s_nop 0
	v_fma_f32 v62, -v81, s2, v107
	v_readlane_b32 s2, v35, 1
	v_readlane_b32 s3, v35, 2
	v_readlane_b32 s98, v35, 3
	v_readlane_b32 s99, v35, 4
	v_fma_f32 v63, -v0, s2, 0
	v_fma_f32 v62, -v1, s3, v62
	v_fma_f32 v63, -v2, s98, v63
	v_fma_f32 v62, -v3, s99, v62
	v_readlane_b32 s2, v35, 5
	v_readlane_b32 s3, v35, 6
	v_readlane_b32 s98, v35, 7
	v_readlane_b32 s99, v35, 8
	v_fma_f32 v63, -v4, s2, v63
	v_fma_f32 v62, -v5, s3, v62
	v_fma_f32 v63, -v7, s98, v63
	v_fma_f32 v62, -v6, s99, v62
	v_readlane_b32 s2, v35, 9
	v_readlane_b32 s3, v35, 10
	v_readlane_b32 s98, v35, 11
	v_readlane_b32 s99, v35, 12
	v_fma_f32 v63, -v8, s2, v63
	v_fma_f32 v62, -v9, s3, v62
	v_fma_f32 v63, -v10, s98, v63
	v_fma_f32 v62, -v11, s99, v62
	v_readlane_b32 s2, v35, 13
	v_readlane_b32 s3, v35, 14
	v_readlane_b32 s98, v35, 15
	v_readlane_b32 s99, v35, 16
	v_fma_f32 v63, -v60, s2, v63
	v_fma_f32 v62, -v61, s3, v62
	v_fma_f32 v63, -v58, s98, v63
	v_fma_f32 v62, -v59, s99, v62
	v_readlane_b32 s2, v35, 17
	v_readlane_b32 s3, v35, 18
	v_readlane_b32 s98, v35, 19
	v_readlane_b32 s99, v35, 20
	v_fma_f32 v63, -v56, s2, v63
	v_fma_f32 v62, -v57, s3, v62
	v_fma_f32 v63, -v54, s98, v63
	v_fma_f32 v62, -v55, s99, v62
	v_readlane_b32 s2, v35, 21
	v_readlane_b32 s3, v35, 22
	v_readlane_b32 s98, v35, 23
	v_readlane_b32 s99, v35, 24
	v_fma_f32 v63, -v52, s2, v63
	v_fma_f32 v62, -v53, s3, v62
	v_fma_f32 v63, -v50, s98, v63
	v_fma_f32 v62, -v51, s99, v62
	v_readlane_b32 s2, v35, 25
	v_readlane_b32 s3, v35, 26
	v_readlane_b32 s98, v35, 27
	v_readlane_b32 s99, v35, 28
	v_fma_f32 v63, -v48, s2, v63
	v_fma_f32 v62, -v49, s3, v62
	v_fma_f32 v63, -v46, s98, v63
	v_fma_f32 v62, -v47, s99, v62
	v_readlane_b32 s2, v35, 29
	v_readlane_b32 s3, v35, 30
	v_readlane_b32 s98, v35, 31
	v_readlane_b32 s99, v35, 32
	v_fma_f32 v63, -v44, s2, v63
	v_fma_f32 v62, -v45, s3, v62
	v_fma_f32 v63, -v42, s98, v63
	v_fma_f32 v62, -v43, s99, v62
	v_readlane_b32 s2, v35, 33
	v_readlane_b32 s3, v35, 34
	v_readlane_b32 s98, v35, 35
	v_readlane_b32 s99, v35, 36
	v_fma_f32 v63, -v40, s2, v63
	v_fma_f32 v62, -v41, s3, v62
	v_fma_f32 v63, -v38, s98, v63
	v_fma_f32 v62, -v39, s99, v62
	v_readlane_b32 s2, v35, 37
	v_readlane_b32 s3, v35, 38
	v_readlane_b32 s98, v35, 39
	v_fma_f32 v63, -v36, s2, v63
	v_fma_f32 v62, -v37, s3, v62
	v_fma_f32 v35, -v34, s98, v63
	v_readlane_b32 s2, v32, 0
	v_add_f32_e32 v35, v62, v35
	s_nop 0
	v_fma_f32 v62, -v81, s2, v104
	v_readlane_b32 s2, v32, 1
	v_readlane_b32 s3, v32, 2
	v_readlane_b32 s98, v32, 3
	v_readlane_b32 s99, v32, 4
	v_fma_f32 v63, -v0, s2, 0
	v_fma_f32 v62, -v1, s3, v62
	v_fma_f32 v63, -v2, s98, v63
	v_fma_f32 v62, -v3, s99, v62
	v_readlane_b32 s2, v32, 5
	v_readlane_b32 s3, v32, 6
	v_readlane_b32 s98, v32, 7
	v_readlane_b32 s99, v32, 8
	v_fma_f32 v63, -v4, s2, v63
	v_fma_f32 v62, -v5, s3, v62
	v_fma_f32 v63, -v7, s98, v63
	v_fma_f32 v62, -v6, s99, v62
	v_readlane_b32 s2, v32, 9
	v_readlane_b32 s3, v32, 10
	v_readlane_b32 s98, v32, 11
	v_readlane_b32 s99, v32, 12
	v_fma_f32 v63, -v8, s2, v63
	v_fma_f32 v62, -v9, s3, v62
	v_fma_f32 v63, -v10, s98, v63
	v_fma_f32 v62, -v11, s99, v62
	v_readlane_b32 s2, v32, 13
	v_readlane_b32 s3, v32, 14
	v_readlane_b32 s98, v32, 15
	v_readlane_b32 s99, v32, 16
	v_fma_f32 v63, -v60, s2, v63
	v_fma_f32 v62, -v61, s3, v62
	v_fma_f32 v63, -v58, s98, v63
	v_fma_f32 v62, -v59, s99, v62
	v_readlane_b32 s2, v32, 17
	v_readlane_b32 s3, v32, 18
	v_readlane_b32 s98, v32, 19
	v_readlane_b32 s99, v32, 20
	v_fma_f32 v63, -v56, s2, v63
	v_fma_f32 v62, -v57, s3, v62
	v_fma_f32 v63, -v54, s98, v63
	v_fma_f32 v62, -v55, s99, v62
	v_readlane_b32 s2, v32, 21
	v_readlane_b32 s3, v32, 22
	v_readlane_b32 s98, v32, 23
	v_readlane_b32 s99, v32, 24
	v_fma_f32 v63, -v52, s2, v63
	v_fma_f32 v62, -v53, s3, v62
	v_fma_f32 v63, -v50, s98, v63
	v_fma_f32 v62, -v51, s99, v62
	v_readlane_b32 s2, v32, 25
	v_readlane_b32 s3, v32, 26
	v_readlane_b32 s98, v32, 27
	v_readlane_b32 s99, v32, 28
	v_fma_f32 v63, -v48, s2, v63
	v_fma_f32 v62, -v49, s3, v62
	v_fma_f32 v63, -v46, s98, v63
	v_fma_f32 v62, -v47, s99, v62
	v_readlane_b32 s2, v32, 29
	v_readlane_b32 s3, v32, 30
	v_readlane_b32 s98, v32, 31
	v_readlane_b32 s99, v32, 32
	v_fma_f32 v63, -v44, s2, v63
	v_fma_f32 v62, -v45, s3, v62
	v_fma_f32 v63, -v42, s98, v63
	v_fma_f32 v62, -v43, s99, v62
	v_readlane_b32 s2, v32, 33
	v_readlane_b32 s3, v32, 34
	v_readlane_b32 s98, v32, 35
	v_readlane_b32 s99, v32, 36
	v_fma_f32 v63, -v40, s2, v63
	v_fma_f32 v62, -v41, s3, v62
	v_fma_f32 v63, -v38, s98, v63
	v_fma_f32 v62, -v39, s99, v62
	v_readlane_b32 s2, v32, 37
	v_readlane_b32 s3, v32, 38
	v_readlane_b32 s98, v32, 39
	v_readlane_b32 s99, v32, 40
	v_fma_f32 v63, -v36, s2, v63
	v_fma_f32 v62, -v37, s3, v62
	v_fma_f32 v63, -v34, s98, v63
	v_fma_f32 v32, -v35, s99, v62
	v_readlane_b32 s2, v33, 0
	v_add_f32_e32 v32, v63, v32
	s_nop 0
	v_fma_f32 v62, -v81, s2, v103
	v_readlane_b32 s2, v33, 1
	v_readlane_b32 s3, v33, 2
	v_readlane_b32 s98, v33, 3
	v_readlane_b32 s99, v33, 4
	v_fma_f32 v63, -v0, s2, 0
	v_fma_f32 v62, -v1, s3, v62
	v_fma_f32 v63, -v2, s98, v63
	v_fma_f32 v62, -v3, s99, v62
	v_readlane_b32 s2, v33, 5
	v_readlane_b32 s3, v33, 6
	v_readlane_b32 s98, v33, 7
	v_readlane_b32 s99, v33, 8
	v_fma_f32 v63, -v4, s2, v63
	v_fma_f32 v62, -v5, s3, v62
	v_fma_f32 v63, -v7, s98, v63
	v_fma_f32 v62, -v6, s99, v62
	v_readlane_b32 s2, v33, 9
	v_readlane_b32 s3, v33, 10
	v_readlane_b32 s98, v33, 11
	v_readlane_b32 s99, v33, 12
	v_fma_f32 v63, -v8, s2, v63
	v_fma_f32 v62, -v9, s3, v62
	v_fma_f32 v63, -v10, s98, v63
	v_fma_f32 v62, -v11, s99, v62
	v_readlane_b32 s2, v33, 13
	v_readlane_b32 s3, v33, 14
	v_readlane_b32 s98, v33, 15
	v_readlane_b32 s99, v33, 16
	v_fma_f32 v63, -v60, s2, v63
	v_fma_f32 v62, -v61, s3, v62
	v_fma_f32 v63, -v58, s98, v63
	v_fma_f32 v62, -v59, s99, v62
	v_readlane_b32 s2, v33, 17
	v_readlane_b32 s3, v33, 18
	v_readlane_b32 s98, v33, 19
	v_readlane_b32 s99, v33, 20
	v_fma_f32 v63, -v56, s2, v63
	v_fma_f32 v62, -v57, s3, v62
	v_fma_f32 v63, -v54, s98, v63
	v_fma_f32 v62, -v55, s99, v62
	v_readlane_b32 s2, v33, 21
	v_readlane_b32 s3, v33, 22
	v_readlane_b32 s98, v33, 23
	v_readlane_b32 s99, v33, 24
	v_fma_f32 v63, -v52, s2, v63
	v_fma_f32 v62, -v53, s3, v62
	v_fma_f32 v63, -v50, s98, v63
	v_fma_f32 v62, -v51, s99, v62
	v_readlane_b32 s2, v33, 25
	v_readlane_b32 s3, v33, 26
	v_readlane_b32 s98, v33, 27
	v_readlane_b32 s99, v33, 28
	v_fma_f32 v63, -v48, s2, v63
	v_fma_f32 v62, -v49, s3, v62
	v_fma_f32 v63, -v46, s98, v63
	v_fma_f32 v62, -v47, s99, v62
	v_readlane_b32 s2, v33, 29
	v_readlane_b32 s3, v33, 30
	v_readlane_b32 s98, v33, 31
	v_readlane_b32 s99, v33, 32
	v_fma_f32 v63, -v44, s2, v63
	v_fma_f32 v62, -v45, s3, v62
	v_fma_f32 v63, -v42, s98, v63
	v_fma_f32 v62, -v43, s99, v62
	v_readlane_b32 s2, v33, 33
	v_readlane_b32 s3, v33, 34
	v_readlane_b32 s98, v33, 35
	v_readlane_b32 s99, v33, 36
	v_fma_f32 v63, -v40, s2, v63
	v_fma_f32 v62, -v41, s3, v62
	v_fma_f32 v63, -v38, s98, v63
	v_fma_f32 v62, -v39, s99, v62
	v_readlane_b32 s2, v33, 37
	v_readlane_b32 s3, v33, 38
	v_readlane_b32 s98, v33, 39
	v_readlane_b32 s99, v33, 40
	v_fma_f32 v63, -v36, s2, v63
	v_fma_f32 v62, -v37, s3, v62
	v_fma_f32 v63, -v34, s98, v63
	v_fma_f32 v62, -v35, s99, v62
	v_readlane_b32 s2, v33, 41
	s_nop 1
	v_fma_f32 v33, -v32, s2, v63
	v_readlane_b32 s2, v30, 0
	v_add_f32_e32 v33, v62, v33
	s_nop 0
	v_fma_f32 v62, -v81, s2, v101
	v_readlane_b32 s2, v30, 1
	v_readlane_b32 s3, v30, 2
	v_readlane_b32 s98, v30, 3
	v_readlane_b32 s99, v30, 4
	v_fma_f32 v63, -v0, s2, 0
	v_fma_f32 v62, -v1, s3, v62
	v_fma_f32 v63, -v2, s98, v63
	v_fma_f32 v62, -v3, s99, v62
	v_readlane_b32 s2, v30, 5
	v_readlane_b32 s3, v30, 6
	v_readlane_b32 s98, v30, 7
	v_readlane_b32 s99, v30, 8
	v_fma_f32 v63, -v4, s2, v63
	v_fma_f32 v62, -v5, s3, v62
	v_fma_f32 v63, -v7, s98, v63
	v_fma_f32 v62, -v6, s99, v62
	v_readlane_b32 s2, v30, 9
	v_readlane_b32 s3, v30, 10
	v_readlane_b32 s98, v30, 11
	v_readlane_b32 s99, v30, 12
	v_fma_f32 v63, -v8, s2, v63
	v_fma_f32 v62, -v9, s3, v62
	v_fma_f32 v63, -v10, s98, v63
	v_fma_f32 v62, -v11, s99, v62
	v_readlane_b32 s2, v30, 13
	v_readlane_b32 s3, v30, 14
	v_readlane_b32 s98, v30, 15
	v_readlane_b32 s99, v30, 16
	v_fma_f32 v63, -v60, s2, v63
	v_fma_f32 v62, -v61, s3, v62
	v_fma_f32 v63, -v58, s98, v63
	v_fma_f32 v62, -v59, s99, v62
	v_readlane_b32 s2, v30, 17
	v_readlane_b32 s3, v30, 18
	v_readlane_b32 s98, v30, 19
	v_readlane_b32 s99, v30, 20
	v_fma_f32 v63, -v56, s2, v63
	v_fma_f32 v62, -v57, s3, v62
	v_fma_f32 v63, -v54, s98, v63
	v_fma_f32 v62, -v55, s99, v62
	v_readlane_b32 s2, v30, 21
	v_readlane_b32 s3, v30, 22
	v_readlane_b32 s98, v30, 23
	v_readlane_b32 s99, v30, 24
	v_fma_f32 v63, -v52, s2, v63
	v_fma_f32 v62, -v53, s3, v62
	v_fma_f32 v63, -v50, s98, v63
	v_fma_f32 v62, -v51, s99, v62
	v_readlane_b32 s2, v30, 25
	v_readlane_b32 s3, v30, 26
	v_readlane_b32 s98, v30, 27
	v_readlane_b32 s99, v30, 28
	v_fma_f32 v63, -v48, s2, v63
	v_fma_f32 v62, -v49, s3, v62
	v_fma_f32 v63, -v46, s98, v63
	v_fma_f32 v62, -v47, s99, v62
	v_readlane_b32 s2, v30, 29
	v_readlane_b32 s3, v30, 30
	v_readlane_b32 s98, v30, 31
	v_readlane_b32 s99, v30, 32
	v_fma_f32 v63, -v44, s2, v63
	v_fma_f32 v62, -v45, s3, v62
	v_fma_f32 v63, -v42, s98, v63
	v_fma_f32 v62, -v43, s99, v62
	v_readlane_b32 s2, v30, 33
	v_readlane_b32 s3, v30, 34
	v_readlane_b32 s98, v30, 35
	v_readlane_b32 s99, v30, 36
	v_fma_f32 v63, -v40, s2, v63
	v_fma_f32 v62, -v41, s3, v62
	v_fma_f32 v63, -v38, s98, v63
	v_fma_f32 v62, -v39, s99, v62
	v_readlane_b32 s2, v30, 37
	v_readlane_b32 s3, v30, 38
	v_readlane_b32 s98, v30, 39
	v_readlane_b32 s99, v30, 40
	v_fma_f32 v63, -v36, s2, v63
	v_fma_f32 v62, -v37, s3, v62
	v_fma_f32 v63, -v34, s98, v63
	v_fma_f32 v62, -v35, s99, v62
	v_readlane_b32 s2, v30, 41
	v_readlane_b32 s3, v30, 42
	s_nop 0
	v_fma_f32 v63, -v32, s2, v63
	v_fma_f32 v30, -v33, s3, v62
	v_readlane_b32 s2, v31, 0
	v_add_f32_e32 v30, v63, v30
	s_nop 0
	v_fma_f32 v62, -v81, s2, v102
	v_readlane_b32 s2, v31, 1
	v_readlane_b32 s3, v31, 2
	v_readlane_b32 s98, v31, 3
	v_readlane_b32 s99, v31, 4
	v_fma_f32 v63, -v0, s2, 0
	v_fma_f32 v62, -v1, s3, v62
	v_fma_f32 v63, -v2, s98, v63
	v_fma_f32 v62, -v3, s99, v62
	v_readlane_b32 s2, v31, 5
	v_readlane_b32 s3, v31, 6
	v_readlane_b32 s98, v31, 7
	v_readlane_b32 s99, v31, 8
	v_fma_f32 v63, -v4, s2, v63
	v_fma_f32 v62, -v5, s3, v62
	v_fma_f32 v63, -v7, s98, v63
	v_fma_f32 v62, -v6, s99, v62
	v_readlane_b32 s2, v31, 9
	v_readlane_b32 s3, v31, 10
	v_readlane_b32 s98, v31, 11
	v_readlane_b32 s99, v31, 12
	v_fma_f32 v63, -v8, s2, v63
	v_fma_f32 v62, -v9, s3, v62
	v_fma_f32 v63, -v10, s98, v63
	v_fma_f32 v62, -v11, s99, v62
	v_readlane_b32 s2, v31, 13
	v_readlane_b32 s3, v31, 14
	v_readlane_b32 s98, v31, 15
	v_readlane_b32 s99, v31, 16
	v_fma_f32 v63, -v60, s2, v63
	v_fma_f32 v62, -v61, s3, v62
	v_fma_f32 v63, -v58, s98, v63
	v_fma_f32 v62, -v59, s99, v62
	v_readlane_b32 s2, v31, 17
	v_readlane_b32 s3, v31, 18
	v_readlane_b32 s98, v31, 19
	v_readlane_b32 s99, v31, 20
	v_fma_f32 v63, -v56, s2, v63
	v_fma_f32 v62, -v57, s3, v62
	v_fma_f32 v63, -v54, s98, v63
	v_fma_f32 v62, -v55, s99, v62
	v_readlane_b32 s2, v31, 21
	v_readlane_b32 s3, v31, 22
	v_readlane_b32 s98, v31, 23
	v_readlane_b32 s99, v31, 24
	v_fma_f32 v63, -v52, s2, v63
	v_fma_f32 v62, -v53, s3, v62
	v_fma_f32 v63, -v50, s98, v63
	v_fma_f32 v62, -v51, s99, v62
	v_readlane_b32 s2, v31, 25
	v_readlane_b32 s3, v31, 26
	v_readlane_b32 s98, v31, 27
	v_readlane_b32 s99, v31, 28
	v_fma_f32 v63, -v48, s2, v63
	v_fma_f32 v62, -v49, s3, v62
	v_fma_f32 v63, -v46, s98, v63
	v_fma_f32 v62, -v47, s99, v62
	v_readlane_b32 s2, v31, 29
	v_readlane_b32 s3, v31, 30
	v_readlane_b32 s98, v31, 31
	v_readlane_b32 s99, v31, 32
	v_fma_f32 v63, -v44, s2, v63
	v_fma_f32 v62, -v45, s3, v62
	v_fma_f32 v63, -v42, s98, v63
	v_fma_f32 v62, -v43, s99, v62
	v_readlane_b32 s2, v31, 33
	v_readlane_b32 s3, v31, 34
	v_readlane_b32 s98, v31, 35
	v_readlane_b32 s99, v31, 36
	v_fma_f32 v63, -v40, s2, v63
	v_fma_f32 v62, -v41, s3, v62
	v_fma_f32 v63, -v38, s98, v63
	v_fma_f32 v62, -v39, s99, v62
	v_readlane_b32 s2, v31, 37
	v_readlane_b32 s3, v31, 38
	v_readlane_b32 s98, v31, 39
	v_readlane_b32 s99, v31, 40
	v_fma_f32 v63, -v36, s2, v63
	v_fma_f32 v62, -v37, s3, v62
	v_fma_f32 v63, -v34, s98, v63
	v_fma_f32 v62, -v35, s99, v62
	v_readlane_b32 s2, v31, 41
	v_readlane_b32 s3, v31, 42
	v_readlane_b32 s98, v31, 43
	v_fma_f32 v63, -v32, s2, v63
	v_fma_f32 v62, -v33, s3, v62
	v_fma_f32 v31, -v30, s98, v63
	v_readlane_b32 s2, v28, 0
	v_add_f32_e32 v31, v62, v31
	s_nop 0
	v_fma_f32 v62, -v81, s2, v100
	v_readlane_b32 s2, v28, 1
	v_readlane_b32 s3, v28, 2
	v_readlane_b32 s98, v28, 3
	v_readlane_b32 s99, v28, 4
	v_fma_f32 v63, -v0, s2, 0
	v_fma_f32 v62, -v1, s3, v62
	v_fma_f32 v63, -v2, s98, v63
	v_fma_f32 v62, -v3, s99, v62
	v_readlane_b32 s2, v28, 5
	v_readlane_b32 s3, v28, 6
	v_readlane_b32 s98, v28, 7
	v_readlane_b32 s99, v28, 8
	v_fma_f32 v63, -v4, s2, v63
	v_fma_f32 v62, -v5, s3, v62
	v_fma_f32 v63, -v7, s98, v63
	v_fma_f32 v62, -v6, s99, v62
	v_readlane_b32 s2, v28, 9
	v_readlane_b32 s3, v28, 10
	v_readlane_b32 s98, v28, 11
	v_readlane_b32 s99, v28, 12
	v_fma_f32 v63, -v8, s2, v63
	v_fma_f32 v62, -v9, s3, v62
	v_fma_f32 v63, -v10, s98, v63
	v_fma_f32 v62, -v11, s99, v62
	v_readlane_b32 s2, v28, 13
	v_readlane_b32 s3, v28, 14
	v_readlane_b32 s98, v28, 15
	v_readlane_b32 s99, v28, 16
	v_fma_f32 v63, -v60, s2, v63
	v_fma_f32 v62, -v61, s3, v62
	v_fma_f32 v63, -v58, s98, v63
	v_fma_f32 v62, -v59, s99, v62
	v_readlane_b32 s2, v28, 17
	v_readlane_b32 s3, v28, 18
	v_readlane_b32 s98, v28, 19
	v_readlane_b32 s99, v28, 20
	v_fma_f32 v63, -v56, s2, v63
	v_fma_f32 v62, -v57, s3, v62
	v_fma_f32 v63, -v54, s98, v63
	v_fma_f32 v62, -v55, s99, v62
	v_readlane_b32 s2, v28, 21
	v_readlane_b32 s3, v28, 22
	v_readlane_b32 s98, v28, 23
	v_readlane_b32 s99, v28, 24
	v_fma_f32 v63, -v52, s2, v63
	v_fma_f32 v62, -v53, s3, v62
	v_fma_f32 v63, -v50, s98, v63
	v_fma_f32 v62, -v51, s99, v62
	v_readlane_b32 s2, v28, 25
	v_readlane_b32 s3, v28, 26
	v_readlane_b32 s98, v28, 27
	v_readlane_b32 s99, v28, 28
	v_fma_f32 v63, -v48, s2, v63
	v_fma_f32 v62, -v49, s3, v62
	v_fma_f32 v63, -v46, s98, v63
	v_fma_f32 v62, -v47, s99, v62
	v_readlane_b32 s2, v28, 29
	v_readlane_b32 s3, v28, 30
	v_readlane_b32 s98, v28, 31
	v_readlane_b32 s99, v28, 32
	v_fma_f32 v63, -v44, s2, v63
	v_fma_f32 v62, -v45, s3, v62
	v_fma_f32 v63, -v42, s98, v63
	v_fma_f32 v62, -v43, s99, v62
	v_readlane_b32 s2, v28, 33
	v_readlane_b32 s3, v28, 34
	v_readlane_b32 s98, v28, 35
	v_readlane_b32 s99, v28, 36
	v_fma_f32 v63, -v40, s2, v63
	v_fma_f32 v62, -v41, s3, v62
	v_fma_f32 v63, -v38, s98, v63
	v_fma_f32 v62, -v39, s99, v62
	v_readlane_b32 s2, v28, 37
	v_readlane_b32 s3, v28, 38
	v_readlane_b32 s98, v28, 39
	v_readlane_b32 s99, v28, 40
	v_fma_f32 v63, -v36, s2, v63
	v_fma_f32 v62, -v37, s3, v62
	v_fma_f32 v63, -v34, s98, v63
	v_fma_f32 v62, -v35, s99, v62
	v_readlane_b32 s2, v28, 41
	v_readlane_b32 s3, v28, 42
	v_readlane_b32 s98, v28, 43
	v_readlane_b32 s99, v28, 44
	v_fma_f32 v63, -v32, s2, v63
	v_fma_f32 v62, -v33, s3, v62
	v_fma_f32 v63, -v30, s98, v63
	v_fma_f32 v28, -v31, s99, v62
	v_readlane_b32 s2, v29, 0
	v_add_f32_e32 v28, v63, v28
	s_nop 0
	v_fma_f32 v62, -v81, s2, v98
	v_readlane_b32 s2, v29, 1
	v_readlane_b32 s3, v29, 2
	v_readlane_b32 s98, v29, 3
	v_readlane_b32 s99, v29, 4
	v_fma_f32 v63, -v0, s2, 0
	v_fma_f32 v62, -v1, s3, v62
	v_fma_f32 v63, -v2, s98, v63
	v_fma_f32 v62, -v3, s99, v62
	v_readlane_b32 s2, v29, 5
	v_readlane_b32 s3, v29, 6
	v_readlane_b32 s98, v29, 7
	v_readlane_b32 s99, v29, 8
	v_fma_f32 v63, -v4, s2, v63
	v_fma_f32 v62, -v5, s3, v62
	v_fma_f32 v63, -v7, s98, v63
	v_fma_f32 v62, -v6, s99, v62
	v_readlane_b32 s2, v29, 9
	v_readlane_b32 s3, v29, 10
	v_readlane_b32 s98, v29, 11
	v_readlane_b32 s99, v29, 12
	v_fma_f32 v63, -v8, s2, v63
	v_fma_f32 v62, -v9, s3, v62
	v_fma_f32 v63, -v10, s98, v63
	v_fma_f32 v62, -v11, s99, v62
	v_readlane_b32 s2, v29, 13
	v_readlane_b32 s3, v29, 14
	v_readlane_b32 s98, v29, 15
	v_readlane_b32 s99, v29, 16
	v_fma_f32 v63, -v60, s2, v63
	v_fma_f32 v62, -v61, s3, v62
	v_fma_f32 v63, -v58, s98, v63
	v_fma_f32 v62, -v59, s99, v62
	v_readlane_b32 s2, v29, 17
	v_readlane_b32 s3, v29, 18
	v_readlane_b32 s98, v29, 19
	v_readlane_b32 s99, v29, 20
	v_fma_f32 v63, -v56, s2, v63
	v_fma_f32 v62, -v57, s3, v62
	v_fma_f32 v63, -v54, s98, v63
	v_fma_f32 v62, -v55, s99, v62
	v_readlane_b32 s2, v29, 21
	v_readlane_b32 s3, v29, 22
	v_readlane_b32 s98, v29, 23
	v_readlane_b32 s99, v29, 24
	v_fma_f32 v63, -v52, s2, v63
	v_fma_f32 v62, -v53, s3, v62
	v_fma_f32 v63, -v50, s98, v63
	v_fma_f32 v62, -v51, s99, v62
	v_readlane_b32 s2, v29, 25
	v_readlane_b32 s3, v29, 26
	v_readlane_b32 s98, v29, 27
	v_readlane_b32 s99, v29, 28
	v_fma_f32 v63, -v48, s2, v63
	v_fma_f32 v62, -v49, s3, v62
	v_fma_f32 v63, -v46, s98, v63
	v_fma_f32 v62, -v47, s99, v62
	v_readlane_b32 s2, v29, 29
	v_readlane_b32 s3, v29, 30
	v_readlane_b32 s98, v29, 31
	v_readlane_b32 s99, v29, 32
	v_fma_f32 v63, -v44, s2, v63
	v_fma_f32 v62, -v45, s3, v62
	v_fma_f32 v63, -v42, s98, v63
	v_fma_f32 v62, -v43, s99, v62
	v_readlane_b32 s2, v29, 33
	v_readlane_b32 s3, v29, 34
	v_readlane_b32 s98, v29, 35
	v_readlane_b32 s99, v29, 36
	v_fma_f32 v63, -v40, s2, v63
	v_fma_f32 v62, -v41, s3, v62
	v_fma_f32 v63, -v38, s98, v63
	v_fma_f32 v62, -v39, s99, v62
	v_readlane_b32 s2, v29, 37
	v_readlane_b32 s3, v29, 38
	v_readlane_b32 s98, v29, 39
	v_readlane_b32 s99, v29, 40
	v_fma_f32 v63, -v36, s2, v63
	v_fma_f32 v62, -v37, s3, v62
	v_fma_f32 v63, -v34, s98, v63
	v_fma_f32 v62, -v35, s99, v62
	v_readlane_b32 s2, v29, 41
	v_readlane_b32 s3, v29, 42
	v_readlane_b32 s98, v29, 43
	v_readlane_b32 s99, v29, 44
	v_fma_f32 v63, -v32, s2, v63
	v_fma_f32 v62, -v33, s3, v62
	v_fma_f32 v63, -v30, s98, v63
	v_fma_f32 v62, -v31, s99, v62
	v_readlane_b32 s2, v29, 45
	s_nop 1
	v_fma_f32 v29, -v28, s2, v63
	v_readlane_b32 s2, v26, 0
	v_add_f32_e32 v29, v62, v29
	s_nop 0
	v_fma_f32 v62, -v81, s2, v99
	v_readlane_b32 s2, v26, 1
	v_readlane_b32 s3, v26, 2
	v_readlane_b32 s98, v26, 3
	v_readlane_b32 s99, v26, 4
	v_fma_f32 v63, -v0, s2, 0
	v_fma_f32 v62, -v1, s3, v62
	v_fma_f32 v63, -v2, s98, v63
	v_fma_f32 v62, -v3, s99, v62
	v_readlane_b32 s2, v26, 5
	v_readlane_b32 s3, v26, 6
	v_readlane_b32 s98, v26, 7
	v_readlane_b32 s99, v26, 8
	v_fma_f32 v63, -v4, s2, v63
	v_fma_f32 v62, -v5, s3, v62
	v_fma_f32 v63, -v7, s98, v63
	v_fma_f32 v62, -v6, s99, v62
	v_readlane_b32 s2, v26, 9
	v_readlane_b32 s3, v26, 10
	v_readlane_b32 s98, v26, 11
	v_readlane_b32 s99, v26, 12
	v_fma_f32 v63, -v8, s2, v63
	v_fma_f32 v62, -v9, s3, v62
	v_fma_f32 v63, -v10, s98, v63
	v_fma_f32 v62, -v11, s99, v62
	v_readlane_b32 s2, v26, 13
	v_readlane_b32 s3, v26, 14
	v_readlane_b32 s98, v26, 15
	v_readlane_b32 s99, v26, 16
	v_fma_f32 v63, -v60, s2, v63
	v_fma_f32 v62, -v61, s3, v62
	v_fma_f32 v63, -v58, s98, v63
	v_fma_f32 v62, -v59, s99, v62
	v_readlane_b32 s2, v26, 17
	v_readlane_b32 s3, v26, 18
	v_readlane_b32 s98, v26, 19
	v_readlane_b32 s99, v26, 20
	v_fma_f32 v63, -v56, s2, v63
	v_fma_f32 v62, -v57, s3, v62
	v_fma_f32 v63, -v54, s98, v63
	v_fma_f32 v62, -v55, s99, v62
	v_readlane_b32 s2, v26, 21
	v_readlane_b32 s3, v26, 22
	v_readlane_b32 s98, v26, 23
	v_readlane_b32 s99, v26, 24
	v_fma_f32 v63, -v52, s2, v63
	v_fma_f32 v62, -v53, s3, v62
	v_fma_f32 v63, -v50, s98, v63
	v_fma_f32 v62, -v51, s99, v62
	v_readlane_b32 s2, v26, 25
	v_readlane_b32 s3, v26, 26
	v_readlane_b32 s98, v26, 27
	v_readlane_b32 s99, v26, 28
	v_fma_f32 v63, -v48, s2, v63
	v_fma_f32 v62, -v49, s3, v62
	v_fma_f32 v63, -v46, s98, v63
	v_fma_f32 v62, -v47, s99, v62
	v_readlane_b32 s2, v26, 29
	v_readlane_b32 s3, v26, 30
	v_readlane_b32 s98, v26, 31
	v_readlane_b32 s99, v26, 32
	v_fma_f32 v63, -v44, s2, v63
	v_fma_f32 v62, -v45, s3, v62
	v_fma_f32 v63, -v42, s98, v63
	v_fma_f32 v62, -v43, s99, v62
	v_readlane_b32 s2, v26, 33
	v_readlane_b32 s3, v26, 34
	v_readlane_b32 s98, v26, 35
	v_readlane_b32 s99, v26, 36
	v_fma_f32 v63, -v40, s2, v63
	v_fma_f32 v62, -v41, s3, v62
	v_fma_f32 v63, -v38, s98, v63
	v_fma_f32 v62, -v39, s99, v62
	v_readlane_b32 s2, v26, 37
	v_readlane_b32 s3, v26, 38
	v_readlane_b32 s98, v26, 39
	v_readlane_b32 s99, v26, 40
	v_fma_f32 v63, -v36, s2, v63
	v_fma_f32 v62, -v37, s3, v62
	v_fma_f32 v63, -v34, s98, v63
	v_fma_f32 v62, -v35, s99, v62
	v_readlane_b32 s2, v26, 41
	v_readlane_b32 s3, v26, 42
	v_readlane_b32 s98, v26, 43
	v_readlane_b32 s99, v26, 44
	v_fma_f32 v63, -v32, s2, v63
	v_fma_f32 v62, -v33, s3, v62
	v_fma_f32 v63, -v30, s98, v63
	v_fma_f32 v62, -v31, s99, v62
	v_readlane_b32 s2, v26, 45
	v_readlane_b32 s3, v26, 46
	s_nop 0
	v_fma_f32 v63, -v28, s2, v63
	v_fma_f32 v26, -v29, s3, v62
	v_readlane_b32 s2, v27, 0
	v_add_f32_e32 v26, v63, v26
	s_nop 0
	v_fma_f32 v62, -v81, s2, v97
	v_readlane_b32 s2, v27, 1
	v_readlane_b32 s3, v27, 2
	v_readlane_b32 s98, v27, 3
	v_readlane_b32 s99, v27, 4
	v_fma_f32 v63, -v0, s2, 0
	v_fma_f32 v62, -v1, s3, v62
	v_fma_f32 v63, -v2, s98, v63
	v_fma_f32 v62, -v3, s99, v62
	v_readlane_b32 s2, v27, 5
	v_readlane_b32 s3, v27, 6
	v_readlane_b32 s98, v27, 7
	v_readlane_b32 s99, v27, 8
	v_fma_f32 v63, -v4, s2, v63
	v_fma_f32 v62, -v5, s3, v62
	v_fma_f32 v63, -v7, s98, v63
	v_fma_f32 v62, -v6, s99, v62
	v_readlane_b32 s2, v27, 9
	v_readlane_b32 s3, v27, 10
	v_readlane_b32 s98, v27, 11
	v_readlane_b32 s99, v27, 12
	v_fma_f32 v63, -v8, s2, v63
	v_fma_f32 v62, -v9, s3, v62
	v_fma_f32 v63, -v10, s98, v63
	v_fma_f32 v62, -v11, s99, v62
	v_readlane_b32 s2, v27, 13
	v_readlane_b32 s3, v27, 14
	v_readlane_b32 s98, v27, 15
	v_readlane_b32 s99, v27, 16
	v_fma_f32 v63, -v60, s2, v63
	v_fma_f32 v62, -v61, s3, v62
	v_fma_f32 v63, -v58, s98, v63
	v_fma_f32 v62, -v59, s99, v62
	v_readlane_b32 s2, v27, 17
	v_readlane_b32 s3, v27, 18
	v_readlane_b32 s98, v27, 19
	v_readlane_b32 s99, v27, 20
	v_fma_f32 v63, -v56, s2, v63
	v_fma_f32 v62, -v57, s3, v62
	v_fma_f32 v63, -v54, s98, v63
	v_fma_f32 v62, -v55, s99, v62
	v_readlane_b32 s2, v27, 21
	v_readlane_b32 s3, v27, 22
	v_readlane_b32 s98, v27, 23
	v_readlane_b32 s99, v27, 24
	v_fma_f32 v63, -v52, s2, v63
	v_fma_f32 v62, -v53, s3, v62
	v_fma_f32 v63, -v50, s98, v63
	v_fma_f32 v62, -v51, s99, v62
	v_readlane_b32 s2, v27, 25
	v_readlane_b32 s3, v27, 26
	v_readlane_b32 s98, v27, 27
	v_readlane_b32 s99, v27, 28
	v_fma_f32 v63, -v48, s2, v63
	v_fma_f32 v62, -v49, s3, v62
	v_fma_f32 v63, -v46, s98, v63
	v_fma_f32 v62, -v47, s99, v62
	v_readlane_b32 s2, v27, 29
	v_readlane_b32 s3, v27, 30
	v_readlane_b32 s98, v27, 31
	v_readlane_b32 s99, v27, 32
	v_fma_f32 v63, -v44, s2, v63
	v_fma_f32 v62, -v45, s3, v62
	v_fma_f32 v63, -v42, s98, v63
	v_fma_f32 v62, -v43, s99, v62
	v_readlane_b32 s2, v27, 33
	v_readlane_b32 s3, v27, 34
	v_readlane_b32 s98, v27, 35
	v_readlane_b32 s99, v27, 36
	v_fma_f32 v63, -v40, s2, v63
	v_fma_f32 v62, -v41, s3, v62
	v_fma_f32 v63, -v38, s98, v63
	v_fma_f32 v62, -v39, s99, v62
	v_readlane_b32 s2, v27, 37
	v_readlane_b32 s3, v27, 38
	v_readlane_b32 s98, v27, 39
	v_readlane_b32 s99, v27, 40
	v_fma_f32 v63, -v36, s2, v63
	v_fma_f32 v62, -v37, s3, v62
	v_fma_f32 v63, -v34, s98, v63
	v_fma_f32 v62, -v35, s99, v62
	v_readlane_b32 s2, v27, 41
	v_readlane_b32 s3, v27, 42
	v_readlane_b32 s98, v27, 43
	v_readlane_b32 s99, v27, 44
	v_fma_f32 v63, -v32, s2, v63
	v_fma_f32 v62, -v33, s3, v62
	v_fma_f32 v63, -v30, s98, v63
	v_fma_f32 v62, -v31, s99, v62
	v_readlane_b32 s2, v27, 45
	v_readlane_b32 s3, v27, 46
	v_readlane_b32 s98, v27, 47
	v_fma_f32 v63, -v28, s2, v63
	v_fma_f32 v62, -v29, s3, v62
	v_fma_f32 v27, -v26, s98, v63
	v_readlane_b32 s2, v24, 0
	v_add_f32_e32 v27, v62, v27
	s_nop 0
	v_fma_f32 v62, -v81, s2, v96
	v_readlane_b32 s2, v24, 1
	v_readlane_b32 s3, v24, 2
	v_readlane_b32 s98, v24, 3
	v_readlane_b32 s99, v24, 4
	v_fma_f32 v63, -v0, s2, 0
	v_fma_f32 v62, -v1, s3, v62
	v_fma_f32 v63, -v2, s98, v63
	v_fma_f32 v62, -v3, s99, v62
	v_readlane_b32 s2, v24, 5
	v_readlane_b32 s3, v24, 6
	v_readlane_b32 s98, v24, 7
	v_readlane_b32 s99, v24, 8
	v_fma_f32 v63, -v4, s2, v63
	v_fma_f32 v62, -v5, s3, v62
	v_fma_f32 v63, -v7, s98, v63
	v_fma_f32 v62, -v6, s99, v62
	v_readlane_b32 s2, v24, 9
	v_readlane_b32 s3, v24, 10
	v_readlane_b32 s98, v24, 11
	v_readlane_b32 s99, v24, 12
	v_fma_f32 v63, -v8, s2, v63
	v_fma_f32 v62, -v9, s3, v62
	v_fma_f32 v63, -v10, s98, v63
	v_fma_f32 v62, -v11, s99, v62
	v_readlane_b32 s2, v24, 13
	v_readlane_b32 s3, v24, 14
	v_readlane_b32 s98, v24, 15
	v_readlane_b32 s99, v24, 16
	v_fma_f32 v63, -v60, s2, v63
	v_fma_f32 v62, -v61, s3, v62
	v_fma_f32 v63, -v58, s98, v63
	v_fma_f32 v62, -v59, s99, v62
	v_readlane_b32 s2, v24, 17
	v_readlane_b32 s3, v24, 18
	v_readlane_b32 s98, v24, 19
	v_readlane_b32 s99, v24, 20
	v_fma_f32 v63, -v56, s2, v63
	v_fma_f32 v62, -v57, s3, v62
	v_fma_f32 v63, -v54, s98, v63
	v_fma_f32 v62, -v55, s99, v62
	v_readlane_b32 s2, v24, 21
	v_readlane_b32 s3, v24, 22
	v_readlane_b32 s98, v24, 23
	v_readlane_b32 s99, v24, 24
	v_fma_f32 v63, -v52, s2, v63
	v_fma_f32 v62, -v53, s3, v62
	v_fma_f32 v63, -v50, s98, v63
	v_fma_f32 v62, -v51, s99, v62
	v_readlane_b32 s2, v24, 25
	v_readlane_b32 s3, v24, 26
	v_readlane_b32 s98, v24, 27
	v_readlane_b32 s99, v24, 28
	v_fma_f32 v63, -v48, s2, v63
	v_fma_f32 v62, -v49, s3, v62
	v_fma_f32 v63, -v46, s98, v63
	v_fma_f32 v62, -v47, s99, v62
	v_readlane_b32 s2, v24, 29
	v_readlane_b32 s3, v24, 30
	v_readlane_b32 s98, v24, 31
	v_readlane_b32 s99, v24, 32
	v_fma_f32 v63, -v44, s2, v63
	v_fma_f32 v62, -v45, s3, v62
	v_fma_f32 v63, -v42, s98, v63
	v_fma_f32 v62, -v43, s99, v62
	v_readlane_b32 s2, v24, 33
	v_readlane_b32 s3, v24, 34
	v_readlane_b32 s98, v24, 35
	v_readlane_b32 s99, v24, 36
	v_fma_f32 v63, -v40, s2, v63
	v_fma_f32 v62, -v41, s3, v62
	v_fma_f32 v63, -v38, s98, v63
	v_fma_f32 v62, -v39, s99, v62
	v_readlane_b32 s2, v24, 37
	v_readlane_b32 s3, v24, 38
	v_readlane_b32 s98, v24, 39
	v_readlane_b32 s99, v24, 40
	v_fma_f32 v63, -v36, s2, v63
	v_fma_f32 v62, -v37, s3, v62
	v_fma_f32 v63, -v34, s98, v63
	v_fma_f32 v62, -v35, s99, v62
	v_readlane_b32 s2, v24, 41
	v_readlane_b32 s3, v24, 42
	v_readlane_b32 s98, v24, 43
	v_readlane_b32 s99, v24, 44
	v_fma_f32 v63, -v32, s2, v63
	v_fma_f32 v62, -v33, s3, v62
	v_fma_f32 v63, -v30, s98, v63
	v_fma_f32 v62, -v31, s99, v62
	v_readlane_b32 s2, v24, 45
	v_readlane_b32 s3, v24, 46
	v_readlane_b32 s98, v24, 47
	v_readlane_b32 s99, v24, 48
	v_fma_f32 v63, -v28, s2, v63
	v_fma_f32 v62, -v29, s3, v62
	v_fma_f32 v63, -v26, s98, v63
	v_fma_f32 v24, -v27, s99, v62
	v_readlane_b32 s2, v25, 0
	v_add_f32_e32 v24, v63, v24
	s_nop 0
	v_fma_f32 v62, -v81, s2, v95
	v_readlane_b32 s2, v25, 1
	v_readlane_b32 s3, v25, 2
	v_readlane_b32 s98, v25, 3
	v_readlane_b32 s99, v25, 4
	v_fma_f32 v63, -v0, s2, 0
	v_fma_f32 v62, -v1, s3, v62
	v_fma_f32 v63, -v2, s98, v63
	v_fma_f32 v62, -v3, s99, v62
	v_readlane_b32 s2, v25, 5
	v_readlane_b32 s3, v25, 6
	v_readlane_b32 s98, v25, 7
	v_readlane_b32 s99, v25, 8
	v_fma_f32 v63, -v4, s2, v63
	v_fma_f32 v62, -v5, s3, v62
	v_fma_f32 v63, -v7, s98, v63
	v_fma_f32 v62, -v6, s99, v62
	v_readlane_b32 s2, v25, 9
	v_readlane_b32 s3, v25, 10
	v_readlane_b32 s98, v25, 11
	v_readlane_b32 s99, v25, 12
	v_fma_f32 v63, -v8, s2, v63
	v_fma_f32 v62, -v9, s3, v62
	v_fma_f32 v63, -v10, s98, v63
	v_fma_f32 v62, -v11, s99, v62
	v_readlane_b32 s2, v25, 13
	v_readlane_b32 s3, v25, 14
	v_readlane_b32 s98, v25, 15
	v_readlane_b32 s99, v25, 16
	v_fma_f32 v63, -v60, s2, v63
	v_fma_f32 v62, -v61, s3, v62
	v_fma_f32 v63, -v58, s98, v63
	v_fma_f32 v62, -v59, s99, v62
	v_readlane_b32 s2, v25, 17
	v_readlane_b32 s3, v25, 18
	v_readlane_b32 s98, v25, 19
	v_readlane_b32 s99, v25, 20
	v_fma_f32 v63, -v56, s2, v63
	v_fma_f32 v62, -v57, s3, v62
	v_fma_f32 v63, -v54, s98, v63
	v_fma_f32 v62, -v55, s99, v62
	v_readlane_b32 s2, v25, 21
	v_readlane_b32 s3, v25, 22
	v_readlane_b32 s98, v25, 23
	v_readlane_b32 s99, v25, 24
	v_fma_f32 v63, -v52, s2, v63
	v_fma_f32 v62, -v53, s3, v62
	v_fma_f32 v63, -v50, s98, v63
	v_fma_f32 v62, -v51, s99, v62
	v_readlane_b32 s2, v25, 25
	v_readlane_b32 s3, v25, 26
	v_readlane_b32 s98, v25, 27
	v_readlane_b32 s99, v25, 28
	v_fma_f32 v63, -v48, s2, v63
	v_fma_f32 v62, -v49, s3, v62
	v_fma_f32 v63, -v46, s98, v63
	v_fma_f32 v62, -v47, s99, v62
	v_readlane_b32 s2, v25, 29
	v_readlane_b32 s3, v25, 30
	v_readlane_b32 s98, v25, 31
	v_readlane_b32 s99, v25, 32
	v_fma_f32 v63, -v44, s2, v63
	v_fma_f32 v62, -v45, s3, v62
	v_fma_f32 v63, -v42, s98, v63
	v_fma_f32 v62, -v43, s99, v62
	v_readlane_b32 s2, v25, 33
	v_readlane_b32 s3, v25, 34
	v_readlane_b32 s98, v25, 35
	v_readlane_b32 s99, v25, 36
	v_fma_f32 v63, -v40, s2, v63
	v_fma_f32 v62, -v41, s3, v62
	v_fma_f32 v63, -v38, s98, v63
	v_fma_f32 v62, -v39, s99, v62
	v_readlane_b32 s2, v25, 37
	v_readlane_b32 s3, v25, 38
	v_readlane_b32 s98, v25, 39
	v_readlane_b32 s99, v25, 40
	v_fma_f32 v63, -v36, s2, v63
	v_fma_f32 v62, -v37, s3, v62
	v_fma_f32 v63, -v34, s98, v63
	v_fma_f32 v62, -v35, s99, v62
	v_readlane_b32 s2, v25, 41
	v_readlane_b32 s3, v25, 42
	v_readlane_b32 s98, v25, 43
	v_readlane_b32 s99, v25, 44
	v_fma_f32 v63, -v32, s2, v63
	v_fma_f32 v62, -v33, s3, v62
	v_fma_f32 v63, -v30, s98, v63
	v_fma_f32 v62, -v31, s99, v62
	v_readlane_b32 s2, v25, 45
	v_readlane_b32 s3, v25, 46
	v_readlane_b32 s98, v25, 47
	v_readlane_b32 s99, v25, 48
	v_fma_f32 v63, -v28, s2, v63
	v_fma_f32 v62, -v29, s3, v62
	v_fma_f32 v63, -v26, s98, v63
	v_fma_f32 v62, -v27, s99, v62
	v_readlane_b32 s2, v25, 49
	s_nop 1
	v_fma_f32 v25, -v24, s2, v63
	v_readlane_b32 s2, v22, 0
	v_add_f32_e32 v25, v62, v25
	s_nop 0
	v_fma_f32 v62, -v81, s2, v93
	v_readlane_b32 s2, v22, 1
	v_readlane_b32 s3, v22, 2
	v_readlane_b32 s98, v22, 3
	v_readlane_b32 s99, v22, 4
	v_fma_f32 v63, -v0, s2, 0
	v_fma_f32 v62, -v1, s3, v62
	v_fma_f32 v63, -v2, s98, v63
	v_fma_f32 v62, -v3, s99, v62
	v_readlane_b32 s2, v22, 5
	v_readlane_b32 s3, v22, 6
	v_readlane_b32 s98, v22, 7
	v_readlane_b32 s99, v22, 8
	v_fma_f32 v63, -v4, s2, v63
	v_fma_f32 v62, -v5, s3, v62
	v_fma_f32 v63, -v7, s98, v63
	v_fma_f32 v62, -v6, s99, v62
	v_readlane_b32 s2, v22, 9
	v_readlane_b32 s3, v22, 10
	v_readlane_b32 s98, v22, 11
	v_readlane_b32 s99, v22, 12
	v_fma_f32 v63, -v8, s2, v63
	v_fma_f32 v62, -v9, s3, v62
	v_fma_f32 v63, -v10, s98, v63
	v_fma_f32 v62, -v11, s99, v62
	v_readlane_b32 s2, v22, 13
	v_readlane_b32 s3, v22, 14
	v_readlane_b32 s98, v22, 15
	v_readlane_b32 s99, v22, 16
	v_fma_f32 v63, -v60, s2, v63
	v_fma_f32 v62, -v61, s3, v62
	v_fma_f32 v63, -v58, s98, v63
	v_fma_f32 v62, -v59, s99, v62
	v_readlane_b32 s2, v22, 17
	v_readlane_b32 s3, v22, 18
	v_readlane_b32 s98, v22, 19
	v_readlane_b32 s99, v22, 20
	v_fma_f32 v63, -v56, s2, v63
	v_fma_f32 v62, -v57, s3, v62
	v_fma_f32 v63, -v54, s98, v63
	v_fma_f32 v62, -v55, s99, v62
	v_readlane_b32 s2, v22, 21
	v_readlane_b32 s3, v22, 22
	v_readlane_b32 s98, v22, 23
	v_readlane_b32 s99, v22, 24
	v_fma_f32 v63, -v52, s2, v63
	v_fma_f32 v62, -v53, s3, v62
	v_fma_f32 v63, -v50, s98, v63
	v_fma_f32 v62, -v51, s99, v62
	v_readlane_b32 s2, v22, 25
	v_readlane_b32 s3, v22, 26
	v_readlane_b32 s98, v22, 27
	v_readlane_b32 s99, v22, 28
	v_fma_f32 v63, -v48, s2, v63
	v_fma_f32 v62, -v49, s3, v62
	v_fma_f32 v63, -v46, s98, v63
	v_fma_f32 v62, -v47, s99, v62
	v_readlane_b32 s2, v22, 29
	v_readlane_b32 s3, v22, 30
	v_readlane_b32 s98, v22, 31
	v_readlane_b32 s99, v22, 32
	v_fma_f32 v63, -v44, s2, v63
	v_fma_f32 v62, -v45, s3, v62
	v_fma_f32 v63, -v42, s98, v63
	v_fma_f32 v62, -v43, s99, v62
	v_readlane_b32 s2, v22, 33
	v_readlane_b32 s3, v22, 34
	v_readlane_b32 s98, v22, 35
	v_readlane_b32 s99, v22, 36
	v_fma_f32 v63, -v40, s2, v63
	v_fma_f32 v62, -v41, s3, v62
	v_fma_f32 v63, -v38, s98, v63
	v_fma_f32 v62, -v39, s99, v62
	v_readlane_b32 s2, v22, 37
	v_readlane_b32 s3, v22, 38
	v_readlane_b32 s98, v22, 39
	v_readlane_b32 s99, v22, 40
	v_fma_f32 v63, -v36, s2, v63
	v_fma_f32 v62, -v37, s3, v62
	v_fma_f32 v63, -v34, s98, v63
	v_fma_f32 v62, -v35, s99, v62
	v_readlane_b32 s2, v22, 41
	v_readlane_b32 s3, v22, 42
	v_readlane_b32 s98, v22, 43
	v_readlane_b32 s99, v22, 44
	v_fma_f32 v63, -v32, s2, v63
	v_fma_f32 v62, -v33, s3, v62
	v_fma_f32 v63, -v30, s98, v63
	v_fma_f32 v62, -v31, s99, v62
	v_readlane_b32 s2, v22, 45
	v_readlane_b32 s3, v22, 46
	v_readlane_b32 s98, v22, 47
	v_readlane_b32 s99, v22, 48
	v_fma_f32 v63, -v28, s2, v63
	v_fma_f32 v62, -v29, s3, v62
	v_fma_f32 v63, -v26, s98, v63
	v_fma_f32 v62, -v27, s99, v62
	v_readlane_b32 s2, v22, 49
	v_readlane_b32 s3, v22, 50
	s_nop 0
	v_fma_f32 v63, -v24, s2, v63
	v_fma_f32 v22, -v25, s3, v62
	v_readlane_b32 s2, v23, 0
	v_add_f32_e32 v22, v63, v22
	s_nop 0
	v_fma_f32 v62, -v81, s2, v94
	v_readlane_b32 s2, v23, 1
	v_readlane_b32 s3, v23, 2
	v_readlane_b32 s98, v23, 3
	v_readlane_b32 s99, v23, 4
	v_fma_f32 v63, -v0, s2, 0
	v_fma_f32 v62, -v1, s3, v62
	v_fma_f32 v63, -v2, s98, v63
	v_fma_f32 v62, -v3, s99, v62
	v_readlane_b32 s2, v23, 5
	v_readlane_b32 s3, v23, 6
	v_readlane_b32 s98, v23, 7
	v_readlane_b32 s99, v23, 8
	v_fma_f32 v63, -v4, s2, v63
	v_fma_f32 v62, -v5, s3, v62
	v_fma_f32 v63, -v7, s98, v63
	v_fma_f32 v62, -v6, s99, v62
	v_readlane_b32 s2, v23, 9
	v_readlane_b32 s3, v23, 10
	v_readlane_b32 s98, v23, 11
	v_readlane_b32 s99, v23, 12
	v_fma_f32 v63, -v8, s2, v63
	v_fma_f32 v62, -v9, s3, v62
	v_fma_f32 v63, -v10, s98, v63
	v_fma_f32 v62, -v11, s99, v62
	v_readlane_b32 s2, v23, 13
	v_readlane_b32 s3, v23, 14
	v_readlane_b32 s98, v23, 15
	v_readlane_b32 s99, v23, 16
	v_fma_f32 v63, -v60, s2, v63
	v_fma_f32 v62, -v61, s3, v62
	v_fma_f32 v63, -v58, s98, v63
	v_fma_f32 v62, -v59, s99, v62
	v_readlane_b32 s2, v23, 17
	v_readlane_b32 s3, v23, 18
	v_readlane_b32 s98, v23, 19
	v_readlane_b32 s99, v23, 20
	v_fma_f32 v63, -v56, s2, v63
	v_fma_f32 v62, -v57, s3, v62
	v_fma_f32 v63, -v54, s98, v63
	v_fma_f32 v62, -v55, s99, v62
	v_readlane_b32 s2, v23, 21
	v_readlane_b32 s3, v23, 22
	v_readlane_b32 s98, v23, 23
	v_readlane_b32 s99, v23, 24
	v_fma_f32 v63, -v52, s2, v63
	v_fma_f32 v62, -v53, s3, v62
	v_fma_f32 v63, -v50, s98, v63
	v_fma_f32 v62, -v51, s99, v62
	v_readlane_b32 s2, v23, 25
	v_readlane_b32 s3, v23, 26
	v_readlane_b32 s98, v23, 27
	v_readlane_b32 s99, v23, 28
	v_fma_f32 v63, -v48, s2, v63
	v_fma_f32 v62, -v49, s3, v62
	v_fma_f32 v63, -v46, s98, v63
	v_fma_f32 v62, -v47, s99, v62
	v_readlane_b32 s2, v23, 29
	v_readlane_b32 s3, v23, 30
	v_readlane_b32 s98, v23, 31
	v_readlane_b32 s99, v23, 32
	v_fma_f32 v63, -v44, s2, v63
	v_fma_f32 v62, -v45, s3, v62
	v_fma_f32 v63, -v42, s98, v63
	v_fma_f32 v62, -v43, s99, v62
	v_readlane_b32 s2, v23, 33
	v_readlane_b32 s3, v23, 34
	v_readlane_b32 s98, v23, 35
	v_readlane_b32 s99, v23, 36
	v_fma_f32 v63, -v40, s2, v63
	v_fma_f32 v62, -v41, s3, v62
	v_fma_f32 v63, -v38, s98, v63
	v_fma_f32 v62, -v39, s99, v62
	v_readlane_b32 s2, v23, 37
	v_readlane_b32 s3, v23, 38
	v_readlane_b32 s98, v23, 39
	v_readlane_b32 s99, v23, 40
	v_fma_f32 v63, -v36, s2, v63
	v_fma_f32 v62, -v37, s3, v62
	v_fma_f32 v63, -v34, s98, v63
	v_fma_f32 v62, -v35, s99, v62
	v_readlane_b32 s2, v23, 41
	v_readlane_b32 s3, v23, 42
	v_readlane_b32 s98, v23, 43
	v_readlane_b32 s99, v23, 44
	v_fma_f32 v63, -v32, s2, v63
	v_fma_f32 v62, -v33, s3, v62
	v_fma_f32 v63, -v30, s98, v63
	v_fma_f32 v62, -v31, s99, v62
	v_readlane_b32 s2, v23, 45
	v_readlane_b32 s3, v23, 46
	v_readlane_b32 s98, v23, 47
	v_readlane_b32 s99, v23, 48
	v_fma_f32 v63, -v28, s2, v63
	v_fma_f32 v62, -v29, s3, v62
	v_fma_f32 v63, -v26, s98, v63
	v_fma_f32 v62, -v27, s99, v62
	v_readlane_b32 s2, v23, 49
	v_readlane_b32 s3, v23, 50
	v_readlane_b32 s98, v23, 51
	v_fma_f32 v63, -v24, s2, v63
	v_fma_f32 v62, -v25, s3, v62
	v_fma_f32 v23, -v22, s98, v63
	v_readlane_b32 s2, v20, 0
	v_add_f32_e32 v23, v62, v23
	s_nop 0
	v_fma_f32 v62, -v81, s2, v92
	v_readlane_b32 s2, v20, 1
	v_readlane_b32 s3, v20, 2
	v_readlane_b32 s98, v20, 3
	v_readlane_b32 s99, v20, 4
	v_fma_f32 v63, -v0, s2, 0
	v_fma_f32 v62, -v1, s3, v62
	v_fma_f32 v63, -v2, s98, v63
	v_fma_f32 v62, -v3, s99, v62
	v_readlane_b32 s2, v20, 5
	v_readlane_b32 s3, v20, 6
	v_readlane_b32 s98, v20, 7
	v_readlane_b32 s99, v20, 8
	v_fma_f32 v63, -v4, s2, v63
	v_fma_f32 v62, -v5, s3, v62
	v_fma_f32 v63, -v7, s98, v63
	v_fma_f32 v62, -v6, s99, v62
	v_readlane_b32 s2, v20, 9
	v_readlane_b32 s3, v20, 10
	v_readlane_b32 s98, v20, 11
	v_readlane_b32 s99, v20, 12
	v_fma_f32 v63, -v8, s2, v63
	v_fma_f32 v62, -v9, s3, v62
	v_fma_f32 v63, -v10, s98, v63
	v_fma_f32 v62, -v11, s99, v62
	v_readlane_b32 s2, v20, 13
	v_readlane_b32 s3, v20, 14
	v_readlane_b32 s98, v20, 15
	v_readlane_b32 s99, v20, 16
	v_fma_f32 v63, -v60, s2, v63
	v_fma_f32 v62, -v61, s3, v62
	v_fma_f32 v63, -v58, s98, v63
	v_fma_f32 v62, -v59, s99, v62
	v_readlane_b32 s2, v20, 17
	v_readlane_b32 s3, v20, 18
	v_readlane_b32 s98, v20, 19
	v_readlane_b32 s99, v20, 20
	v_fma_f32 v63, -v56, s2, v63
	v_fma_f32 v62, -v57, s3, v62
	v_fma_f32 v63, -v54, s98, v63
	v_fma_f32 v62, -v55, s99, v62
	v_readlane_b32 s2, v20, 21
	v_readlane_b32 s3, v20, 22
	v_readlane_b32 s98, v20, 23
	v_readlane_b32 s99, v20, 24
	v_fma_f32 v63, -v52, s2, v63
	v_fma_f32 v62, -v53, s3, v62
	v_fma_f32 v63, -v50, s98, v63
	v_fma_f32 v62, -v51, s99, v62
	v_readlane_b32 s2, v20, 25
	v_readlane_b32 s3, v20, 26
	v_readlane_b32 s98, v20, 27
	v_readlane_b32 s99, v20, 28
	v_fma_f32 v63, -v48, s2, v63
	v_fma_f32 v62, -v49, s3, v62
	v_fma_f32 v63, -v46, s98, v63
	v_fma_f32 v62, -v47, s99, v62
	v_readlane_b32 s2, v20, 29
	v_readlane_b32 s3, v20, 30
	v_readlane_b32 s98, v20, 31
	v_readlane_b32 s99, v20, 32
	v_fma_f32 v63, -v44, s2, v63
	v_fma_f32 v62, -v45, s3, v62
	v_fma_f32 v63, -v42, s98, v63
	v_fma_f32 v62, -v43, s99, v62
	v_readlane_b32 s2, v20, 33
	v_readlane_b32 s3, v20, 34
	v_readlane_b32 s98, v20, 35
	v_readlane_b32 s99, v20, 36
	v_fma_f32 v63, -v40, s2, v63
	v_fma_f32 v62, -v41, s3, v62
	v_fma_f32 v63, -v38, s98, v63
	v_fma_f32 v62, -v39, s99, v62
	v_readlane_b32 s2, v20, 37
	v_readlane_b32 s3, v20, 38
	v_readlane_b32 s98, v20, 39
	v_readlane_b32 s99, v20, 40
	v_fma_f32 v63, -v36, s2, v63
	v_fma_f32 v62, -v37, s3, v62
	v_fma_f32 v63, -v34, s98, v63
	v_fma_f32 v62, -v35, s99, v62
	v_readlane_b32 s2, v20, 41
	v_readlane_b32 s3, v20, 42
	v_readlane_b32 s98, v20, 43
	v_readlane_b32 s99, v20, 44
	v_fma_f32 v63, -v32, s2, v63
	v_fma_f32 v62, -v33, s3, v62
	v_fma_f32 v63, -v30, s98, v63
	v_fma_f32 v62, -v31, s99, v62
	v_readlane_b32 s2, v20, 45
	v_readlane_b32 s3, v20, 46
	v_readlane_b32 s98, v20, 47
	v_readlane_b32 s99, v20, 48
	v_fma_f32 v63, -v28, s2, v63
	v_fma_f32 v62, -v29, s3, v62
	v_fma_f32 v63, -v26, s98, v63
	v_fma_f32 v62, -v27, s99, v62
	v_readlane_b32 s2, v20, 49
	v_readlane_b32 s3, v20, 50
	v_readlane_b32 s98, v20, 51
	v_readlane_b32 s99, v20, 52
	v_fma_f32 v63, -v24, s2, v63
	v_fma_f32 v62, -v25, s3, v62
	v_fma_f32 v63, -v22, s98, v63
	v_fma_f32 v20, -v23, s99, v62
	v_readlane_b32 s2, v21, 0
	v_add_f32_e32 v20, v63, v20
	s_nop 0
	v_fma_f32 v62, -v81, s2, v90
	v_readlane_b32 s2, v21, 1
	v_readlane_b32 s3, v21, 2
	v_readlane_b32 s98, v21, 3
	v_readlane_b32 s99, v21, 4
	v_fma_f32 v63, -v0, s2, 0
	v_fma_f32 v62, -v1, s3, v62
	v_fma_f32 v63, -v2, s98, v63
	v_fma_f32 v62, -v3, s99, v62
	v_readlane_b32 s2, v21, 5
	v_readlane_b32 s3, v21, 6
	v_readlane_b32 s98, v21, 7
	v_readlane_b32 s99, v21, 8
	v_fma_f32 v63, -v4, s2, v63
	v_fma_f32 v62, -v5, s3, v62
	v_fma_f32 v63, -v7, s98, v63
	v_fma_f32 v62, -v6, s99, v62
	v_readlane_b32 s2, v21, 9
	v_readlane_b32 s3, v21, 10
	v_readlane_b32 s98, v21, 11
	v_readlane_b32 s99, v21, 12
	v_fma_f32 v63, -v8, s2, v63
	v_fma_f32 v62, -v9, s3, v62
	v_fma_f32 v63, -v10, s98, v63
	v_fma_f32 v62, -v11, s99, v62
	v_readlane_b32 s2, v21, 13
	v_readlane_b32 s3, v21, 14
	v_readlane_b32 s98, v21, 15
	v_readlane_b32 s99, v21, 16
	v_fma_f32 v63, -v60, s2, v63
	v_fma_f32 v62, -v61, s3, v62
	v_fma_f32 v63, -v58, s98, v63
	v_fma_f32 v62, -v59, s99, v62
	v_readlane_b32 s2, v21, 17
	v_readlane_b32 s3, v21, 18
	v_readlane_b32 s98, v21, 19
	v_readlane_b32 s99, v21, 20
	v_fma_f32 v63, -v56, s2, v63
	v_fma_f32 v62, -v57, s3, v62
	v_fma_f32 v63, -v54, s98, v63
	v_fma_f32 v62, -v55, s99, v62
	v_readlane_b32 s2, v21, 21
	v_readlane_b32 s3, v21, 22
	v_readlane_b32 s98, v21, 23
	v_readlane_b32 s99, v21, 24
	v_fma_f32 v63, -v52, s2, v63
	v_fma_f32 v62, -v53, s3, v62
	v_fma_f32 v63, -v50, s98, v63
	v_fma_f32 v62, -v51, s99, v62
	v_readlane_b32 s2, v21, 25
	v_readlane_b32 s3, v21, 26
	v_readlane_b32 s98, v21, 27
	v_readlane_b32 s99, v21, 28
	v_fma_f32 v63, -v48, s2, v63
	v_fma_f32 v62, -v49, s3, v62
	v_fma_f32 v63, -v46, s98, v63
	v_fma_f32 v62, -v47, s99, v62
	v_readlane_b32 s2, v21, 29
	v_readlane_b32 s3, v21, 30
	v_readlane_b32 s98, v21, 31
	v_readlane_b32 s99, v21, 32
	v_fma_f32 v63, -v44, s2, v63
	v_fma_f32 v62, -v45, s3, v62
	v_fma_f32 v63, -v42, s98, v63
	v_fma_f32 v62, -v43, s99, v62
	v_readlane_b32 s2, v21, 33
	v_readlane_b32 s3, v21, 34
	v_readlane_b32 s98, v21, 35
	v_readlane_b32 s99, v21, 36
	v_fma_f32 v63, -v40, s2, v63
	v_fma_f32 v62, -v41, s3, v62
	v_fma_f32 v63, -v38, s98, v63
	v_fma_f32 v62, -v39, s99, v62
	v_readlane_b32 s2, v21, 37
	v_readlane_b32 s3, v21, 38
	v_readlane_b32 s98, v21, 39
	v_readlane_b32 s99, v21, 40
	v_fma_f32 v63, -v36, s2, v63
	v_fma_f32 v62, -v37, s3, v62
	v_fma_f32 v63, -v34, s98, v63
	v_fma_f32 v62, -v35, s99, v62
	v_readlane_b32 s2, v21, 41
	v_readlane_b32 s3, v21, 42
	v_readlane_b32 s98, v21, 43
	v_readlane_b32 s99, v21, 44
	v_fma_f32 v63, -v32, s2, v63
	v_fma_f32 v62, -v33, s3, v62
	v_fma_f32 v63, -v30, s98, v63
	v_fma_f32 v62, -v31, s99, v62
	v_readlane_b32 s2, v21, 45
	v_readlane_b32 s3, v21, 46
	v_readlane_b32 s98, v21, 47
	v_readlane_b32 s99, v21, 48
	v_fma_f32 v63, -v28, s2, v63
	v_fma_f32 v62, -v29, s3, v62
	v_fma_f32 v63, -v26, s98, v63
	v_fma_f32 v62, -v27, s99, v62
	v_readlane_b32 s2, v21, 49
	v_readlane_b32 s3, v21, 50
	v_readlane_b32 s98, v21, 51
	v_readlane_b32 s99, v21, 52
	v_fma_f32 v63, -v24, s2, v63
	v_fma_f32 v62, -v25, s3, v62
	v_fma_f32 v63, -v22, s98, v63
	v_fma_f32 v62, -v23, s99, v62
	v_readlane_b32 s2, v21, 53
	s_nop 1
	v_fma_f32 v21, -v20, s2, v63
	v_readlane_b32 s2, v18, 0
	v_add_f32_e32 v21, v62, v21
	s_nop 0
	v_fma_f32 v62, -v81, s2, v91
	v_readlane_b32 s2, v18, 1
	v_readlane_b32 s3, v18, 2
	v_readlane_b32 s98, v18, 3
	v_readlane_b32 s99, v18, 4
	v_fma_f32 v63, -v0, s2, 0
	v_fma_f32 v62, -v1, s3, v62
	v_fma_f32 v63, -v2, s98, v63
	v_fma_f32 v62, -v3, s99, v62
	v_readlane_b32 s2, v18, 5
	v_readlane_b32 s3, v18, 6
	v_readlane_b32 s98, v18, 7
	v_readlane_b32 s99, v18, 8
	v_fma_f32 v63, -v4, s2, v63
	v_fma_f32 v62, -v5, s3, v62
	v_fma_f32 v63, -v7, s98, v63
	v_fma_f32 v62, -v6, s99, v62
	v_readlane_b32 s2, v18, 9
	v_readlane_b32 s3, v18, 10
	v_readlane_b32 s98, v18, 11
	v_readlane_b32 s99, v18, 12
	v_fma_f32 v63, -v8, s2, v63
	v_fma_f32 v62, -v9, s3, v62
	v_fma_f32 v63, -v10, s98, v63
	v_fma_f32 v62, -v11, s99, v62
	v_readlane_b32 s2, v18, 13
	v_readlane_b32 s3, v18, 14
	v_readlane_b32 s98, v18, 15
	v_readlane_b32 s99, v18, 16
	v_fma_f32 v63, -v60, s2, v63
	v_fma_f32 v62, -v61, s3, v62
	v_fma_f32 v63, -v58, s98, v63
	v_fma_f32 v62, -v59, s99, v62
	v_readlane_b32 s2, v18, 17
	v_readlane_b32 s3, v18, 18
	v_readlane_b32 s98, v18, 19
	v_readlane_b32 s99, v18, 20
	v_fma_f32 v63, -v56, s2, v63
	v_fma_f32 v62, -v57, s3, v62
	v_fma_f32 v63, -v54, s98, v63
	v_fma_f32 v62, -v55, s99, v62
	v_readlane_b32 s2, v18, 21
	v_readlane_b32 s3, v18, 22
	v_readlane_b32 s98, v18, 23
	v_readlane_b32 s99, v18, 24
	v_fma_f32 v63, -v52, s2, v63
	v_fma_f32 v62, -v53, s3, v62
	v_fma_f32 v63, -v50, s98, v63
	v_fma_f32 v62, -v51, s99, v62
	v_readlane_b32 s2, v18, 25
	v_readlane_b32 s3, v18, 26
	v_readlane_b32 s98, v18, 27
	v_readlane_b32 s99, v18, 28
	v_fma_f32 v63, -v48, s2, v63
	v_fma_f32 v62, -v49, s3, v62
	v_fma_f32 v63, -v46, s98, v63
	v_fma_f32 v62, -v47, s99, v62
	v_readlane_b32 s2, v18, 29
	v_readlane_b32 s3, v18, 30
	v_readlane_b32 s98, v18, 31
	v_readlane_b32 s99, v18, 32
	v_fma_f32 v63, -v44, s2, v63
	v_fma_f32 v62, -v45, s3, v62
	v_fma_f32 v63, -v42, s98, v63
	v_fma_f32 v62, -v43, s99, v62
	v_readlane_b32 s2, v18, 33
	v_readlane_b32 s3, v18, 34
	v_readlane_b32 s98, v18, 35
	v_readlane_b32 s99, v18, 36
	v_fma_f32 v63, -v40, s2, v63
	v_fma_f32 v62, -v41, s3, v62
	v_fma_f32 v63, -v38, s98, v63
	v_fma_f32 v62, -v39, s99, v62
	v_readlane_b32 s2, v18, 37
	v_readlane_b32 s3, v18, 38
	v_readlane_b32 s98, v18, 39
	v_readlane_b32 s99, v18, 40
	v_fma_f32 v63, -v36, s2, v63
	v_fma_f32 v62, -v37, s3, v62
	v_fma_f32 v63, -v34, s98, v63
	v_fma_f32 v62, -v35, s99, v62
	v_readlane_b32 s2, v18, 41
	v_readlane_b32 s3, v18, 42
	v_readlane_b32 s98, v18, 43
	v_readlane_b32 s99, v18, 44
	v_fma_f32 v63, -v32, s2, v63
	v_fma_f32 v62, -v33, s3, v62
	v_fma_f32 v63, -v30, s98, v63
	v_fma_f32 v62, -v31, s99, v62
	v_readlane_b32 s2, v18, 45
	v_readlane_b32 s3, v18, 46
	v_readlane_b32 s98, v18, 47
	v_readlane_b32 s99, v18, 48
	v_fma_f32 v63, -v28, s2, v63
	v_fma_f32 v62, -v29, s3, v62
	v_fma_f32 v63, -v26, s98, v63
	v_fma_f32 v62, -v27, s99, v62
	v_readlane_b32 s2, v18, 49
	v_readlane_b32 s3, v18, 50
	v_readlane_b32 s98, v18, 51
	v_readlane_b32 s99, v18, 52
	v_fma_f32 v63, -v24, s2, v63
	v_fma_f32 v62, -v25, s3, v62
	v_fma_f32 v63, -v22, s98, v63
	v_fma_f32 v62, -v23, s99, v62
	v_readlane_b32 s2, v18, 53
	v_readlane_b32 s3, v18, 54
	s_nop 0
	v_fma_f32 v63, -v20, s2, v63
	v_fma_f32 v18, -v21, s3, v62
	v_readlane_b32 s2, v19, 0
	v_add_f32_e32 v18, v63, v18
	s_nop 0
	v_fma_f32 v62, -v81, s2, v89
	v_readlane_b32 s2, v19, 1
	v_readlane_b32 s3, v19, 2
	v_readlane_b32 s98, v19, 3
	v_readlane_b32 s99, v19, 4
	v_fma_f32 v63, -v0, s2, 0
	v_fma_f32 v62, -v1, s3, v62
	v_fma_f32 v63, -v2, s98, v63
	v_fma_f32 v62, -v3, s99, v62
	v_readlane_b32 s2, v19, 5
	v_readlane_b32 s3, v19, 6
	v_readlane_b32 s98, v19, 7
	v_readlane_b32 s99, v19, 8
	v_fma_f32 v63, -v4, s2, v63
	v_fma_f32 v62, -v5, s3, v62
	v_fma_f32 v63, -v7, s98, v63
	v_fma_f32 v62, -v6, s99, v62
	v_readlane_b32 s2, v19, 9
	v_readlane_b32 s3, v19, 10
	v_readlane_b32 s98, v19, 11
	v_readlane_b32 s99, v19, 12
	v_fma_f32 v63, -v8, s2, v63
	v_fma_f32 v62, -v9, s3, v62
	v_fma_f32 v63, -v10, s98, v63
	v_fma_f32 v62, -v11, s99, v62
	v_readlane_b32 s2, v19, 13
	v_readlane_b32 s3, v19, 14
	v_readlane_b32 s98, v19, 15
	v_readlane_b32 s99, v19, 16
	v_fma_f32 v63, -v60, s2, v63
	v_fma_f32 v62, -v61, s3, v62
	v_fma_f32 v63, -v58, s98, v63
	v_fma_f32 v62, -v59, s99, v62
	v_readlane_b32 s2, v19, 17
	v_readlane_b32 s3, v19, 18
	v_readlane_b32 s98, v19, 19
	v_readlane_b32 s99, v19, 20
	v_fma_f32 v63, -v56, s2, v63
	v_fma_f32 v62, -v57, s3, v62
	v_fma_f32 v63, -v54, s98, v63
	v_fma_f32 v62, -v55, s99, v62
	v_readlane_b32 s2, v19, 21
	v_readlane_b32 s3, v19, 22
	v_readlane_b32 s98, v19, 23
	v_readlane_b32 s99, v19, 24
	v_fma_f32 v63, -v52, s2, v63
	v_fma_f32 v62, -v53, s3, v62
	v_fma_f32 v63, -v50, s98, v63
	v_fma_f32 v62, -v51, s99, v62
	v_readlane_b32 s2, v19, 25
	v_readlane_b32 s3, v19, 26
	v_readlane_b32 s98, v19, 27
	v_readlane_b32 s99, v19, 28
	v_fma_f32 v63, -v48, s2, v63
	v_fma_f32 v62, -v49, s3, v62
	v_fma_f32 v63, -v46, s98, v63
	v_fma_f32 v62, -v47, s99, v62
	v_readlane_b32 s2, v19, 29
	v_readlane_b32 s3, v19, 30
	v_readlane_b32 s98, v19, 31
	v_readlane_b32 s99, v19, 32
	v_fma_f32 v63, -v44, s2, v63
	v_fma_f32 v62, -v45, s3, v62
	v_fma_f32 v63, -v42, s98, v63
	v_fma_f32 v62, -v43, s99, v62
	v_readlane_b32 s2, v19, 33
	v_readlane_b32 s3, v19, 34
	v_readlane_b32 s98, v19, 35
	v_readlane_b32 s99, v19, 36
	v_fma_f32 v63, -v40, s2, v63
	v_fma_f32 v62, -v41, s3, v62
	v_fma_f32 v63, -v38, s98, v63
	v_fma_f32 v62, -v39, s99, v62
	v_readlane_b32 s2, v19, 37
	v_readlane_b32 s3, v19, 38
	v_readlane_b32 s98, v19, 39
	v_readlane_b32 s99, v19, 40
	v_fma_f32 v63, -v36, s2, v63
	v_fma_f32 v62, -v37, s3, v62
	v_fma_f32 v63, -v34, s98, v63
	v_fma_f32 v62, -v35, s99, v62
	v_readlane_b32 s2, v19, 41
	v_readlane_b32 s3, v19, 42
	v_readlane_b32 s98, v19, 43
	v_readlane_b32 s99, v19, 44
	v_fma_f32 v63, -v32, s2, v63
	v_fma_f32 v62, -v33, s3, v62
	v_fma_f32 v63, -v30, s98, v63
	v_fma_f32 v62, -v31, s99, v62
	v_readlane_b32 s2, v19, 45
	v_readlane_b32 s3, v19, 46
	v_readlane_b32 s98, v19, 47
	v_readlane_b32 s99, v19, 48
	v_fma_f32 v63, -v28, s2, v63
	v_fma_f32 v62, -v29, s3, v62
	v_fma_f32 v63, -v26, s98, v63
	v_fma_f32 v62, -v27, s99, v62
	v_readlane_b32 s2, v19, 49
	v_readlane_b32 s3, v19, 50
	v_readlane_b32 s98, v19, 51
	v_readlane_b32 s99, v19, 52
	v_fma_f32 v63, -v24, s2, v63
	v_fma_f32 v62, -v25, s3, v62
	v_fma_f32 v63, -v22, s98, v63
	v_fma_f32 v62, -v23, s99, v62
	v_readlane_b32 s2, v19, 53
	v_readlane_b32 s3, v19, 54
	v_readlane_b32 s98, v19, 55
	v_fma_f32 v63, -v20, s2, v63
	v_fma_f32 v62, -v21, s3, v62
	v_fma_f32 v19, -v18, s98, v63
	v_readlane_b32 s2, v16, 0
	v_add_f32_e32 v19, v62, v19
	s_nop 0
	v_fma_f32 v62, -v81, s2, v88
	v_readlane_b32 s2, v16, 1
	v_readlane_b32 s3, v16, 2
	v_readlane_b32 s98, v16, 3
	v_readlane_b32 s99, v16, 4
	v_fma_f32 v63, -v0, s2, 0
	v_fma_f32 v62, -v1, s3, v62
	v_fma_f32 v63, -v2, s98, v63
	v_fma_f32 v62, -v3, s99, v62
	v_readlane_b32 s2, v16, 5
	v_readlane_b32 s3, v16, 6
	v_readlane_b32 s98, v16, 7
	v_readlane_b32 s99, v16, 8
	v_fma_f32 v63, -v4, s2, v63
	v_fma_f32 v62, -v5, s3, v62
	v_fma_f32 v63, -v7, s98, v63
	v_fma_f32 v62, -v6, s99, v62
	v_readlane_b32 s2, v16, 9
	v_readlane_b32 s3, v16, 10
	v_readlane_b32 s98, v16, 11
	v_readlane_b32 s99, v16, 12
	v_fma_f32 v63, -v8, s2, v63
	v_fma_f32 v62, -v9, s3, v62
	v_fma_f32 v63, -v10, s98, v63
	v_fma_f32 v62, -v11, s99, v62
	v_readlane_b32 s2, v16, 13
	v_readlane_b32 s3, v16, 14
	v_readlane_b32 s98, v16, 15
	v_readlane_b32 s99, v16, 16
	v_fma_f32 v63, -v60, s2, v63
	v_fma_f32 v62, -v61, s3, v62
	v_fma_f32 v63, -v58, s98, v63
	v_fma_f32 v62, -v59, s99, v62
	v_readlane_b32 s2, v16, 17
	v_readlane_b32 s3, v16, 18
	v_readlane_b32 s98, v16, 19
	v_readlane_b32 s99, v16, 20
	v_fma_f32 v63, -v56, s2, v63
	v_fma_f32 v62, -v57, s3, v62
	v_fma_f32 v63, -v54, s98, v63
	v_fma_f32 v62, -v55, s99, v62
	v_readlane_b32 s2, v16, 21
	v_readlane_b32 s3, v16, 22
	v_readlane_b32 s98, v16, 23
	v_readlane_b32 s99, v16, 24
	v_fma_f32 v63, -v52, s2, v63
	v_fma_f32 v62, -v53, s3, v62
	v_fma_f32 v63, -v50, s98, v63
	v_fma_f32 v62, -v51, s99, v62
	v_readlane_b32 s2, v16, 25
	v_readlane_b32 s3, v16, 26
	v_readlane_b32 s98, v16, 27
	v_readlane_b32 s99, v16, 28
	v_fma_f32 v63, -v48, s2, v63
	v_fma_f32 v62, -v49, s3, v62
	v_fma_f32 v63, -v46, s98, v63
	v_fma_f32 v62, -v47, s99, v62
	v_readlane_b32 s2, v16, 29
	v_readlane_b32 s3, v16, 30
	v_readlane_b32 s98, v16, 31
	v_readlane_b32 s99, v16, 32
	v_fma_f32 v63, -v44, s2, v63
	v_fma_f32 v62, -v45, s3, v62
	v_fma_f32 v63, -v42, s98, v63
	v_fma_f32 v62, -v43, s99, v62
	v_readlane_b32 s2, v16, 33
	v_readlane_b32 s3, v16, 34
	v_readlane_b32 s98, v16, 35
	v_readlane_b32 s99, v16, 36
	v_fma_f32 v63, -v40, s2, v63
	v_fma_f32 v62, -v41, s3, v62
	v_fma_f32 v63, -v38, s98, v63
	v_fma_f32 v62, -v39, s99, v62
	v_readlane_b32 s2, v16, 37
	v_readlane_b32 s3, v16, 38
	v_readlane_b32 s98, v16, 39
	v_readlane_b32 s99, v16, 40
	v_fma_f32 v63, -v36, s2, v63
	v_fma_f32 v62, -v37, s3, v62
	v_fma_f32 v63, -v34, s98, v63
	v_fma_f32 v62, -v35, s99, v62
	v_readlane_b32 s2, v16, 41
	v_readlane_b32 s3, v16, 42
	v_readlane_b32 s98, v16, 43
	v_readlane_b32 s99, v16, 44
	v_fma_f32 v63, -v32, s2, v63
	v_fma_f32 v62, -v33, s3, v62
	v_fma_f32 v63, -v30, s98, v63
	v_fma_f32 v62, -v31, s99, v62
	v_readlane_b32 s2, v16, 45
	v_readlane_b32 s3, v16, 46
	v_readlane_b32 s98, v16, 47
	v_readlane_b32 s99, v16, 48
	v_fma_f32 v63, -v28, s2, v63
	v_fma_f32 v62, -v29, s3, v62
	v_fma_f32 v63, -v26, s98, v63
	v_fma_f32 v62, -v27, s99, v62
	v_readlane_b32 s2, v16, 49
	v_readlane_b32 s3, v16, 50
	v_readlane_b32 s98, v16, 51
	v_readlane_b32 s99, v16, 52
	v_fma_f32 v63, -v24, s2, v63
	v_fma_f32 v62, -v25, s3, v62
	v_fma_f32 v63, -v22, s98, v63
	v_fma_f32 v62, -v23, s99, v62
	v_readlane_b32 s2, v16, 53
	v_readlane_b32 s3, v16, 54
	v_readlane_b32 s98, v16, 55
	v_readlane_b32 s99, v16, 56
	v_fma_f32 v63, -v20, s2, v63
	v_fma_f32 v62, -v21, s3, v62
	v_fma_f32 v63, -v18, s98, v63
	v_fma_f32 v16, -v19, s99, v62
	v_readlane_b32 s2, v17, 0
	v_add_f32_e32 v16, v63, v16
	s_nop 0
	v_fma_f32 v62, -v81, s2, v87
	v_readlane_b32 s2, v17, 1
	v_readlane_b32 s3, v17, 2
	v_readlane_b32 s98, v17, 3
	v_readlane_b32 s99, v17, 4
	v_fma_f32 v63, -v0, s2, 0
	v_fma_f32 v62, -v1, s3, v62
	v_fma_f32 v63, -v2, s98, v63
	v_fma_f32 v62, -v3, s99, v62
	v_readlane_b32 s2, v17, 5
	v_readlane_b32 s3, v17, 6
	v_readlane_b32 s98, v17, 7
	v_readlane_b32 s99, v17, 8
	v_fma_f32 v63, -v4, s2, v63
	v_fma_f32 v62, -v5, s3, v62
	v_fma_f32 v63, -v7, s98, v63
	v_fma_f32 v62, -v6, s99, v62
	v_readlane_b32 s2, v17, 9
	v_readlane_b32 s3, v17, 10
	v_readlane_b32 s98, v17, 11
	v_readlane_b32 s99, v17, 12
	v_fma_f32 v63, -v8, s2, v63
	v_fma_f32 v62, -v9, s3, v62
	v_fma_f32 v63, -v10, s98, v63
	v_fma_f32 v62, -v11, s99, v62
	v_readlane_b32 s2, v17, 13
	v_readlane_b32 s3, v17, 14
	v_readlane_b32 s98, v17, 15
	v_readlane_b32 s99, v17, 16
	v_fma_f32 v63, -v60, s2, v63
	v_fma_f32 v62, -v61, s3, v62
	v_fma_f32 v63, -v58, s98, v63
	v_fma_f32 v62, -v59, s99, v62
	v_readlane_b32 s2, v17, 17
	v_readlane_b32 s3, v17, 18
	v_readlane_b32 s98, v17, 19
	v_readlane_b32 s99, v17, 20
	v_fma_f32 v63, -v56, s2, v63
	v_fma_f32 v62, -v57, s3, v62
	v_fma_f32 v63, -v54, s98, v63
	v_fma_f32 v62, -v55, s99, v62
	v_readlane_b32 s2, v17, 21
	v_readlane_b32 s3, v17, 22
	v_readlane_b32 s98, v17, 23
	v_readlane_b32 s99, v17, 24
	v_fma_f32 v63, -v52, s2, v63
	v_fma_f32 v62, -v53, s3, v62
	v_fma_f32 v63, -v50, s98, v63
	v_fma_f32 v62, -v51, s99, v62
	v_readlane_b32 s2, v17, 25
	v_readlane_b32 s3, v17, 26
	v_readlane_b32 s98, v17, 27
	v_readlane_b32 s99, v17, 28
	v_fma_f32 v63, -v48, s2, v63
	v_fma_f32 v62, -v49, s3, v62
	v_fma_f32 v63, -v46, s98, v63
	v_fma_f32 v62, -v47, s99, v62
	v_readlane_b32 s2, v17, 29
	v_readlane_b32 s3, v17, 30
	v_readlane_b32 s98, v17, 31
	v_readlane_b32 s99, v17, 32
	v_fma_f32 v63, -v44, s2, v63
	v_fma_f32 v62, -v45, s3, v62
	v_fma_f32 v63, -v42, s98, v63
	v_fma_f32 v62, -v43, s99, v62
	v_readlane_b32 s2, v17, 33
	v_readlane_b32 s3, v17, 34
	v_readlane_b32 s98, v17, 35
	v_readlane_b32 s99, v17, 36
	v_fma_f32 v63, -v40, s2, v63
	v_fma_f32 v62, -v41, s3, v62
	v_fma_f32 v63, -v38, s98, v63
	v_fma_f32 v62, -v39, s99, v62
	v_readlane_b32 s2, v17, 37
	v_readlane_b32 s3, v17, 38
	v_readlane_b32 s98, v17, 39
	v_readlane_b32 s99, v17, 40
	v_fma_f32 v63, -v36, s2, v63
	v_fma_f32 v62, -v37, s3, v62
	v_fma_f32 v63, -v34, s98, v63
	v_fma_f32 v62, -v35, s99, v62
	v_readlane_b32 s2, v17, 41
	v_readlane_b32 s3, v17, 42
	v_readlane_b32 s98, v17, 43
	v_readlane_b32 s99, v17, 44
	v_fma_f32 v63, -v32, s2, v63
	v_fma_f32 v62, -v33, s3, v62
	v_fma_f32 v63, -v30, s98, v63
	v_fma_f32 v62, -v31, s99, v62
	v_readlane_b32 s2, v17, 45
	v_readlane_b32 s3, v17, 46
	v_readlane_b32 s98, v17, 47
	v_readlane_b32 s99, v17, 48
	v_fma_f32 v63, -v28, s2, v63
	v_fma_f32 v62, -v29, s3, v62
	v_fma_f32 v63, -v26, s98, v63
	v_fma_f32 v62, -v27, s99, v62
	v_readlane_b32 s2, v17, 49
	v_readlane_b32 s3, v17, 50
	v_readlane_b32 s98, v17, 51
	v_readlane_b32 s99, v17, 52
	v_fma_f32 v63, -v24, s2, v63
	v_fma_f32 v62, -v25, s3, v62
	v_fma_f32 v63, -v22, s98, v63
	v_fma_f32 v62, -v23, s99, v62
	v_readlane_b32 s2, v17, 53
	v_readlane_b32 s3, v17, 54
	v_readlane_b32 s98, v17, 55
	v_readlane_b32 s99, v17, 56
	v_fma_f32 v63, -v20, s2, v63
	v_fma_f32 v62, -v21, s3, v62
	v_fma_f32 v63, -v18, s98, v63
	v_fma_f32 v62, -v19, s99, v62
	v_readlane_b32 s2, v17, 57
	s_nop 1
	v_fma_f32 v17, -v16, s2, v63
	v_readlane_b32 s2, v14, 0
	v_add_f32_e32 v17, v62, v17
	s_nop 0
	v_fma_f32 v62, -v81, s2, v86
	v_readlane_b32 s2, v14, 1
	v_readlane_b32 s3, v14, 2
	v_readlane_b32 s98, v14, 3
	v_readlane_b32 s99, v14, 4
	v_fma_f32 v63, -v0, s2, 0
	v_fma_f32 v62, -v1, s3, v62
	v_fma_f32 v63, -v2, s98, v63
	v_fma_f32 v62, -v3, s99, v62
	v_readlane_b32 s2, v14, 5
	v_readlane_b32 s3, v14, 6
	v_readlane_b32 s98, v14, 7
	v_readlane_b32 s99, v14, 8
	v_fma_f32 v63, -v4, s2, v63
	v_fma_f32 v62, -v5, s3, v62
	v_fma_f32 v63, -v7, s98, v63
	v_fma_f32 v62, -v6, s99, v62
	v_readlane_b32 s2, v14, 9
	v_readlane_b32 s3, v14, 10
	v_readlane_b32 s98, v14, 11
	v_readlane_b32 s99, v14, 12
	v_fma_f32 v63, -v8, s2, v63
	v_fma_f32 v62, -v9, s3, v62
	v_fma_f32 v63, -v10, s98, v63
	v_fma_f32 v62, -v11, s99, v62
	v_readlane_b32 s2, v14, 13
	v_readlane_b32 s3, v14, 14
	v_readlane_b32 s98, v14, 15
	v_readlane_b32 s99, v14, 16
	v_fma_f32 v63, -v60, s2, v63
	v_fma_f32 v62, -v61, s3, v62
	v_fma_f32 v63, -v58, s98, v63
	v_fma_f32 v62, -v59, s99, v62
	v_readlane_b32 s2, v14, 17
	v_readlane_b32 s3, v14, 18
	v_readlane_b32 s98, v14, 19
	v_readlane_b32 s99, v14, 20
	v_fma_f32 v63, -v56, s2, v63
	v_fma_f32 v62, -v57, s3, v62
	v_fma_f32 v63, -v54, s98, v63
	v_fma_f32 v62, -v55, s99, v62
	v_readlane_b32 s2, v14, 21
	v_readlane_b32 s3, v14, 22
	v_readlane_b32 s98, v14, 23
	v_readlane_b32 s99, v14, 24
	v_fma_f32 v63, -v52, s2, v63
	v_fma_f32 v62, -v53, s3, v62
	v_fma_f32 v63, -v50, s98, v63
	v_fma_f32 v62, -v51, s99, v62
	v_readlane_b32 s2, v14, 25
	v_readlane_b32 s3, v14, 26
	v_readlane_b32 s98, v14, 27
	v_readlane_b32 s99, v14, 28
	v_fma_f32 v63, -v48, s2, v63
	v_fma_f32 v62, -v49, s3, v62
	v_fma_f32 v63, -v46, s98, v63
	v_fma_f32 v62, -v47, s99, v62
	v_readlane_b32 s2, v14, 29
	v_readlane_b32 s3, v14, 30
	v_readlane_b32 s98, v14, 31
	v_readlane_b32 s99, v14, 32
	v_fma_f32 v63, -v44, s2, v63
	v_fma_f32 v62, -v45, s3, v62
	v_fma_f32 v63, -v42, s98, v63
	v_fma_f32 v62, -v43, s99, v62
	v_readlane_b32 s2, v14, 33
	v_readlane_b32 s3, v14, 34
	v_readlane_b32 s98, v14, 35
	v_readlane_b32 s99, v14, 36
	v_fma_f32 v63, -v40, s2, v63
	v_fma_f32 v62, -v41, s3, v62
	v_fma_f32 v63, -v38, s98, v63
	v_fma_f32 v62, -v39, s99, v62
	v_readlane_b32 s2, v14, 37
	v_readlane_b32 s3, v14, 38
	v_readlane_b32 s98, v14, 39
	v_readlane_b32 s99, v14, 40
	v_fma_f32 v63, -v36, s2, v63
	v_fma_f32 v62, -v37, s3, v62
	v_fma_f32 v63, -v34, s98, v63
	v_fma_f32 v62, -v35, s99, v62
	v_readlane_b32 s2, v14, 41
	v_readlane_b32 s3, v14, 42
	v_readlane_b32 s98, v14, 43
	v_readlane_b32 s99, v14, 44
	v_fma_f32 v63, -v32, s2, v63
	v_fma_f32 v62, -v33, s3, v62
	v_fma_f32 v63, -v30, s98, v63
	v_fma_f32 v62, -v31, s99, v62
	v_readlane_b32 s2, v14, 45
	v_readlane_b32 s3, v14, 46
	v_readlane_b32 s98, v14, 47
	v_readlane_b32 s99, v14, 48
	v_fma_f32 v63, -v28, s2, v63
	v_fma_f32 v62, -v29, s3, v62
	v_fma_f32 v63, -v26, s98, v63
	v_fma_f32 v62, -v27, s99, v62
	v_readlane_b32 s2, v14, 49
	v_readlane_b32 s3, v14, 50
	v_readlane_b32 s98, v14, 51
	v_readlane_b32 s99, v14, 52
	v_fma_f32 v63, -v24, s2, v63
	v_fma_f32 v62, -v25, s3, v62
	v_fma_f32 v63, -v22, s98, v63
	v_fma_f32 v62, -v23, s99, v62
	v_readlane_b32 s2, v14, 53
	v_readlane_b32 s3, v14, 54
	v_readlane_b32 s98, v14, 55
	v_readlane_b32 s99, v14, 56
	v_fma_f32 v63, -v20, s2, v63
	v_fma_f32 v62, -v21, s3, v62
	v_fma_f32 v63, -v18, s98, v63
	v_fma_f32 v62, -v19, s99, v62
	v_readlane_b32 s2, v14, 57
	v_readlane_b32 s3, v14, 58
	s_nop 0
	v_fma_f32 v63, -v16, s2, v63
	v_fma_f32 v14, -v17, s3, v62
	v_readlane_b32 s2, v15, 0
	v_add_f32_e32 v14, v63, v14
	s_nop 0
	v_fma_f32 v62, -v81, s2, v85
	v_readlane_b32 s2, v15, 1
	v_readlane_b32 s3, v15, 2
	v_readlane_b32 s98, v15, 3
	v_readlane_b32 s99, v15, 4
	v_fma_f32 v63, -v0, s2, 0
	v_fma_f32 v62, -v1, s3, v62
	v_fma_f32 v63, -v2, s98, v63
	v_fma_f32 v62, -v3, s99, v62
	v_readlane_b32 s2, v15, 5
	v_readlane_b32 s3, v15, 6
	v_readlane_b32 s98, v15, 7
	v_readlane_b32 s99, v15, 8
	v_fma_f32 v63, -v4, s2, v63
	v_fma_f32 v62, -v5, s3, v62
	v_fma_f32 v63, -v7, s98, v63
	v_fma_f32 v62, -v6, s99, v62
	v_readlane_b32 s2, v15, 9
	v_readlane_b32 s3, v15, 10
	v_readlane_b32 s98, v15, 11
	v_readlane_b32 s99, v15, 12
	v_fma_f32 v63, -v8, s2, v63
	v_fma_f32 v62, -v9, s3, v62
	v_fma_f32 v63, -v10, s98, v63
	v_fma_f32 v62, -v11, s99, v62
	v_readlane_b32 s2, v15, 13
	v_readlane_b32 s3, v15, 14
	v_readlane_b32 s98, v15, 15
	v_readlane_b32 s99, v15, 16
	v_fma_f32 v63, -v60, s2, v63
	v_fma_f32 v62, -v61, s3, v62
	v_fma_f32 v63, -v58, s98, v63
	v_fma_f32 v62, -v59, s99, v62
	v_readlane_b32 s2, v15, 17
	v_readlane_b32 s3, v15, 18
	v_readlane_b32 s98, v15, 19
	v_readlane_b32 s99, v15, 20
	v_fma_f32 v63, -v56, s2, v63
	v_fma_f32 v62, -v57, s3, v62
	v_fma_f32 v63, -v54, s98, v63
	v_fma_f32 v62, -v55, s99, v62
	v_readlane_b32 s2, v15, 21
	v_readlane_b32 s3, v15, 22
	v_readlane_b32 s98, v15, 23
	v_readlane_b32 s99, v15, 24
	v_fma_f32 v63, -v52, s2, v63
	v_fma_f32 v62, -v53, s3, v62
	v_fma_f32 v63, -v50, s98, v63
	v_fma_f32 v62, -v51, s99, v62
	v_readlane_b32 s2, v15, 25
	v_readlane_b32 s3, v15, 26
	v_readlane_b32 s98, v15, 27
	v_readlane_b32 s99, v15, 28
	v_fma_f32 v63, -v48, s2, v63
	v_fma_f32 v62, -v49, s3, v62
	v_fma_f32 v63, -v46, s98, v63
	v_fma_f32 v62, -v47, s99, v62
	v_readlane_b32 s2, v15, 29
	v_readlane_b32 s3, v15, 30
	v_readlane_b32 s98, v15, 31
	v_readlane_b32 s99, v15, 32
	v_fma_f32 v63, -v44, s2, v63
	v_fma_f32 v62, -v45, s3, v62
	v_fma_f32 v63, -v42, s98, v63
	v_fma_f32 v62, -v43, s99, v62
	v_readlane_b32 s2, v15, 33
	v_readlane_b32 s3, v15, 34
	v_readlane_b32 s98, v15, 35
	v_readlane_b32 s99, v15, 36
	v_fma_f32 v63, -v40, s2, v63
	v_fma_f32 v62, -v41, s3, v62
	v_fma_f32 v63, -v38, s98, v63
	v_fma_f32 v62, -v39, s99, v62
	v_readlane_b32 s2, v15, 37
	v_readlane_b32 s3, v15, 38
	v_readlane_b32 s98, v15, 39
	v_readlane_b32 s99, v15, 40
	v_fma_f32 v63, -v36, s2, v63
	v_fma_f32 v62, -v37, s3, v62
	v_fma_f32 v63, -v34, s98, v63
	v_fma_f32 v62, -v35, s99, v62
	v_readlane_b32 s2, v15, 41
	v_readlane_b32 s3, v15, 42
	v_readlane_b32 s98, v15, 43
	v_readlane_b32 s99, v15, 44
	v_fma_f32 v63, -v32, s2, v63
	v_fma_f32 v62, -v33, s3, v62
	v_fma_f32 v63, -v30, s98, v63
	v_fma_f32 v62, -v31, s99, v62
	v_readlane_b32 s2, v15, 45
	v_readlane_b32 s3, v15, 46
	v_readlane_b32 s98, v15, 47
	v_readlane_b32 s99, v15, 48
	v_fma_f32 v63, -v28, s2, v63
	v_fma_f32 v62, -v29, s3, v62
	v_fma_f32 v63, -v26, s98, v63
	v_fma_f32 v62, -v27, s99, v62
	v_readlane_b32 s2, v15, 49
	v_readlane_b32 s3, v15, 50
	v_readlane_b32 s98, v15, 51
	v_readlane_b32 s99, v15, 52
	v_fma_f32 v63, -v24, s2, v63
	v_fma_f32 v62, -v25, s3, v62
	v_fma_f32 v63, -v22, s98, v63
	v_fma_f32 v62, -v23, s99, v62
	v_readlane_b32 s2, v15, 53
	v_readlane_b32 s3, v15, 54
	v_readlane_b32 s98, v15, 55
	v_readlane_b32 s99, v15, 56
	v_fma_f32 v63, -v20, s2, v63
	v_fma_f32 v62, -v21, s3, v62
	v_fma_f32 v63, -v18, s98, v63
	v_fma_f32 v62, -v19, s99, v62
	v_readlane_b32 s2, v15, 57
	v_readlane_b32 s3, v15, 58
	v_readlane_b32 s98, v15, 59
	v_fma_f32 v63, -v16, s2, v63
	v_fma_f32 v62, -v17, s3, v62
	v_fma_f32 v15, -v14, s98, v63
	v_readlane_b32 s2, v12, 0
	v_add_f32_e32 v15, v62, v15
	s_nop 0
	v_fma_f32 v62, -v81, s2, v84
	v_readlane_b32 s2, v12, 1
	v_readlane_b32 s3, v12, 2
	v_readlane_b32 s98, v12, 3
	v_readlane_b32 s99, v12, 4
	v_fma_f32 v63, -v0, s2, 0
	v_fma_f32 v62, -v1, s3, v62
	v_fma_f32 v63, -v2, s98, v63
	v_fma_f32 v62, -v3, s99, v62
	v_readlane_b32 s2, v12, 5
	v_readlane_b32 s3, v12, 6
	v_readlane_b32 s98, v12, 7
	v_readlane_b32 s99, v12, 8
	v_fma_f32 v63, -v4, s2, v63
	v_fma_f32 v62, -v5, s3, v62
	v_fma_f32 v63, -v7, s98, v63
	v_fma_f32 v62, -v6, s99, v62
	v_readlane_b32 s2, v12, 9
	v_readlane_b32 s3, v12, 10
	v_readlane_b32 s98, v12, 11
	v_readlane_b32 s99, v12, 12
	v_fma_f32 v63, -v8, s2, v63
	v_fma_f32 v62, -v9, s3, v62
	v_fma_f32 v63, -v10, s98, v63
	v_fma_f32 v62, -v11, s99, v62
	v_readlane_b32 s2, v12, 13
	v_readlane_b32 s3, v12, 14
	v_readlane_b32 s98, v12, 15
	v_readlane_b32 s99, v12, 16
	v_fma_f32 v63, -v60, s2, v63
	v_fma_f32 v62, -v61, s3, v62
	v_fma_f32 v63, -v58, s98, v63
	v_fma_f32 v62, -v59, s99, v62
	v_readlane_b32 s2, v12, 17
	v_readlane_b32 s3, v12, 18
	v_readlane_b32 s98, v12, 19
	v_readlane_b32 s99, v12, 20
	v_fma_f32 v63, -v56, s2, v63
	v_fma_f32 v62, -v57, s3, v62
	v_fma_f32 v63, -v54, s98, v63
	v_fma_f32 v62, -v55, s99, v62
	v_readlane_b32 s2, v12, 21
	v_readlane_b32 s3, v12, 22
	v_readlane_b32 s98, v12, 23
	v_readlane_b32 s99, v12, 24
	v_fma_f32 v63, -v52, s2, v63
	v_fma_f32 v62, -v53, s3, v62
	v_fma_f32 v63, -v50, s98, v63
	v_fma_f32 v62, -v51, s99, v62
	v_readlane_b32 s2, v12, 25
	v_readlane_b32 s3, v12, 26
	v_readlane_b32 s98, v12, 27
	v_readlane_b32 s99, v12, 28
	v_fma_f32 v63, -v48, s2, v63
	v_fma_f32 v62, -v49, s3, v62
	v_fma_f32 v63, -v46, s98, v63
	v_fma_f32 v62, -v47, s99, v62
	v_readlane_b32 s2, v12, 29
	v_readlane_b32 s3, v12, 30
	v_readlane_b32 s98, v12, 31
	v_readlane_b32 s99, v12, 32
	v_fma_f32 v63, -v44, s2, v63
	v_fma_f32 v62, -v45, s3, v62
	v_fma_f32 v63, -v42, s98, v63
	v_fma_f32 v62, -v43, s99, v62
	v_readlane_b32 s2, v12, 33
	v_readlane_b32 s3, v12, 34
	v_readlane_b32 s98, v12, 35
	v_readlane_b32 s99, v12, 36
	v_fma_f32 v63, -v40, s2, v63
	v_fma_f32 v62, -v41, s3, v62
	v_fma_f32 v63, -v38, s98, v63
	v_fma_f32 v62, -v39, s99, v62
	v_readlane_b32 s2, v12, 37
	v_readlane_b32 s3, v12, 38
	v_readlane_b32 s98, v12, 39
	v_readlane_b32 s99, v12, 40
	v_fma_f32 v63, -v36, s2, v63
	v_fma_f32 v62, -v37, s3, v62
	v_fma_f32 v63, -v34, s98, v63
	v_fma_f32 v62, -v35, s99, v62
	v_readlane_b32 s2, v12, 41
	v_readlane_b32 s3, v12, 42
	v_readlane_b32 s98, v12, 43
	v_readlane_b32 s99, v12, 44
	v_fma_f32 v63, -v32, s2, v63
	v_fma_f32 v62, -v33, s3, v62
	v_fma_f32 v63, -v30, s98, v63
	v_fma_f32 v62, -v31, s99, v62
	v_readlane_b32 s2, v12, 45
	v_readlane_b32 s3, v12, 46
	v_readlane_b32 s98, v12, 47
	v_readlane_b32 s99, v12, 48
	v_fma_f32 v63, -v28, s2, v63
	v_fma_f32 v62, -v29, s3, v62
	v_fma_f32 v63, -v26, s98, v63
	v_fma_f32 v62, -v27, s99, v62
	v_readlane_b32 s2, v12, 49
	v_readlane_b32 s3, v12, 50
	v_readlane_b32 s98, v12, 51
	v_readlane_b32 s99, v12, 52
	v_fma_f32 v63, -v24, s2, v63
	v_fma_f32 v62, -v25, s3, v62
	v_fma_f32 v63, -v22, s98, v63
	v_fma_f32 v62, -v23, s99, v62
	v_readlane_b32 s2, v12, 53
	v_readlane_b32 s3, v12, 54
	v_readlane_b32 s98, v12, 55
	v_readlane_b32 s99, v12, 56
	v_fma_f32 v63, -v20, s2, v63
	v_fma_f32 v62, -v21, s3, v62
	v_fma_f32 v63, -v18, s98, v63
	v_fma_f32 v62, -v19, s99, v62
	v_readlane_b32 s2, v12, 57
	v_readlane_b32 s3, v12, 58
	v_readlane_b32 s98, v12, 59
	v_readlane_b32 s99, v12, 60
	v_fma_f32 v63, -v16, s2, v63
	v_fma_f32 v62, -v17, s3, v62
	v_fma_f32 v63, -v14, s98, v63
	v_fma_f32 v12, -v15, s99, v62
	v_readlane_b32 s2, v13, 0
	v_add_f32_e32 v12, v63, v12
	s_nop 0
	v_fma_f32 v62, -v81, s2, v83
	v_readlane_b32 s2, v13, 1
	v_readlane_b32 s3, v13, 2
	v_readlane_b32 s98, v13, 3
	v_readlane_b32 s99, v13, 4
	v_fma_f32 v63, -v0, s2, 0
	v_fma_f32 v62, -v1, s3, v62
	v_fma_f32 v63, -v2, s98, v63
	v_fma_f32 v62, -v3, s99, v62
	v_readlane_b32 s2, v13, 5
	v_readlane_b32 s3, v13, 6
	v_readlane_b32 s98, v13, 7
	v_readlane_b32 s99, v13, 8
	v_fma_f32 v63, -v4, s2, v63
	v_fma_f32 v62, -v5, s3, v62
	v_fma_f32 v63, -v7, s98, v63
	v_fma_f32 v62, -v6, s99, v62
	v_readlane_b32 s2, v13, 9
	v_readlane_b32 s3, v13, 10
	v_readlane_b32 s98, v13, 11
	v_readlane_b32 s99, v13, 12
	v_fma_f32 v63, -v8, s2, v63
	v_fma_f32 v62, -v9, s3, v62
	v_fma_f32 v63, -v10, s98, v63
	v_fma_f32 v62, -v11, s99, v62
	v_readlane_b32 s2, v13, 13
	v_readlane_b32 s3, v13, 14
	v_readlane_b32 s98, v13, 15
	v_readlane_b32 s99, v13, 16
	v_fma_f32 v63, -v60, s2, v63
	v_fma_f32 v62, -v61, s3, v62
	v_fma_f32 v63, -v58, s98, v63
	v_fma_f32 v62, -v59, s99, v62
	v_readlane_b32 s2, v13, 17
	v_readlane_b32 s3, v13, 18
	v_readlane_b32 s98, v13, 19
	v_readlane_b32 s99, v13, 20
	v_fma_f32 v63, -v56, s2, v63
	v_fma_f32 v62, -v57, s3, v62
	v_fma_f32 v63, -v54, s98, v63
	v_fma_f32 v62, -v55, s99, v62
	v_readlane_b32 s2, v13, 21
	v_readlane_b32 s3, v13, 22
	v_readlane_b32 s98, v13, 23
	v_readlane_b32 s99, v13, 24
	v_fma_f32 v63, -v52, s2, v63
	v_fma_f32 v62, -v53, s3, v62
	v_fma_f32 v63, -v50, s98, v63
	v_fma_f32 v62, -v51, s99, v62
	v_readlane_b32 s2, v13, 25
	v_readlane_b32 s3, v13, 26
	v_readlane_b32 s98, v13, 27
	v_readlane_b32 s99, v13, 28
	v_fma_f32 v63, -v48, s2, v63
	v_fma_f32 v62, -v49, s3, v62
	v_fma_f32 v63, -v46, s98, v63
	v_fma_f32 v62, -v47, s99, v62
	v_readlane_b32 s2, v13, 29
	v_readlane_b32 s3, v13, 30
	v_readlane_b32 s98, v13, 31
	v_readlane_b32 s99, v13, 32
	v_fma_f32 v63, -v44, s2, v63
	v_fma_f32 v62, -v45, s3, v62
	v_fma_f32 v63, -v42, s98, v63
	v_fma_f32 v62, -v43, s99, v62
	v_readlane_b32 s2, v13, 33
	v_readlane_b32 s3, v13, 34
	v_readlane_b32 s98, v13, 35
	v_readlane_b32 s99, v13, 36
	v_fma_f32 v63, -v40, s2, v63
	v_fma_f32 v62, -v41, s3, v62
	v_fma_f32 v63, -v38, s98, v63
	v_fma_f32 v62, -v39, s99, v62
	v_readlane_b32 s2, v13, 37
	v_readlane_b32 s3, v13, 38
	v_readlane_b32 s98, v13, 39
	v_readlane_b32 s99, v13, 40
	v_fma_f32 v63, -v36, s2, v63
	v_fma_f32 v62, -v37, s3, v62
	v_fma_f32 v63, -v34, s98, v63
	v_fma_f32 v62, -v35, s99, v62
	v_readlane_b32 s2, v13, 41
	v_readlane_b32 s3, v13, 42
	v_readlane_b32 s98, v13, 43
	v_readlane_b32 s99, v13, 44
	v_fma_f32 v63, -v32, s2, v63
	v_fma_f32 v62, -v33, s3, v62
	v_fma_f32 v63, -v30, s98, v63
	v_fma_f32 v62, -v31, s99, v62
	v_readlane_b32 s2, v13, 45
	v_readlane_b32 s3, v13, 46
	v_readlane_b32 s98, v13, 47
	v_readlane_b32 s99, v13, 48
	v_fma_f32 v63, -v28, s2, v63
	v_fma_f32 v62, -v29, s3, v62
	v_fma_f32 v63, -v26, s98, v63
	v_fma_f32 v62, -v27, s99, v62
	v_readlane_b32 s2, v13, 49
	v_readlane_b32 s3, v13, 50
	v_readlane_b32 s98, v13, 51
	v_readlane_b32 s99, v13, 52
	v_fma_f32 v63, -v24, s2, v63
	v_fma_f32 v62, -v25, s3, v62
	v_fma_f32 v63, -v22, s98, v63
	v_fma_f32 v62, -v23, s99, v62
	v_readlane_b32 s2, v13, 53
	v_readlane_b32 s3, v13, 54
	v_readlane_b32 s98, v13, 55
	v_readlane_b32 s99, v13, 56
	v_fma_f32 v63, -v20, s2, v63
	v_fma_f32 v62, -v21, s3, v62
	v_fma_f32 v63, -v18, s98, v63
	v_fma_f32 v62, -v19, s99, v62
	v_readlane_b32 s2, v13, 57
	v_readlane_b32 s3, v13, 58
	v_readlane_b32 s98, v13, 59
	v_readlane_b32 s99, v13, 60
	v_fma_f32 v63, -v16, s2, v63
	v_fma_f32 v62, -v17, s3, v62
	v_fma_f32 v63, -v14, s98, v63
	v_fma_f32 v62, -v15, s99, v62
	v_readlane_b32 s2, v13, 61
	s_nop 1
	v_fma_f32 v13, -v12, s2, v63
	v_readlane_b32 s2, v80, 0
	v_add_f32_e32 v13, v62, v13
	s_nop 0
	v_fma_f32 v62, -v81, s2, v82
	v_readlane_b32 s2, v80, 1
	v_readlane_b32 s3, v80, 2
	v_readlane_b32 s98, v80, 3
	v_readlane_b32 s99, v80, 4
	v_fma_f32 v63, -v0, s2, 0
	v_fma_f32 v62, -v1, s3, v62
	v_fma_f32 v63, -v2, s98, v63
	v_fma_f32 v62, -v3, s99, v62
	v_readlane_b32 s2, v80, 5
	v_readlane_b32 s3, v80, 6
	v_readlane_b32 s98, v80, 7
	v_readlane_b32 s99, v80, 8
	v_fma_f32 v63, -v4, s2, v63
	v_fma_f32 v62, -v5, s3, v62
	v_fma_f32 v63, -v7, s98, v63
	v_fma_f32 v62, -v6, s99, v62
	v_readlane_b32 s2, v80, 9
	v_readlane_b32 s3, v80, 10
	v_readlane_b32 s98, v80, 11
	v_readlane_b32 s99, v80, 12
	v_fma_f32 v63, -v8, s2, v63
	v_fma_f32 v62, -v9, s3, v62
	v_fma_f32 v63, -v10, s98, v63
	v_fma_f32 v62, -v11, s99, v62
	v_readlane_b32 s2, v80, 13
	v_readlane_b32 s3, v80, 14
	v_readlane_b32 s98, v80, 15
	v_readlane_b32 s99, v80, 16
	v_fma_f32 v63, -v60, s2, v63
	v_fma_f32 v62, -v61, s3, v62
	v_fma_f32 v63, -v58, s98, v63
	v_fma_f32 v62, -v59, s99, v62
	v_readlane_b32 s2, v80, 17
	v_readlane_b32 s3, v80, 18
	v_readlane_b32 s98, v80, 19
	v_readlane_b32 s99, v80, 20
	v_fma_f32 v63, -v56, s2, v63
	v_fma_f32 v62, -v57, s3, v62
	v_fma_f32 v63, -v54, s98, v63
	v_fma_f32 v62, -v55, s99, v62
	v_readlane_b32 s2, v80, 21
	v_readlane_b32 s3, v80, 22
	v_readlane_b32 s98, v80, 23
	v_readlane_b32 s99, v80, 24
	v_fma_f32 v63, -v52, s2, v63
	v_fma_f32 v62, -v53, s3, v62
	v_fma_f32 v63, -v50, s98, v63
	v_fma_f32 v62, -v51, s99, v62
	v_readlane_b32 s2, v80, 25
	v_readlane_b32 s3, v80, 26
	v_readlane_b32 s98, v80, 27
	v_readlane_b32 s99, v80, 28
	v_fma_f32 v63, -v48, s2, v63
	v_fma_f32 v62, -v49, s3, v62
	v_fma_f32 v63, -v46, s98, v63
	v_fma_f32 v62, -v47, s99, v62
	v_readlane_b32 s2, v80, 29
	v_readlane_b32 s3, v80, 30
	v_readlane_b32 s98, v80, 31
	v_readlane_b32 s99, v80, 32
	v_fma_f32 v63, -v44, s2, v63
	v_fma_f32 v62, -v45, s3, v62
	v_fma_f32 v63, -v42, s98, v63
	v_fma_f32 v62, -v43, s99, v62
	v_readlane_b32 s2, v80, 33
	v_readlane_b32 s3, v80, 34
	v_readlane_b32 s98, v80, 35
	v_readlane_b32 s99, v80, 36
	v_fma_f32 v63, -v40, s2, v63
	v_fma_f32 v62, -v41, s3, v62
	v_fma_f32 v63, -v38, s98, v63
	v_fma_f32 v62, -v39, s99, v62
	v_readlane_b32 s2, v80, 37
	v_readlane_b32 s3, v80, 38
	v_readlane_b32 s98, v80, 39
	v_readlane_b32 s99, v80, 40
	v_fma_f32 v63, -v36, s2, v63
	v_fma_f32 v62, -v37, s3, v62
	v_fma_f32 v63, -v34, s98, v63
	v_fma_f32 v62, -v35, s99, v62
	v_readlane_b32 s2, v80, 41
	v_readlane_b32 s3, v80, 42
	v_readlane_b32 s98, v80, 43
	v_readlane_b32 s99, v80, 44
	v_fma_f32 v63, -v32, s2, v63
	v_fma_f32 v62, -v33, s3, v62
	v_fma_f32 v63, -v30, s98, v63
	v_fma_f32 v62, -v31, s99, v62
	v_readlane_b32 s2, v80, 45
	v_readlane_b32 s3, v80, 46
	v_readlane_b32 s98, v80, 47
	v_readlane_b32 s99, v80, 48
	v_fma_f32 v63, -v28, s2, v63
	v_fma_f32 v62, -v29, s3, v62
	v_fma_f32 v63, -v26, s98, v63
	v_fma_f32 v62, -v27, s99, v62
	v_readlane_b32 s2, v80, 49
	v_readlane_b32 s3, v80, 50
	v_readlane_b32 s98, v80, 51
	v_readlane_b32 s99, v80, 52
	v_fma_f32 v63, -v24, s2, v63
	v_fma_f32 v62, -v25, s3, v62
	v_fma_f32 v63, -v22, s98, v63
	v_fma_f32 v62, -v23, s99, v62
	v_readlane_b32 s2, v80, 53
	v_readlane_b32 s3, v80, 54
	v_readlane_b32 s98, v80, 55
	v_readlane_b32 s99, v80, 56
	v_fma_f32 v63, -v20, s2, v63
	v_fma_f32 v62, -v21, s3, v62
	v_fma_f32 v63, -v18, s98, v63
	v_fma_f32 v62, -v19, s99, v62
	v_readlane_b32 s2, v80, 57
	v_readlane_b32 s3, v80, 58
	v_readlane_b32 s98, v80, 59
	v_readlane_b32 s99, v80, 60
	v_fma_f32 v63, -v16, s2, v63
	v_fma_f32 v62, -v17, s3, v62
	v_fma_f32 v63, -v14, s98, v63
	v_fma_f32 v62, -v15, s99, v62
	v_readlane_b32 s2, v80, 61
	v_readlane_b32 s3, v80, 62
	s_nop 0
	v_fma_f32 v63, -v12, s2, v63
	v_fma_f32 v62, -v13, s3, v62
	v_add_f32_e32 v62, v63, v62
	s_and_saveexec_b64 s[2:3], s[38:39]
	s_xor_b64 s[2:3], exec, s[2:3]
	s_cbranch_execz .LBB0_657
	v_readlane_b32 s44, v246, 41
	s_lshl_b64 s[4:5], s[42:43], 1
	v_readlane_b32 s52, v246, 49
	v_readlane_b32 s53, v246, 50
	s_add_u32 s4, s52, s4
	v_cvt_pk_bf16_f32 v0, v79, v0
	v_cvt_pk_bf16_f32 v1, v1, v2
	v_cvt_pk_bf16_f32 v2, v3, v4
	v_cvt_pk_bf16_f32 v3, v5, v7
	s_addc_u32 s5, s53, s5
	v_lshlrev_b32_e32 v4, 7, v75
	global_store_dwordx4 v4, v[0:3], s[4:5]
	v_readlane_b32 s45, v246, 42
	v_readlane_b32 s46, v246, 43
	v_cvt_pk_bf16_f32 v0, v6, v8
	v_cvt_pk_bf16_f32 v1, v9, v10
	v_cvt_pk_bf16_f32 v2, v11, v60
	v_cvt_pk_bf16_f32 v3, v61, v58
	global_store_dwordx4 v4, v[0:3], s[4:5] offset:16
	v_readlane_b32 s47, v246, 44
	v_readlane_b32 s48, v246, 45
	v_cvt_pk_bf16_f32 v0, v59, v56
	v_cvt_pk_bf16_f32 v1, v57, v54
	v_cvt_pk_bf16_f32 v2, v55, v52
	v_cvt_pk_bf16_f32 v3, v53, v50
	global_store_dwordx4 v4, v[0:3], s[4:5] offset:32
	v_readlane_b32 s49, v246, 46
	v_readlane_b32 s50, v246, 47
	v_cvt_pk_bf16_f32 v0, v51, v48
	v_cvt_pk_bf16_f32 v1, v49, v46
	v_cvt_pk_bf16_f32 v2, v47, v44
	v_cvt_pk_bf16_f32 v3, v45, v42
	global_store_dwordx4 v4, v[0:3], s[4:5] offset:48
	v_readlane_b32 s51, v246, 48
	v_readlane_b32 s54, v246, 51
	v_cvt_pk_bf16_f32 v0, v43, v40
	v_cvt_pk_bf16_f32 v1, v41, v38
	v_cvt_pk_bf16_f32 v2, v39, v36
	v_cvt_pk_bf16_f32 v3, v37, v34
	global_store_dwordx4 v4, v[0:3], s[4:5] offset:64
	v_readlane_b32 s55, v246, 52
	v_readlane_b32 s56, v246, 53
	v_cvt_pk_bf16_f32 v0, v35, v32
	v_cvt_pk_bf16_f32 v1, v33, v30
	v_cvt_pk_bf16_f32 v2, v31, v28
	v_cvt_pk_bf16_f32 v3, v29, v26
	global_store_dwordx4 v4, v[0:3], s[4:5] offset:80
	v_readlane_b32 s57, v246, 54
	v_readlane_b32 s58, v246, 55
	v_cvt_pk_bf16_f32 v0, v27, v24
	v_cvt_pk_bf16_f32 v1, v25, v22
	v_cvt_pk_bf16_f32 v2, v23, v20
	v_cvt_pk_bf16_f32 v3, v21, v18
	global_store_dwordx4 v4, v[0:3], s[4:5] offset:96
	v_readlane_b32 s59, v246, 56
	s_nop 0
	v_cvt_pk_bf16_f32 v0, v19, v16
	v_cvt_pk_bf16_f32 v1, v17, v14
	v_cvt_pk_bf16_f32 v2, v15, v12
	v_cvt_pk_bf16_f32 v3, v13, v62
	global_store_dwordx4 v4, v[0:3], s[4:5] offset:112
